# up epilogue: conv weights halved once per tile (one packed multiply less per pair), tiles with a sequence boundary use the fast row path with exec-masked tap fix-ups
# speedup vs baseline: 1.1121x; 1.0067x over previous
.Lg_up_loop:
	ds_read_b128 v[198:201], v134 offset:8192
	ds_read_b128 v[202:205], v134 offset:10240
	ds_read_b128 v[206:209], v134 offset:12288
	ds_read_b128 v[210:213], v134 offset:14336
	s_waitcnt lgkmcnt(4)
	v_mfma_f32_16x16x32_bf16 v[124:127], v[168:171], v[152:155], v[124:127]
	v_mfma_f32_16x16x32_bf16 v[120:123], v[168:171], v[156:159], v[120:123]
	v_mfma_f32_16x16x32_bf16 v[116:119], v[168:171], v[160:163], v[116:119]
	v_mfma_f32_16x16x32_bf16 v[112:115], v[168:171], v[164:167], v[112:115]
	v_mfma_f32_16x16x32_bf16 v[108:111], v[172:175], v[152:155], v[108:111]
	v_mfma_f32_16x16x32_bf16 v[104:107], v[172:175], v[156:159], v[104:107]
	v_mfma_f32_16x16x32_bf16 v[100:103], v[172:175], v[160:163], v[100:103]
	v_mfma_f32_16x16x32_bf16 v[96:99], v[172:175], v[164:167], v[96:99]
	v_mfma_f32_16x16x32_bf16 v[92:95], v[176:179], v[152:155], v[92:95]
	v_mfma_f32_16x16x32_bf16 v[84:87], v[176:179], v[156:159], v[84:87]
	v_mfma_f32_16x16x32_bf16 v[80:83], v[176:179], v[160:163], v[80:83]
	v_mfma_f32_16x16x32_bf16 v[76:79], v[176:179], v[164:167], v[76:79]
	v_mfma_f32_16x16x32_bf16 v[72:75], v[180:183], v[152:155], v[72:75]
	v_mfma_f32_16x16x32_bf16 v[68:71], v[180:183], v[156:159], v[68:71]
	v_mfma_f32_16x16x32_bf16 v[64:67], v[180:183], v[160:163], v[64:67]
	v_mfma_f32_16x16x32_bf16 v[60:63], v[180:183], v[164:167], v[60:63]
	v_add_u32_e32 v180, v149, v150
	v_add_u32_e32 v134, v149, v148
	ds_read_b128 v[168:171], v180 offset:32768
	ds_read_b128 v[172:175], v180 offset:34816
	ds_read_b128 v[176:179], v180 offset:36864
	ds_read_b128 v[180:183], v180 offset:38912
	ds_read_b128 v[214:217], v134 offset:0
	ds_read_b128 v[218:221], v134 offset:2048
	ds_read_b128 v[222:225], v134 offset:4096
	ds_read_b128 v[226:229], v134 offset:6144
	s_waitcnt lgkmcnt(8)
	v_mfma_f32_16x16x32_bf16 v[56:59], v[198:201], v[152:155], v[56:59]
	v_mfma_f32_16x16x32_bf16 v[52:55], v[198:201], v[156:159], v[52:55]
	v_mfma_f32_16x16x32_bf16 v[48:51], v[198:201], v[160:163], v[48:51]
	v_mfma_f32_16x16x32_bf16 v[44:47], v[198:201], v[164:167], v[44:47]
	v_mfma_f32_16x16x32_bf16 v[40:43], v[202:205], v[152:155], v[40:43]
	v_mfma_f32_16x16x32_bf16 v[36:39], v[202:205], v[156:159], v[36:39]
	v_mfma_f32_16x16x32_bf16 v[32:35], v[202:205], v[160:163], v[32:35]
	v_mfma_f32_16x16x32_bf16 v[28:31], v[202:205], v[164:167], v[28:31]
	v_mfma_f32_16x16x32_bf16 v[24:27], v[206:209], v[152:155], v[24:27]
	v_mfma_f32_16x16x32_bf16 v[20:23], v[206:209], v[156:159], v[20:23]
	v_mfma_f32_16x16x32_bf16 v[16:19], v[206:209], v[160:163], v[16:19]
	v_mfma_f32_16x16x32_bf16 v[12:15], v[206:209], v[164:167], v[12:15]
	v_mfma_f32_16x16x32_bf16 v[8:11], v[210:213], v[152:155], v[8:11]
	v_mfma_f32_16x16x32_bf16 v[4:7], v[210:213], v[156:159], v[4:7]
	v_mfma_f32_16x16x32_bf16 v[0:3], v[210:213], v[160:163], v[0:3]
	v_mfma_f32_16x16x32_bf16 v[88:91], v[210:213], v[164:167], v[88:91]
	ds_read_b128 v[152:155], v134 offset:8192
	ds_read_b128 v[156:159], v134 offset:10240
	ds_read_b128 v[160:163], v134 offset:12288
	ds_read_b128 v[164:167], v134 offset:14336
	s_waitcnt lgkmcnt(4)
	v_mfma_f32_16x16x32_bf16 v[124:127], v[214:217], v[168:171], v[124:127]
	v_mfma_f32_16x16x32_bf16 v[120:123], v[214:217], v[172:175], v[120:123]
	v_mfma_f32_16x16x32_bf16 v[116:119], v[214:217], v[176:179], v[116:119]
	v_mfma_f32_16x16x32_bf16 v[112:115], v[214:217], v[180:183], v[112:115]
	v_mfma_f32_16x16x32_bf16 v[108:111], v[218:221], v[168:171], v[108:111]
	v_mfma_f32_16x16x32_bf16 v[104:107], v[218:221], v[172:175], v[104:107]
	v_mfma_f32_16x16x32_bf16 v[100:103], v[218:221], v[176:179], v[100:103]
	v_mfma_f32_16x16x32_bf16 v[96:99], v[218:221], v[180:183], v[96:99]
	v_mfma_f32_16x16x32_bf16 v[92:95], v[222:225], v[168:171], v[92:95]
	v_mfma_f32_16x16x32_bf16 v[84:87], v[222:225], v[172:175], v[84:87]
	v_mfma_f32_16x16x32_bf16 v[80:83], v[222:225], v[176:179], v[80:83]
	v_mfma_f32_16x16x32_bf16 v[76:79], v[222:225], v[180:183], v[76:79]
	v_mfma_f32_16x16x32_bf16 v[72:75], v[226:229], v[168:171], v[72:75]
	v_mfma_f32_16x16x32_bf16 v[68:71], v[226:229], v[172:175], v[68:71]
	v_mfma_f32_16x16x32_bf16 v[64:67], v[226:229], v[176:179], v[64:67]
	v_mfma_f32_16x16x32_bf16 v[60:63], v[226:229], v[180:183], v[60:63]
	s_waitcnt lgkmcnt(0)
	v_mfma_f32_16x16x32_bf16 v[56:59], v[152:155], v[168:171], v[56:59]
	s_waitcnt vmcnt(0)
	s_barrier
	v_add3_u32 v210, v151, v150, s99
	v_add3_u32 v134, v151, v148, s99
	v_mfma_f32_16x16x32_bf16 v[52:55], v[152:155], v[172:175], v[52:55]
	ds_read_b128 v[198:201], v210 offset:32768
	ds_read_b128 v[202:205], v210 offset:34816
	v_mfma_f32_16x16x32_bf16 v[48:51], v[152:155], v[176:179], v[48:51]
	ds_read_b128 v[206:209], v210 offset:36864
	ds_read_b128 v[210:213], v210 offset:38912
	v_mfma_f32_16x16x32_bf16 v[44:47], v[152:155], v[180:183], v[44:47]
	ds_read_b128 v[214:217], v134 offset:0
	ds_read_b128 v[218:221], v134 offset:2048
	v_mfma_f32_16x16x32_bf16 v[40:43], v[156:159], v[168:171], v[40:43]
	ds_read_b128 v[222:225], v134 offset:4096
	ds_read_b128 v[226:229], v134 offset:6144
	s_mov_b32 m0, s93
	v_mfma_f32_16x16x32_bf16 v[36:39], v[156:159], v[172:175], v[36:39]
	global_load_lds_dwordx4 v[128:129], off
	v_lshl_add_u64 v[128:129], v[128:129], 0, s[100:101]
	s_add_i32 m0, s93, 0x8000
	v_mfma_f32_16x16x32_bf16 v[32:35], v[156:159], v[176:179], v[32:35]
	global_load_lds_dwordx4 v[140:141], off
	v_lshl_add_u64 v[140:141], v[140:141], 0, s[100:101]
	s_mov_b32 m0, s94
	v_mfma_f32_16x16x32_bf16 v[28:31], v[156:159], v[180:183], v[28:31]
	global_load_lds_dwordx4 v[130:131], off
	v_lshl_add_u64 v[130:131], v[130:131], 0, s[100:101]
	s_add_i32 m0, s94, 0x8000
	v_mfma_f32_16x16x32_bf16 v[24:27], v[160:163], v[168:171], v[24:27]
	global_load_lds_dwordx4 v[142:143], off
	v_lshl_add_u64 v[142:143], v[142:143], 0, s[100:101]
	s_mov_b32 m0, s95
	v_mfma_f32_16x16x32_bf16 v[20:23], v[160:163], v[172:175], v[20:23]
	global_load_lds_dwordx4 v[136:137], off
	v_lshl_add_u64 v[136:137], v[136:137], 0, s[100:101]
	s_add_i32 m0, s95, 0x8000
	v_mfma_f32_16x16x32_bf16 v[16:19], v[160:163], v[176:179], v[16:19]
	global_load_lds_dwordx4 v[144:145], off
	v_lshl_add_u64 v[144:145], v[144:145], 0, s[100:101]
	s_mov_b32 m0, s96
	v_mfma_f32_16x16x32_bf16 v[12:15], v[160:163], v[180:183], v[12:15]
	global_load_lds_dwordx4 v[138:139], off
	v_lshl_add_u64 v[138:139], v[138:139], 0, s[100:101]
	s_add_i32 m0, s96, 0x8000
	v_mfma_f32_16x16x32_bf16 v[8:11], v[164:167], v[168:171], v[8:11]
	global_load_lds_dwordx4 v[146:147], off
	v_lshl_add_u64 v[146:147], v[146:147], 0, s[100:101]
	v_mfma_f32_16x16x32_bf16 v[4:7], v[164:167], v[172:175], v[4:7]
	v_mfma_f32_16x16x32_bf16 v[0:3], v[164:167], v[176:179], v[0:3]
	v_mfma_f32_16x16x32_bf16 v[88:91], v[164:167], v[180:183], v[88:91]
	ds_read_b128 v[152:155], v134 offset:8192
	ds_read_b128 v[156:159], v134 offset:10240
	ds_read_b128 v[160:163], v134 offset:12288
	ds_read_b128 v[164:167], v134 offset:14336
	s_waitcnt lgkmcnt(4)
	v_mfma_f32_16x16x32_bf16 v[124:127], v[214:217], v[198:201], v[124:127]
	v_mfma_f32_16x16x32_bf16 v[120:123], v[214:217], v[202:205], v[120:123]
	v_mfma_f32_16x16x32_bf16 v[116:119], v[214:217], v[206:209], v[116:119]
	v_mfma_f32_16x16x32_bf16 v[112:115], v[214:217], v[210:213], v[112:115]
	v_mfma_f32_16x16x32_bf16 v[108:111], v[218:221], v[198:201], v[108:111]
	v_mfma_f32_16x16x32_bf16 v[104:107], v[218:221], v[202:205], v[104:107]
	v_mfma_f32_16x16x32_bf16 v[100:103], v[218:221], v[206:209], v[100:103]
	v_mfma_f32_16x16x32_bf16 v[96:99], v[218:221], v[210:213], v[96:99]
	v_mfma_f32_16x16x32_bf16 v[92:95], v[222:225], v[198:201], v[92:95]
	v_mfma_f32_16x16x32_bf16 v[84:87], v[222:225], v[202:205], v[84:87]
	v_mfma_f32_16x16x32_bf16 v[80:83], v[222:225], v[206:209], v[80:83]
	v_mfma_f32_16x16x32_bf16 v[76:79], v[222:225], v[210:213], v[76:79]
	v_mfma_f32_16x16x32_bf16 v[72:75], v[226:229], v[198:201], v[72:75]
	v_mfma_f32_16x16x32_bf16 v[68:71], v[226:229], v[202:205], v[68:71]
	v_mfma_f32_16x16x32_bf16 v[64:67], v[226:229], v[206:209], v[64:67]
	v_mfma_f32_16x16x32_bf16 v[60:63], v[226:229], v[210:213], v[60:63]
	v_add3_u32 v226, v149, v150, s99
	v_add3_u32 v134, v149, v148, s99
	ds_read_b128 v[214:217], v226 offset:32768
	ds_read_b128 v[218:221], v226 offset:34816
	ds_read_b128 v[222:225], v226 offset:36864
	ds_read_b128 v[226:229], v226 offset:38912
	ds_read_b128 v[168:171], v134 offset:0
	ds_read_b128 v[172:175], v134 offset:2048
	ds_read_b128 v[176:179], v134 offset:4096
	ds_read_b128 v[180:183], v134 offset:6144
	s_waitcnt lgkmcnt(8)
	v_mfma_f32_16x16x32_bf16 v[56:59], v[152:155], v[198:201], v[56:59]
	v_mfma_f32_16x16x32_bf16 v[52:55], v[152:155], v[202:205], v[52:55]
	v_mfma_f32_16x16x32_bf16 v[48:51], v[152:155], v[206:209], v[48:51]
	v_mfma_f32_16x16x32_bf16 v[44:47], v[152:155], v[210:213], v[44:47]
	v_mfma_f32_16x16x32_bf16 v[40:43], v[156:159], v[198:201], v[40:43]
	v_mfma_f32_16x16x32_bf16 v[36:39], v[156:159], v[202:205], v[36:39]
	v_mfma_f32_16x16x32_bf16 v[32:35], v[156:159], v[206:209], v[32:35]
	v_mfma_f32_16x16x32_bf16 v[28:31], v[156:159], v[210:213], v[28:31]
	v_mfma_f32_16x16x32_bf16 v[24:27], v[160:163], v[198:201], v[24:27]
	v_mfma_f32_16x16x32_bf16 v[20:23], v[160:163], v[202:205], v[20:23]
	v_mfma_f32_16x16x32_bf16 v[16:19], v[160:163], v[206:209], v[16:19]
	v_mfma_f32_16x16x32_bf16 v[12:15], v[160:163], v[210:213], v[12:15]
	v_mfma_f32_16x16x32_bf16 v[8:11], v[164:167], v[198:201], v[8:11]
	v_mfma_f32_16x16x32_bf16 v[4:7], v[164:167], v[202:205], v[4:7]
	v_mfma_f32_16x16x32_bf16 v[0:3], v[164:167], v[206:209], v[0:3]
	v_mfma_f32_16x16x32_bf16 v[88:91], v[164:167], v[210:213], v[88:91]
	ds_read_b128 v[198:201], v134 offset:8192
	ds_read_b128 v[202:205], v134 offset:10240
	ds_read_b128 v[206:209], v134 offset:12288
	ds_read_b128 v[210:213], v134 offset:14336
	s_waitcnt lgkmcnt(4)
	v_mfma_f32_16x16x32_bf16 v[124:127], v[168:171], v[214:217], v[124:127]
	v_mfma_f32_16x16x32_bf16 v[120:123], v[168:171], v[218:221], v[120:123]
	v_mfma_f32_16x16x32_bf16 v[116:119], v[168:171], v[222:225], v[116:119]
	v_mfma_f32_16x16x32_bf16 v[112:115], v[168:171], v[226:229], v[112:115]
	v_mfma_f32_16x16x32_bf16 v[108:111], v[172:175], v[214:217], v[108:111]
	v_mfma_f32_16x16x32_bf16 v[104:107], v[172:175], v[218:221], v[104:107]
	v_mfma_f32_16x16x32_bf16 v[100:103], v[172:175], v[222:225], v[100:103]
	v_mfma_f32_16x16x32_bf16 v[96:99], v[172:175], v[226:229], v[96:99]
	v_mfma_f32_16x16x32_bf16 v[92:95], v[176:179], v[214:217], v[92:95]
	v_mfma_f32_16x16x32_bf16 v[84:87], v[176:179], v[218:221], v[84:87]
	v_mfma_f32_16x16x32_bf16 v[80:83], v[176:179], v[222:225], v[80:83]
	v_mfma_f32_16x16x32_bf16 v[76:79], v[176:179], v[226:229], v[76:79]
	v_mfma_f32_16x16x32_bf16 v[72:75], v[180:183], v[214:217], v[72:75]
	v_mfma_f32_16x16x32_bf16 v[68:71], v[180:183], v[218:221], v[68:71]
	v_mfma_f32_16x16x32_bf16 v[64:67], v[180:183], v[222:225], v[64:67]
	v_mfma_f32_16x16x32_bf16 v[60:63], v[180:183], v[226:229], v[60:63]
	s_waitcnt lgkmcnt(0)
	v_mfma_f32_16x16x32_bf16 v[56:59], v[198:201], v[214:217], v[56:59]
	s_waitcnt vmcnt(0)
	s_barrier
	v_add_u32_e32 v164, v151, v150
	v_add_u32_e32 v134, v151, v148
	v_mfma_f32_16x16x32_bf16 v[52:55], v[198:201], v[218:221], v[52:55]
	ds_read_b128 v[152:155], v164 offset:32768
	ds_read_b128 v[156:159], v164 offset:34816
	v_mfma_f32_16x16x32_bf16 v[48:51], v[198:201], v[222:225], v[48:51]
	ds_read_b128 v[160:163], v164 offset:36864
	ds_read_b128 v[164:167], v164 offset:38912
	v_mfma_f32_16x16x32_bf16 v[44:47], v[198:201], v[226:229], v[44:47]
	ds_read_b128 v[168:171], v134 offset:0
	ds_read_b128 v[172:175], v134 offset:2048
	v_mfma_f32_16x16x32_bf16 v[40:43], v[202:205], v[214:217], v[40:43]
	ds_read_b128 v[176:179], v134 offset:4096
	ds_read_b128 v[180:183], v134 offset:6144
	s_add_i32 m0, s93, 0x10000
	v_mfma_f32_16x16x32_bf16 v[36:39], v[202:205], v[218:221], v[36:39]
	global_load_lds_dwordx4 v[128:129], off
	v_lshl_add_u64 v[128:129], v[128:129], 0, s[100:101]
	s_add_i32 m0, s93, 0x18000
	v_mfma_f32_16x16x32_bf16 v[32:35], v[202:205], v[222:225], v[32:35]
	global_load_lds_dwordx4 v[140:141], off
	v_lshl_add_u64 v[140:141], v[140:141], 0, s[100:101]
	s_add_i32 m0, s94, 0x10000
	v_mfma_f32_16x16x32_bf16 v[28:31], v[202:205], v[226:229], v[28:31]
	global_load_lds_dwordx4 v[130:131], off
	v_lshl_add_u64 v[130:131], v[130:131], 0, s[100:101]
	s_add_i32 m0, s94, 0x18000
	v_mfma_f32_16x16x32_bf16 v[24:27], v[206:209], v[214:217], v[24:27]
	global_load_lds_dwordx4 v[142:143], off
	v_lshl_add_u64 v[142:143], v[142:143], 0, s[100:101]
	s_add_i32 m0, s95, 0x10000
	v_mfma_f32_16x16x32_bf16 v[20:23], v[206:209], v[218:221], v[20:23]
	global_load_lds_dwordx4 v[136:137], off
	v_lshl_add_u64 v[136:137], v[136:137], 0, s[100:101]
	s_add_i32 m0, s95, 0x18000
	v_mfma_f32_16x16x32_bf16 v[16:19], v[206:209], v[222:225], v[16:19]
	global_load_lds_dwordx4 v[144:145], off
	v_lshl_add_u64 v[144:145], v[144:145], 0, s[100:101]
	s_add_i32 m0, s96, 0x10000
	v_mfma_f32_16x16x32_bf16 v[12:15], v[206:209], v[226:229], v[12:15]
	global_load_lds_dwordx4 v[138:139], off
	v_lshl_add_u64 v[138:139], v[138:139], 0, s[100:101]
	s_add_i32 m0, s96, 0x18000
	v_mfma_f32_16x16x32_bf16 v[8:11], v[210:213], v[214:217], v[8:11]
	global_load_lds_dwordx4 v[146:147], off
	v_lshl_add_u64 v[146:147], v[146:147], 0, s[100:101]
	v_mfma_f32_16x16x32_bf16 v[4:7], v[210:213], v[218:221], v[4:7]
	v_mfma_f32_16x16x32_bf16 v[0:3], v[210:213], v[222:225], v[0:3]
	v_mfma_f32_16x16x32_bf16 v[88:91], v[210:213], v[226:229], v[88:91]
	s_add_u32 s2, s2, 0x100
	s_cmpk_lg_i32 s2, 0x700
	s_cbranch_scc1 .Lg_up_loop
	ds_read_b128 v[198:201], v134 offset:8192
	ds_read_b128 v[202:205], v134 offset:10240
	ds_read_b128 v[206:209], v134 offset:12288
	ds_read_b128 v[210:213], v134 offset:14336
	s_waitcnt lgkmcnt(4)
	v_mfma_f32_16x16x32_bf16 v[124:127], v[168:171], v[152:155], v[124:127]
	v_mfma_f32_16x16x32_bf16 v[120:123], v[168:171], v[156:159], v[120:123]
	v_mfma_f32_16x16x32_bf16 v[116:119], v[168:171], v[160:163], v[116:119]
	v_mfma_f32_16x16x32_bf16 v[112:115], v[168:171], v[164:167], v[112:115]
	v_mfma_f32_16x16x32_bf16 v[108:111], v[172:175], v[152:155], v[108:111]
	v_mfma_f32_16x16x32_bf16 v[104:107], v[172:175], v[156:159], v[104:107]
	v_mfma_f32_16x16x32_bf16 v[100:103], v[172:175], v[160:163], v[100:103]
	v_mfma_f32_16x16x32_bf16 v[96:99], v[172:175], v[164:167], v[96:99]
	v_mfma_f32_16x16x32_bf16 v[92:95], v[176:179], v[152:155], v[92:95]
	v_mfma_f32_16x16x32_bf16 v[84:87], v[176:179], v[156:159], v[84:87]
	v_mfma_f32_16x16x32_bf16 v[80:83], v[176:179], v[160:163], v[80:83]
	v_mfma_f32_16x16x32_bf16 v[76:79], v[176:179], v[164:167], v[76:79]
	v_mfma_f32_16x16x32_bf16 v[72:75], v[180:183], v[152:155], v[72:75]
	v_mfma_f32_16x16x32_bf16 v[68:71], v[180:183], v[156:159], v[68:71]
	v_mfma_f32_16x16x32_bf16 v[64:67], v[180:183], v[160:163], v[64:67]
	v_mfma_f32_16x16x32_bf16 v[60:63], v[180:183], v[164:167], v[60:63]
	v_add_u32_e32 v180, v149, v150
	v_add_u32_e32 v134, v149, v148
	ds_read_b128 v[168:171], v180 offset:32768
	ds_read_b128 v[172:175], v180 offset:34816
	ds_read_b128 v[176:179], v180 offset:36864
	ds_read_b128 v[180:183], v180 offset:38912
	ds_read_b128 v[214:217], v134 offset:0
	ds_read_b128 v[218:221], v134 offset:2048
	ds_read_b128 v[222:225], v134 offset:4096
	ds_read_b128 v[226:229], v134 offset:6144
	s_waitcnt lgkmcnt(8)
	v_mfma_f32_16x16x32_bf16 v[56:59], v[198:201], v[152:155], v[56:59]
	v_mfma_f32_16x16x32_bf16 v[52:55], v[198:201], v[156:159], v[52:55]
	v_mfma_f32_16x16x32_bf16 v[48:51], v[198:201], v[160:163], v[48:51]
	v_mfma_f32_16x16x32_bf16 v[44:47], v[198:201], v[164:167], v[44:47]
	v_mfma_f32_16x16x32_bf16 v[40:43], v[202:205], v[152:155], v[40:43]
	v_mfma_f32_16x16x32_bf16 v[36:39], v[202:205], v[156:159], v[36:39]
	v_mfma_f32_16x16x32_bf16 v[32:35], v[202:205], v[160:163], v[32:35]
	v_mfma_f32_16x16x32_bf16 v[28:31], v[202:205], v[164:167], v[28:31]
	v_mfma_f32_16x16x32_bf16 v[24:27], v[206:209], v[152:155], v[24:27]
	v_mfma_f32_16x16x32_bf16 v[20:23], v[206:209], v[156:159], v[20:23]
	v_mfma_f32_16x16x32_bf16 v[16:19], v[206:209], v[160:163], v[16:19]
	v_mfma_f32_16x16x32_bf16 v[12:15], v[206:209], v[164:167], v[12:15]
	v_mfma_f32_16x16x32_bf16 v[8:11], v[210:213], v[152:155], v[8:11]
	v_mfma_f32_16x16x32_bf16 v[4:7], v[210:213], v[156:159], v[4:7]
	v_mfma_f32_16x16x32_bf16 v[0:3], v[210:213], v[160:163], v[0:3]
	v_mfma_f32_16x16x32_bf16 v[88:91], v[210:213], v[164:167], v[88:91]
	ds_read_b128 v[152:155], v134 offset:8192
	ds_read_b128 v[156:159], v134 offset:10240
	ds_read_b128 v[160:163], v134 offset:12288
	ds_read_b128 v[164:167], v134 offset:14336
	s_waitcnt lgkmcnt(4)
	v_mfma_f32_16x16x32_bf16 v[124:127], v[214:217], v[168:171], v[124:127]
	v_mfma_f32_16x16x32_bf16 v[120:123], v[214:217], v[172:175], v[120:123]
	v_mfma_f32_16x16x32_bf16 v[116:119], v[214:217], v[176:179], v[116:119]
	v_mfma_f32_16x16x32_bf16 v[112:115], v[214:217], v[180:183], v[112:115]
	v_mfma_f32_16x16x32_bf16 v[108:111], v[218:221], v[168:171], v[108:111]
	v_mfma_f32_16x16x32_bf16 v[104:107], v[218:221], v[172:175], v[104:107]
	v_mfma_f32_16x16x32_bf16 v[100:103], v[218:221], v[176:179], v[100:103]
	v_mfma_f32_16x16x32_bf16 v[96:99], v[218:221], v[180:183], v[96:99]
	v_mfma_f32_16x16x32_bf16 v[92:95], v[222:225], v[168:171], v[92:95]
	v_mfma_f32_16x16x32_bf16 v[84:87], v[222:225], v[172:175], v[84:87]
	v_mfma_f32_16x16x32_bf16 v[80:83], v[222:225], v[176:179], v[80:83]
	v_mfma_f32_16x16x32_bf16 v[76:79], v[222:225], v[180:183], v[76:79]
	v_mfma_f32_16x16x32_bf16 v[72:75], v[226:229], v[168:171], v[72:75]
	v_mfma_f32_16x16x32_bf16 v[68:71], v[226:229], v[172:175], v[68:71]
	v_mfma_f32_16x16x32_bf16 v[64:67], v[226:229], v[176:179], v[64:67]
	v_mfma_f32_16x16x32_bf16 v[60:63], v[226:229], v[180:183], v[60:63]
	s_waitcnt lgkmcnt(0)
	v_mfma_f32_16x16x32_bf16 v[56:59], v[152:155], v[168:171], v[56:59]
	s_waitcnt vmcnt(0)
	s_barrier
	v_lshlrev_b32_e32 v254, 3, v184
	v_and_b32_e32 v254, 0x78, v254
	v_lshl_or_b32 v254, s44, 7, v254
	v_lshlrev_b32_e32 v254, 2, v254
	v_add_u32_e32 v222, 0x2c00, v254
	v_add_u32_e32 v223, 0x5800, v254
	global_load_dwordx4 v[234:237], v254, s[10:11]
	global_load_dwordx4 v[230:233], v254, s[10:11] offset:16
	global_load_dwordx4 v[238:241], v222, s[10:11]
	global_load_dwordx4 v[242:245], v222, s[10:11] offset:16
	global_load_dwordx4 v[246:249], v223, s[10:11]
	global_load_dwordx4 v[250:253], v223, s[10:11] offset:16
	global_load_dwordx4 v[214:217], v254, s[12:13] offset:16
	global_load_dwordx4 v[218:221], v254, s[12:13]
	v_mfma_f32_16x16x32_bf16 v[52:55], v[152:155], v[172:175], v[52:55]
	v_mfma_f32_16x16x32_bf16 v[48:51], v[152:155], v[176:179], v[48:51]
	v_mfma_f32_16x16x32_bf16 v[44:47], v[152:155], v[180:183], v[44:47]
	v_mfma_f32_16x16x32_bf16 v[40:43], v[156:159], v[168:171], v[40:43]
	v_mfma_f32_16x16x32_bf16 v[36:39], v[156:159], v[172:175], v[36:39]
	v_mfma_f32_16x16x32_bf16 v[32:35], v[156:159], v[176:179], v[32:35]
	v_mfma_f32_16x16x32_bf16 v[28:31], v[156:159], v[180:183], v[28:31]
	v_mfma_f32_16x16x32_bf16 v[24:27], v[160:163], v[168:171], v[24:27]
	v_mfma_f32_16x16x32_bf16 v[20:23], v[160:163], v[172:175], v[20:23]
	v_mfma_f32_16x16x32_bf16 v[16:19], v[160:163], v[176:179], v[16:19]
	v_mfma_f32_16x16x32_bf16 v[12:15], v[160:163], v[180:183], v[12:15]
	v_mfma_f32_16x16x32_bf16 v[8:11], v[164:167], v[168:171], v[8:11]
	v_mfma_f32_16x16x32_bf16 v[4:7], v[164:167], v[172:175], v[4:7]
	v_mfma_f32_16x16x32_bf16 v[0:3], v[164:167], v[176:179], v[0:3]
	v_mfma_f32_16x16x32_bf16 v[88:91], v[164:167], v[180:183], v[88:91]
	s_movk_i32 s2, 0x780
	s_mov_b32 s97, 0xf0000
	v_add3_u32 v134, v148, v151, s75
	ds_read_b128 v[128:131], v134 offset:14336
	ds_read_b128 v[136:139], v134 offset:12288
	ds_read_b128 v[140:143], v134 offset:10240
	ds_read_b128 v[144:147], v134 offset:8192
	ds_read_b128 v[152:155], v134 offset:6144
	ds_read_b128 v[156:159], v134 offset:4096
	ds_read_b128 v[160:163], v134 offset:2048
	ds_read_b128 v[164:167], v134
	v_add3_u32 v134, v150, v151, s63
	ds_read_b128 v[168:171], v134 offset:6144
	ds_read_b128 v[172:175], v134 offset:4096
	ds_read_b128 v[176:179], v134 offset:2048
	ds_read_b128 v[180:183], v134
	s_waitcnt lgkmcnt(0)
	v_mfma_f32_16x16x32_bf16 v[124:127], v[164:167], v[180:183], v[124:127]
	v_mfma_f32_16x16x32_bf16 v[120:123], v[164:167], v[176:179], v[120:123]
	v_mfma_f32_16x16x32_bf16 v[116:119], v[164:167], v[172:175], v[116:119]
	v_mfma_f32_16x16x32_bf16 v[112:115], v[164:167], v[168:171], v[112:115]
	v_mfma_f32_16x16x32_bf16 v[108:111], v[160:163], v[180:183], v[108:111]
	v_mfma_f32_16x16x32_bf16 v[104:107], v[160:163], v[176:179], v[104:107]
	v_mfma_f32_16x16x32_bf16 v[100:103], v[160:163], v[172:175], v[100:103]
	v_mfma_f32_16x16x32_bf16 v[96:99], v[160:163], v[168:171], v[96:99]
	v_mfma_f32_16x16x32_bf16 v[92:95], v[156:159], v[180:183], v[92:95]
	v_mfma_f32_16x16x32_bf16 v[84:87], v[156:159], v[176:179], v[84:87]
	v_mfma_f32_16x16x32_bf16 v[80:83], v[156:159], v[172:175], v[80:83]
	v_mfma_f32_16x16x32_bf16 v[76:79], v[156:159], v[168:171], v[76:79]
	v_mfma_f32_16x16x32_bf16 v[72:75], v[152:155], v[180:183], v[72:75]
	v_mfma_f32_16x16x32_bf16 v[68:71], v[152:155], v[176:179], v[68:71]
	v_mfma_f32_16x16x32_bf16 v[64:67], v[152:155], v[172:175], v[64:67]
	v_mfma_f32_16x16x32_bf16 v[60:63], v[152:155], v[168:171], v[60:63]
	v_add3_u32 v134, v150, v149, s63
	ds_read_b128 v[150:153], v134
	ds_read_b128 v[154:157], v134 offset:2048
	ds_read_b128 v[158:161], v134 offset:4096
	ds_read_b128 v[162:165], v134 offset:6144
	v_add3_u32 v134, v148, v149, s75
	ds_read_b128 v[198:201], v134
	ds_read_b128 v[202:205], v134 offset:2048
	ds_read_b128 v[206:209], v134 offset:4096
	ds_read_b128 v[210:213], v134 offset:6144
	v_mfma_f32_16x16x32_bf16 v[44:47], v[144:147], v[168:171], v[44:47]
	v_mfma_f32_16x16x32_bf16 v[40:43], v[140:143], v[180:183], v[40:43]
	v_mfma_f32_16x16x32_bf16 v[28:31], v[140:143], v[168:171], v[28:31]
	v_mfma_f32_16x16x32_bf16 v[24:27], v[136:139], v[180:183], v[24:27]
	v_mfma_f32_16x16x32_bf16 v[20:23], v[136:139], v[176:179], v[20:23]
	v_mfma_f32_16x16x32_bf16 v[16:19], v[136:139], v[172:175], v[16:19]
	v_mfma_f32_16x16x32_bf16 v[12:15], v[136:139], v[168:171], v[12:15]
	v_mfma_f32_16x16x32_bf16 v[8:11], v[128:131], v[180:183], v[8:11]
	v_mfma_f32_16x16x32_bf16 v[4:7], v[128:131], v[176:179], v[4:7]
	v_mfma_f32_16x16x32_bf16 v[0:3], v[128:131], v[172:175], v[0:3]
	v_mfma_f32_16x16x32_bf16 v[56:59], v[144:147], v[180:183], v[56:59]
	v_mfma_f32_16x16x32_bf16 v[52:55], v[144:147], v[176:179], v[52:55]
	v_mfma_f32_16x16x32_bf16 v[48:51], v[144:147], v[172:175], v[48:51]
	v_mfma_f32_16x16x32_bf16 v[36:39], v[140:143], v[176:179], v[36:39]
	v_mfma_f32_16x16x32_bf16 v[32:35], v[140:143], v[172:175], v[32:35]
	v_mfma_f32_16x16x32_bf16 v[88:91], v[128:131], v[168:171], v[88:91]
	ds_read_b128 v[128:131], v134 offset:8192
	ds_read_b128 v[136:139], v134 offset:10240
	ds_read_b128 v[140:143], v134 offset:12288
	ds_read_b128 v[144:147], v134 offset:14336
	s_waitcnt lgkmcnt(0)
	v_mfma_f32_16x16x32_bf16 v[124:127], v[198:201], v[150:153], v[124:127]
	v_mfma_f32_16x16x32_bf16 v[120:123], v[198:201], v[154:157], v[120:123]
	v_mfma_f32_16x16x32_bf16 v[116:119], v[198:201], v[158:161], v[116:119]
	v_mfma_f32_16x16x32_bf16 v[112:115], v[198:201], v[162:165], v[112:115]
	v_mfma_f32_16x16x32_bf16 v[108:111], v[202:205], v[150:153], v[108:111]
	v_mfma_f32_16x16x32_bf16 v[104:107], v[202:205], v[154:157], v[104:107]
	v_mfma_f32_16x16x32_bf16 v[100:103], v[202:205], v[158:161], v[100:103]
	v_mfma_f32_16x16x32_bf16 v[96:99], v[202:205], v[162:165], v[96:99]
	v_mfma_f32_16x16x32_bf16 v[92:95], v[206:209], v[150:153], v[92:95]
	v_mfma_f32_16x16x32_bf16 v[84:87], v[206:209], v[154:157], v[84:87]
	v_mfma_f32_16x16x32_bf16 v[80:83], v[206:209], v[158:161], v[80:83]
	v_mfma_f32_16x16x32_bf16 v[76:79], v[206:209], v[162:165], v[76:79]
	v_mfma_f32_16x16x32_bf16 v[72:75], v[210:213], v[150:153], v[72:75]
	v_mfma_f32_16x16x32_bf16 v[68:71], v[210:213], v[154:157], v[68:71]
	v_mfma_f32_16x16x32_bf16 v[64:67], v[210:213], v[158:161], v[64:67]
	v_mfma_f32_16x16x32_bf16 v[60:63], v[210:213], v[162:165], v[60:63]
	v_mov_b32_e32 v148, v184
	v_mfma_f32_16x16x32_bf16 v[24:27], v[140:143], v[150:153], v[24:27]
	s_waitcnt lgkmcnt(0)
	s_barrier
	v_mfma_f32_16x16x32_bf16 v[8:11], v[144:147], v[150:153], v[8:11]
	s_nop 5
	v_cvt_pk_bf16_f32 v24, v24, v25
	v_lshrrev_b32_e32 v134, 8, v148
	v_mul_i32_i24_e32 v134, 0x11000, v134
	v_lshrrev_b32_e32 v166, 1, v148
	v_and_b32_e32 v149, 0xcf, v148
	v_and_or_b32 v134, v166, 24, v134
	v_mfma_f32_16x16x32_bf16 v[56:59], v[128:131], v[150:153], v[56:59]
	v_cvt_pk_bf16_f32 v25, v26, v27
	v_cvt_pk_bf16_f32 v8, v8, v9
	v_cvt_pk_bf16_f32 v9, v10, v11
	v_mfma_f32_16x16x32_bf16 v[52:55], v[128:131], v[154:157], v[52:55]
	s_mov_b64 s[2:3], 0x2c00
	s_nop 2
	v_cvt_pk_bf16_f32 v56, v56, v57
	v_cvt_pk_bf16_f32 v57, v58, v59
	v_mfma_f32_16x16x32_bf16 v[48:51], v[128:131], v[158:161], v[48:51]
	v_cvt_pk_bf16_f32 v124, v124, v125
	v_cvt_pk_bf16_f32 v125, v126, v127
	v_cvt_pk_bf16_f32 v108, v108, v109
	v_mfma_f32_16x16x32_bf16 v[44:47], v[128:131], v[162:165], v[44:47]
	v_mad_u32_u24 v128, v149, s51, v134
	ds_write2_b64 v128, v[24:25], v[8:9] offset0:24 offset1:28
	v_cvt_pk_bf16_f32 v24, v52, v53
	v_mfma_f32_16x16x32_bf16 v[40:43], v[136:139], v[150:153], v[40:43]
	v_cvt_pk_bf16_f32 v25, v54, v55
	v_cvt_pk_bf16_f32 v109, v110, v111
	v_cvt_pk_bf16_f32 v92, v92, v93
	v_mfma_f32_16x16x32_bf16 v[8:11], v[140:143], v[154:157], v[20:23]
	v_cvt_pk_bf16_f32 v93, v94, v95
	s_nop 2
	v_cvt_pk_bf16_f32 v40, v40, v41
	v_cvt_pk_bf16_f32 v41, v42, v43
	v_mfma_f32_16x16x32_bf16 v[4:7], v[144:147], v[154:157], v[4:7]
	ds_write2_b64 v128, v[56:57], v[40:41] offset0:16 offset1:20
	v_add_u32_e32 v40, 0x1000, v128
	v_cvt_pk_bf16_f32 v8, v8, v9
	v_mfma_f32_16x16x32_bf16 v[32:35], v[136:139], v[158:161], v[32:35]
	v_cvt_pk_bf16_f32 v9, v10, v11
	s_nop 2
	v_cvt_pk_bf16_f32 v4, v4, v5
	v_cvt_pk_bf16_f32 v5, v6, v7
	v_mfma_f32_16x16x32_bf16 v[16:19], v[140:143], v[158:161], v[16:19]
	ds_write2_b64 v40, v[8:9], v[4:5] offset0:56 offset1:60
	v_cvt_pk_bf16_f32 v4, v116, v117
	v_cvt_pk_bf16_f32 v5, v118, v119
	v_mfma_f32_16x16x32_bf16 v[0:3], v[144:147], v[158:161], v[0:3]
	v_cvt_pk_bf16_f32 v6, v100, v101
	v_cvt_pk_bf16_f32 v7, v102, v103
	v_add_u32_e32 v8, 0x2000, v128
	v_cvt_pk_bf16_f32 v20, v120, v121
	v_cvt_pk_bf16_f32 v21, v122, v123
	v_cvt_pk_bf16_f32 v22, v104, v105
	v_cvt_pk_bf16_f32 v23, v106, v107
	ds_write2_b64 v8, v[4:5], v[6:7] offset0:64 offset1:68
	v_cvt_pk_bf16_f32 v4, v80, v81
	v_cvt_pk_bf16_f32 v5, v82, v83
	v_cvt_pk_bf16_f32 v6, v64, v65
	v_cvt_pk_bf16_f32 v7, v66, v67
	v_mfma_f32_16x16x32_bf16 v[28:31], v[136:139], v[162:165], v[28:31]
	ds_write2_b64 v40, v[20:21], v[22:23] offset0:32 offset1:36
	v_cvt_pk_bf16_f32 v20, v84, v85
	v_cvt_pk_bf16_f32 v21, v86, v87
	v_cvt_pk_bf16_f32 v22, v68, v69
	v_cvt_pk_bf16_f32 v23, v70, v71
	ds_write2_b64 v8, v[4:5], v[6:7] offset0:72 offset1:76
	v_cvt_pk_bf16_f32 v4, v48, v49
	v_cvt_pk_bf16_f32 v5, v50, v51
	v_cvt_pk_bf16_f32 v6, v32, v33
	v_cvt_pk_bf16_f32 v7, v34, v35
	v_mfma_f32_16x16x32_bf16 v[12:15], v[140:143], v[162:165], v[12:15]
	ds_write2_b64 v40, v[20:21], v[22:23] offset0:40 offset1:44
	ds_write2_b64 v8, v[4:5], v[6:7] offset0:80 offset1:84
	v_cvt_pk_bf16_f32 v4, v16, v17
	v_mfma_f32_16x16x32_bf16 v[20:23], v[144:147], v[162:165], v[88:91]
	v_cvt_pk_bf16_f32 v5, v18, v19
	v_cvt_pk_bf16_f32 v0, v0, v1
	v_cvt_pk_bf16_f32 v1, v2, v3
	ds_write2_b64 v8, v[4:5], v[0:1] offset0:88 offset1:92
	v_cvt_pk_bf16_f32 v0, v112, v113
	v_cvt_pk_bf16_f32 v1, v114, v115
	v_cvt_pk_bf16_f32 v2, v96, v97
	v_cvt_pk_bf16_f32 v3, v98, v99
	v_add_u32_e32 v4, 0x3000, v128
	ds_write2_b64 v4, v[0:1], v[2:3] offset0:96 offset1:100
	v_cvt_pk_bf16_f32 v0, v76, v77
	v_cvt_pk_bf16_f32 v1, v78, v79
	v_cvt_pk_bf16_f32 v2, v60, v61
	v_cvt_pk_bf16_f32 v3, v62, v63
	v_mfma_f32_16x16x32_bf16 v[36:39], v[136:139], v[154:157], v[36:39]
	ds_write2_b64 v4, v[0:1], v[2:3] offset0:104 offset1:108
	v_cvt_pk_bf16_f32 v0, v44, v45
	v_cvt_pk_bf16_f32 v1, v46, v47
	v_cvt_pk_bf16_f32 v2, v28, v29
	v_cvt_pk_bf16_f32 v3, v30, v31
	ds_write2_b64 v4, v[0:1], v[2:3] offset0:112 offset1:116
	v_cvt_pk_bf16_f32 v0, v12, v13
	v_cvt_pk_bf16_f32 v1, v14, v15
	v_cvt_pk_bf16_f32 v2, v20, v21
	v_cvt_pk_bf16_f32 v3, v22, v23
	ds_write2_b64 v4, v[0:1], v[2:3] offset0:120 offset1:124
	v_lshlrev_b32_e32 v0, 3, v148
	v_and_b32_e32 v32, 0x78, v0
	v_cvt_pk_bf16_f32 v26, v36, v37
	v_cvt_pk_bf16_f32 v27, v38, v39
	v_lshl_or_b32 v134, s44, 7, v32
	ds_write2_b64 v40, v[24:25], v[26:27] offset0:48 offset1:52
	v_lshlrev_b64 v[24:25], 2, v[134:135]
	v_lshl_add_u64 v[16:17], s[10:11], 0, v[24:25]
	v_cvt_pk_bf16_f32 v72, v72, v73
	v_cvt_pk_bf16_f32 v73, v74, v75
	v_lshl_add_u64 v[12:13], v[16:17], 0, s[2:3]
	s_movk_i32 s2, 0x2000
	ds_write2_b64 v128, v[124:125], v[108:109] offset1:4
	ds_write2_b64 v128, v[92:93], v[72:73] offset0:8 offset1:12
	v_add_co_u32_e32 v8, vcc, s2, v16
	s_mov_b64 s[2:3], 0x5800
	s_waitcnt lgkmcnt(0)
	s_barrier
	v_addc_co_u32_e32 v9, vcc, 0, v17, vcc
	v_lshl_add_u64 v[20:21], v[16:17], 0, s[2:3]
	s_movk_i32 s2, 0x5000
	v_add_co_u32_e32 v16, vcc, s2, v16
	v_lshl_add_u64 v[28:29], s[12:13], 0, v[24:25]
	s_nop 0
	v_addc_co_u32_e32 v17, vcc, 0, v17, vcc
	s_nop 0
	s_nop 0
	s_nop 0
	s_nop 0
	s_nop 0
	v_ashrrev_i32_e32 v33, 4, v148
	v_mul_lo_u32 v34, v33, s51
	s_mov_b32 s44, 0
	v_lshl_add_u64 v[40:41], v[134:135], 1, s[22:23]
	v_lshl_add_u32 v44, v32, 1, v34
	v_add_u32_e32 v45, 31, v33
	s_waitcnt vmcnt(0)
	s_mov_b32 s32, 1
	s_add_i32 s2, s92, 0xff
	s_ashr_i32 s3, s92, 12
	s_ashr_i32 s2, s2, 12
	s_cmp_eq_u32 s2, s3
	s_cbranch_scc1 .Lup_fast
	s_mov_b32 s32, 3
	s_add_i32 s2, s92, 0xff
	s_cmp_lt_i32 s2, s81
	s_cbranch_scc1 .Lup_fast
	s_mov_b32 s32, 0
	s_branch .LBB0_2308
.Lup_fast:
	v_mov_b32_e32 v183, 0x3eed3388
	v_mov_b32_e32 v126, 0xc038aa3b
	v_mov_b32_e32 v127, 0xc038aa3b
	v_mov_b64_e32 v[180:181], s[76:77]
	v_pk_mul_f32 v[234:235], v[234:235], 0.5 op_sel_hi:[1,0]
	v_pk_mul_f32 v[236:237], v[236:237], 0.5 op_sel_hi:[1,0]
	v_pk_mul_f32 v[230:231], v[230:231], 0.5 op_sel_hi:[1,0]
	v_pk_mul_f32 v[232:233], v[232:233], 0.5 op_sel_hi:[1,0]
	v_pk_mul_f32 v[238:239], v[238:239], 0.5 op_sel_hi:[1,0]
	v_pk_mul_f32 v[240:241], v[240:241], 0.5 op_sel_hi:[1,0]
	v_pk_mul_f32 v[242:243], v[242:243], 0.5 op_sel_hi:[1,0]
	v_pk_mul_f32 v[244:245], v[244:245], 0.5 op_sel_hi:[1,0]
	v_pk_mul_f32 v[246:247], v[246:247], 0.5 op_sel_hi:[1,0]
	v_pk_mul_f32 v[248:249], v[248:249], 0.5 op_sel_hi:[1,0]
	v_pk_mul_f32 v[250:251], v[250:251], 0.5 op_sel_hi:[1,0]
	v_pk_mul_f32 v[252:253], v[252:253], 0.5 op_sel_hi:[1,0]
	v_pk_mul_f32 v[218:219], v[218:219], 0.5 op_sel_hi:[1,0]
	v_pk_mul_f32 v[220:221], v[220:221], 0.5 op_sel_hi:[1,0]
	v_pk_mul_f32 v[214:215], v[214:215], 0.5 op_sel_hi:[1,0]
	v_pk_mul_f32 v[216:217], v[216:217], 0.5 op_sel_hi:[1,0]
	v_lshlrev_b32_e32 v13, 1, v32
	v_lshl_add_u32 v222, v34, 3, v13
	v_add_u32_e32 v223, 0x11000, v222
	v_subrev_u32_e32 v213, 0x110, v222
	v_max_i32_e32 v213, v213, v13
	v_mov_b32_e32 v212, v33
	v_lshl_add_u32 v14, v33, 3, s36
	v_add_u32_e32 v14, -1, v14
	v_mad_i64_i32 v[228:229], vcc, v14, s35, v[40:41]
	ds_read_b128 v[16:19], v213
	ds_read_b128 v[20:23], v222
	ds_read_b128 v[24:27], v222 offset:272
	ds_read_b128 v[56:59], v223
	ds_read_b128 v[28:31], v222 offset:544
	ds_read_b128 v[60:63], v223 offset:272
	ds_read_b128 v[32:35], v222 offset:816
	ds_read_b128 v[64:67], v223 offset:544
	ds_read_b128 v[36:39], v222 offset:1088
	ds_read_b128 v[68:71], v223 offset:816
	ds_read_b128 v[40:43], v222 offset:1360
	ds_read_b128 v[72:75], v223 offset:1088
	ds_read_b128 v[44:47], v222 offset:1632
	ds_read_b128 v[76:79], v223 offset:1360
	ds_read_b128 v[48:51], v222 offset:1904
	ds_read_b128 v[80:83], v223 offset:1632
	ds_read_b128 v[52:55], v222 offset:2176
	ds_read_b128 v[84:87], v223 offset:1904
	s_branch .LBB0_2297
.Lup_rows:
	s_bitcmp1_b32 s32, 1
	s_cbranch_scc1 .Lup_rows_b
.Lup_rows_a:
	s_mov_b32 s98, 0x1600
	s_mov_b32 s99, 0
	s_waitcnt lgkmcnt(0)
	v_lshlrev_b32_e32 v88, 16, v16
	v_and_b32_e32 v89, 0xffff0000, v16
	v_lshlrev_b32_e32 v90, 16, v17
	v_and_b32_e32 v91, 0xffff0000, v17
	v_lshlrev_b32_e32 v92, 16, v18
	v_and_b32_e32 v93, 0xffff0000, v18
	v_lshlrev_b32_e32 v94, 16, v19
	v_and_b32_e32 v95, 0xffff0000, v19
	v_lshlrev_b32_e32 v96, 16, v20
	v_and_b32_e32 v97, 0xffff0000, v20
	v_lshlrev_b32_e32 v98, 16, v21
	v_and_b32_e32 v99, 0xffff0000, v21
	v_lshlrev_b32_e32 v100, 16, v22
	v_and_b32_e32 v101, 0xffff0000, v22
	v_lshlrev_b32_e32 v102, 16, v23
	v_and_b32_e32 v103, 0xffff0000, v23
	v_lshlrev_b32_e32 v104, 16, v24
	v_and_b32_e32 v105, 0xffff0000, v24
	v_lshlrev_b32_e32 v106, 16, v25
	v_and_b32_e32 v107, 0xffff0000, v25
	v_lshlrev_b32_e32 v108, 16, v26
	v_and_b32_e32 v109, 0xffff0000, v26
	v_lshlrev_b32_e32 v110, 16, v27
	v_and_b32_e32 v111, 0xffff0000, v27
	v_pk_fma_f32 v[112:113], v[234:235], v[88:89], v[218:219]
	v_pk_fma_f32 v[152:153], v[236:237], v[90:91], v[220:221]
	v_pk_fma_f32 v[166:167], v[230:231], v[92:93], v[214:215]
	v_pk_fma_f32 v[198:199], v[232:233], v[94:95], v[216:217]
	v_pk_fma_f32 v[112:113], v[238:239], v[96:97], v[112:113]
	v_pk_fma_f32 v[152:153], v[240:241], v[98:99], v[152:153]
	v_pk_fma_f32 v[166:167], v[242:243], v[100:101], v[166:167]
	v_pk_fma_f32 v[198:199], v[244:245], v[102:103], v[198:199]
	v_pk_fma_f32 v[112:113], v[246:247], v[104:105], v[112:113]
	v_pk_fma_f32 v[152:153], v[248:249], v[106:107], v[152:153]
	v_pk_fma_f32 v[166:167], v[250:251], v[108:109], v[166:167]
	v_pk_fma_f32 v[198:199], v[252:253], v[110:111], v[198:199]
	v_fma_f32 v114, |v112|, v183, 1.0
	v_fma_f32 v115, |v113|, v183, 1.0
	v_fma_f32 v154, |v152|, v183, 1.0
	v_fma_f32 v155, |v153|, v183, 1.0
	v_fma_f32 v168, |v166|, v183, 1.0
	v_fma_f32 v169, |v167|, v183, 1.0
	v_fma_f32 v200, |v198|, v183, 1.0
	v_fma_f32 v201, |v199|, v183, 1.0
	v_mul_f32_e32 v116, v114, v115
	v_mul_f32_e32 v156, v154, v155
	v_mul_f32_e32 v170, v168, v169
	v_mul_f32_e32 v202, v200, v201
	v_pk_mul_f32 v[118:119], v[112:113], v[112:113]
	v_pk_mul_f32 v[158:159], v[152:153], v[152:153]
	v_pk_mul_f32 v[172:173], v[166:167], v[166:167]
	v_pk_mul_f32 v[204:205], v[198:199], v[198:199]
	v_rcp_f32_e32 v116, v116
	v_rcp_f32_e32 v156, v156
	v_rcp_f32_e32 v170, v170
	v_rcp_f32_e32 v202, v202
	v_pk_mul_f32 v[118:119], v[118:119], v[126:127]
	v_pk_mul_f32 v[158:159], v[158:159], v[126:127]
	v_pk_mul_f32 v[172:173], v[172:173], v[126:127]
	v_pk_mul_f32 v[204:205], v[204:205], v[126:127]
	v_pk_mul_f32 v[114:115], v[114:115], v[116:117] op_sel:[1,0] op_sel_hi:[0,0]
	v_pk_mul_f32 v[154:155], v[154:155], v[156:157] op_sel:[1,0] op_sel_hi:[0,0]
	v_pk_mul_f32 v[168:169], v[168:169], v[170:171] op_sel:[1,0] op_sel_hi:[0,0]
	v_pk_mul_f32 v[200:201], v[200:201], v[202:203] op_sel:[1,0] op_sel_hi:[0,0]
	v_exp_f32_e32 v118, v118
	v_exp_f32_e32 v119, v119
	v_exp_f32_e32 v158, v158
	v_exp_f32_e32 v159, v159
	v_exp_f32_e32 v172, v172
	v_exp_f32_e32 v173, v173
	v_exp_f32_e32 v204, v204
	v_exp_f32_e32 v205, v205
	v_pk_fma_f32 v[120:121], v[114:115], s[74:75], v[180:181] op_sel_hi:[1,0,0]
	v_pk_fma_f32 v[160:161], v[154:155], s[74:75], v[180:181] op_sel_hi:[1,0,0]
	v_pk_fma_f32 v[174:175], v[168:169], s[74:75], v[180:181] op_sel_hi:[1,0,0]
	v_pk_fma_f32 v[206:207], v[200:201], s[74:75], v[180:181] op_sel_hi:[1,0,0]
	v_pk_fma_f32 v[120:121], v[114:115], v[120:121], s[78:79] op_sel_hi:[1,1,0]
	v_pk_fma_f32 v[160:161], v[154:155], v[160:161], s[78:79] op_sel_hi:[1,1,0]
	v_pk_fma_f32 v[174:175], v[168:169], v[174:175], s[78:79] op_sel_hi:[1,1,0]
	v_pk_fma_f32 v[206:207], v[200:201], v[206:207], s[78:79] op_sel_hi:[1,1,0]
	v_pk_fma_f32 v[120:121], v[114:115], v[120:121], s[80:81] op_sel_hi:[1,1,0]
	v_pk_fma_f32 v[160:161], v[154:155], v[160:161], s[80:81] op_sel_hi:[1,1,0]
	v_pk_fma_f32 v[174:175], v[168:169], v[174:175], s[80:81] op_sel_hi:[1,1,0]
	v_pk_fma_f32 v[206:207], v[200:201], v[206:207], s[80:81] op_sel_hi:[1,1,0]
	v_pk_fma_f32 v[120:121], v[114:115], v[120:121], s[82:83] op_sel_hi:[1,1,0]
	v_pk_fma_f32 v[160:161], v[154:155], v[160:161], s[82:83] op_sel_hi:[1,1,0]
	v_pk_fma_f32 v[174:175], v[168:169], v[174:175], s[82:83] op_sel_hi:[1,1,0]
	v_pk_fma_f32 v[206:207], v[200:201], v[206:207], s[82:83] op_sel_hi:[1,1,0]
	v_pk_mul_f32 v[120:121], v[114:115], v[120:121]
	v_pk_mul_f32 v[160:161], v[154:155], v[160:161]
	v_pk_mul_f32 v[174:175], v[168:169], v[174:175]
	v_pk_mul_f32 v[206:207], v[200:201], v[206:207]
	v_pk_fma_f32 v[118:119], v[118:119], v[120:121], 1.0 op_sel_hi:[1,1,0] neg_lo:[1,0,0] neg_hi:[1,0,0]
	v_pk_fma_f32 v[158:159], v[158:159], v[160:161], 1.0 op_sel_hi:[1,1,0] neg_lo:[1,0,0] neg_hi:[1,0,0]
	v_pk_fma_f32 v[172:173], v[172:173], v[174:175], 1.0 op_sel_hi:[1,1,0] neg_lo:[1,0,0] neg_hi:[1,0,0]
	v_pk_fma_f32 v[204:205], v[204:205], v[206:207], 1.0 op_sel_hi:[1,1,0] neg_lo:[1,0,0] neg_hi:[1,0,0]
	v_bfi_b32 v119, s34, v119, v113
	v_bfi_b32 v118, s34, v118, v112
	v_bfi_b32 v159, s34, v159, v153
	v_bfi_b32 v158, s34, v158, v152
	v_bfi_b32 v173, s34, v173, v167
	v_bfi_b32 v172, s34, v172, v166
	v_bfi_b32 v205, s34, v205, v199
	v_bfi_b32 v204, s34, v204, v198
	v_lshlrev_b32_e32 v124, 16, v56
	v_and_b32_e32 v125, 0xffff0000, v56
	v_lshlrev_b32_e32 v164, 16, v57
	v_and_b32_e32 v165, 0xffff0000, v57
	v_lshlrev_b32_e32 v178, 16, v58
	v_and_b32_e32 v179, 0xffff0000, v58
	v_lshlrev_b32_e32 v210, 16, v59
	v_and_b32_e32 v211, 0xffff0000, v59
	v_pk_fma_f32 v[112:113], v[112:113], v[118:119], v[112:113]
	v_pk_fma_f32 v[152:153], v[152:153], v[158:159], v[152:153]
	v_pk_fma_f32 v[166:167], v[166:167], v[172:173], v[166:167]
	v_pk_fma_f32 v[198:199], v[198:199], v[204:205], v[198:199]
	v_pk_mul_f32 v[112:113], v[112:113], v[124:125]
	v_pk_mul_f32 v[152:153], v[152:153], v[164:165]
	v_pk_mul_f32 v[166:167], v[166:167], v[178:179]
	v_pk_mul_f32 v[198:199], v[198:199], v[210:211]
	v_cvt_pk_bf16_f32 v224, v112, v113
	v_cvt_pk_bf16_f32 v225, v152, v153
	v_cvt_pk_bf16_f32 v226, v166, v167
	v_cvt_pk_bf16_f32 v227, v198, v199
	v_cmp_ne_u32_e32 vcc, 0, v212
	s_and_saveexec_b64 s[100:101], vcc
	global_store_dwordx4 v[228:229], v[224:227], off nt
	s_mov_b64 exec, s[100:101]
	v_lshl_add_u64 v[228:229], v[228:229], 0, s[98:99]
	v_lshlrev_b32_e32 v88, 16, v28
	v_and_b32_e32 v89, 0xffff0000, v28
	v_lshlrev_b32_e32 v90, 16, v29
	v_and_b32_e32 v91, 0xffff0000, v29
	v_lshlrev_b32_e32 v92, 16, v30
	v_and_b32_e32 v93, 0xffff0000, v30
	v_lshlrev_b32_e32 v94, 16, v31
	v_and_b32_e32 v95, 0xffff0000, v31
	v_pk_fma_f32 v[112:113], v[234:235], v[96:97], v[218:219]
	v_pk_fma_f32 v[152:153], v[236:237], v[98:99], v[220:221]
	v_pk_fma_f32 v[166:167], v[230:231], v[100:101], v[214:215]
	v_pk_fma_f32 v[198:199], v[232:233], v[102:103], v[216:217]
	v_pk_fma_f32 v[112:113], v[238:239], v[104:105], v[112:113]
	v_pk_fma_f32 v[152:153], v[240:241], v[106:107], v[152:153]
	v_pk_fma_f32 v[166:167], v[242:243], v[108:109], v[166:167]
	v_pk_fma_f32 v[198:199], v[244:245], v[110:111], v[198:199]
	v_pk_fma_f32 v[112:113], v[246:247], v[88:89], v[112:113]
	v_pk_fma_f32 v[152:153], v[248:249], v[90:91], v[152:153]
	v_pk_fma_f32 v[166:167], v[250:251], v[92:93], v[166:167]
	v_pk_fma_f32 v[198:199], v[252:253], v[94:95], v[198:199]
	v_fma_f32 v114, |v112|, v183, 1.0
	v_fma_f32 v115, |v113|, v183, 1.0
	v_fma_f32 v154, |v152|, v183, 1.0
	v_fma_f32 v155, |v153|, v183, 1.0
	v_fma_f32 v168, |v166|, v183, 1.0
	v_fma_f32 v169, |v167|, v183, 1.0
	v_fma_f32 v200, |v198|, v183, 1.0
	v_fma_f32 v201, |v199|, v183, 1.0
	v_mul_f32_e32 v116, v114, v115
	v_mul_f32_e32 v156, v154, v155
	v_mul_f32_e32 v170, v168, v169
	v_mul_f32_e32 v202, v200, v201
	v_pk_mul_f32 v[118:119], v[112:113], v[112:113]
	v_pk_mul_f32 v[158:159], v[152:153], v[152:153]
	v_pk_mul_f32 v[172:173], v[166:167], v[166:167]
	v_pk_mul_f32 v[204:205], v[198:199], v[198:199]
	v_rcp_f32_e32 v116, v116
	v_rcp_f32_e32 v156, v156
	v_rcp_f32_e32 v170, v170
	v_rcp_f32_e32 v202, v202
	v_pk_mul_f32 v[118:119], v[118:119], v[126:127]
	v_pk_mul_f32 v[158:159], v[158:159], v[126:127]
	v_pk_mul_f32 v[172:173], v[172:173], v[126:127]
	v_pk_mul_f32 v[204:205], v[204:205], v[126:127]
	v_pk_mul_f32 v[114:115], v[114:115], v[116:117] op_sel:[1,0] op_sel_hi:[0,0]
	v_pk_mul_f32 v[154:155], v[154:155], v[156:157] op_sel:[1,0] op_sel_hi:[0,0]
	v_pk_mul_f32 v[168:169], v[168:169], v[170:171] op_sel:[1,0] op_sel_hi:[0,0]
	v_pk_mul_f32 v[200:201], v[200:201], v[202:203] op_sel:[1,0] op_sel_hi:[0,0]
	v_exp_f32_e32 v118, v118
	v_exp_f32_e32 v119, v119
	v_exp_f32_e32 v158, v158
	v_exp_f32_e32 v159, v159
	v_exp_f32_e32 v172, v172
	v_exp_f32_e32 v173, v173
	v_exp_f32_e32 v204, v204
	v_exp_f32_e32 v205, v205
	v_pk_fma_f32 v[120:121], v[114:115], s[74:75], v[180:181] op_sel_hi:[1,0,0]
	v_pk_fma_f32 v[160:161], v[154:155], s[74:75], v[180:181] op_sel_hi:[1,0,0]
	v_pk_fma_f32 v[174:175], v[168:169], s[74:75], v[180:181] op_sel_hi:[1,0,0]
	v_pk_fma_f32 v[206:207], v[200:201], s[74:75], v[180:181] op_sel_hi:[1,0,0]
	v_pk_fma_f32 v[120:121], v[114:115], v[120:121], s[78:79] op_sel_hi:[1,1,0]
	v_pk_fma_f32 v[160:161], v[154:155], v[160:161], s[78:79] op_sel_hi:[1,1,0]
	v_pk_fma_f32 v[174:175], v[168:169], v[174:175], s[78:79] op_sel_hi:[1,1,0]
	v_pk_fma_f32 v[206:207], v[200:201], v[206:207], s[78:79] op_sel_hi:[1,1,0]
	v_pk_fma_f32 v[120:121], v[114:115], v[120:121], s[80:81] op_sel_hi:[1,1,0]
	v_pk_fma_f32 v[160:161], v[154:155], v[160:161], s[80:81] op_sel_hi:[1,1,0]
	v_pk_fma_f32 v[174:175], v[168:169], v[174:175], s[80:81] op_sel_hi:[1,1,0]
	v_pk_fma_f32 v[206:207], v[200:201], v[206:207], s[80:81] op_sel_hi:[1,1,0]
	v_pk_fma_f32 v[120:121], v[114:115], v[120:121], s[82:83] op_sel_hi:[1,1,0]
	v_pk_fma_f32 v[160:161], v[154:155], v[160:161], s[82:83] op_sel_hi:[1,1,0]
	v_pk_fma_f32 v[174:175], v[168:169], v[174:175], s[82:83] op_sel_hi:[1,1,0]
	v_pk_fma_f32 v[206:207], v[200:201], v[206:207], s[82:83] op_sel_hi:[1,1,0]
	v_pk_mul_f32 v[120:121], v[114:115], v[120:121]
	v_pk_mul_f32 v[160:161], v[154:155], v[160:161]
	v_pk_mul_f32 v[174:175], v[168:169], v[174:175]
	v_pk_mul_f32 v[206:207], v[200:201], v[206:207]
	v_pk_fma_f32 v[118:119], v[118:119], v[120:121], 1.0 op_sel_hi:[1,1,0] neg_lo:[1,0,0] neg_hi:[1,0,0]
	v_pk_fma_f32 v[158:159], v[158:159], v[160:161], 1.0 op_sel_hi:[1,1,0] neg_lo:[1,0,0] neg_hi:[1,0,0]
	v_pk_fma_f32 v[172:173], v[172:173], v[174:175], 1.0 op_sel_hi:[1,1,0] neg_lo:[1,0,0] neg_hi:[1,0,0]
	v_pk_fma_f32 v[204:205], v[204:205], v[206:207], 1.0 op_sel_hi:[1,1,0] neg_lo:[1,0,0] neg_hi:[1,0,0]
	v_bfi_b32 v119, s34, v119, v113
	v_bfi_b32 v118, s34, v118, v112
	v_bfi_b32 v159, s34, v159, v153
	v_bfi_b32 v158, s34, v158, v152
	v_bfi_b32 v173, s34, v173, v167
	v_bfi_b32 v172, s34, v172, v166
	v_bfi_b32 v205, s34, v205, v199
	v_bfi_b32 v204, s34, v204, v198
	v_lshlrev_b32_e32 v124, 16, v60
	v_and_b32_e32 v125, 0xffff0000, v60
	v_lshlrev_b32_e32 v164, 16, v61
	v_and_b32_e32 v165, 0xffff0000, v61
	v_lshlrev_b32_e32 v178, 16, v62
	v_and_b32_e32 v179, 0xffff0000, v62
	v_lshlrev_b32_e32 v210, 16, v63
	v_and_b32_e32 v211, 0xffff0000, v63
	v_pk_fma_f32 v[112:113], v[112:113], v[118:119], v[112:113]
	v_pk_fma_f32 v[152:153], v[152:153], v[158:159], v[152:153]
	v_pk_fma_f32 v[166:167], v[166:167], v[172:173], v[166:167]
	v_pk_fma_f32 v[198:199], v[198:199], v[204:205], v[198:199]
	v_pk_mul_f32 v[112:113], v[112:113], v[124:125]
	v_pk_mul_f32 v[152:153], v[152:153], v[164:165]
	v_pk_mul_f32 v[166:167], v[166:167], v[178:179]
	v_pk_mul_f32 v[198:199], v[198:199], v[210:211]
	v_cvt_pk_bf16_f32 v224, v112, v113
	v_cvt_pk_bf16_f32 v225, v152, v153
	v_cvt_pk_bf16_f32 v226, v166, v167
	v_cvt_pk_bf16_f32 v227, v198, v199
	global_store_dwordx4 v[228:229], v[224:227], off nt
	v_lshl_add_u64 v[228:229], v[228:229], 0, s[98:99]
	v_lshlrev_b32_e32 v96, 16, v32
	v_and_b32_e32 v97, 0xffff0000, v32
	v_lshlrev_b32_e32 v98, 16, v33
	v_and_b32_e32 v99, 0xffff0000, v33
	v_lshlrev_b32_e32 v100, 16, v34
	v_and_b32_e32 v101, 0xffff0000, v34
	v_lshlrev_b32_e32 v102, 16, v35
	v_and_b32_e32 v103, 0xffff0000, v35
	v_pk_fma_f32 v[112:113], v[234:235], v[104:105], v[218:219]
	v_pk_fma_f32 v[152:153], v[236:237], v[106:107], v[220:221]
	v_pk_fma_f32 v[166:167], v[230:231], v[108:109], v[214:215]
	v_pk_fma_f32 v[198:199], v[232:233], v[110:111], v[216:217]
	v_pk_fma_f32 v[112:113], v[238:239], v[88:89], v[112:113]
	v_pk_fma_f32 v[152:153], v[240:241], v[90:91], v[152:153]
	v_pk_fma_f32 v[166:167], v[242:243], v[92:93], v[166:167]
	v_pk_fma_f32 v[198:199], v[244:245], v[94:95], v[198:199]
	v_pk_fma_f32 v[112:113], v[246:247], v[96:97], v[112:113]
	v_pk_fma_f32 v[152:153], v[248:249], v[98:99], v[152:153]
	v_pk_fma_f32 v[166:167], v[250:251], v[100:101], v[166:167]
	v_pk_fma_f32 v[198:199], v[252:253], v[102:103], v[198:199]
	v_fma_f32 v114, |v112|, v183, 1.0
	v_fma_f32 v115, |v113|, v183, 1.0
	v_fma_f32 v154, |v152|, v183, 1.0
	v_fma_f32 v155, |v153|, v183, 1.0
	v_fma_f32 v168, |v166|, v183, 1.0
	v_fma_f32 v169, |v167|, v183, 1.0
	v_fma_f32 v200, |v198|, v183, 1.0
	v_fma_f32 v201, |v199|, v183, 1.0
	v_mul_f32_e32 v116, v114, v115
	v_mul_f32_e32 v156, v154, v155
	v_mul_f32_e32 v170, v168, v169
	v_mul_f32_e32 v202, v200, v201
	v_pk_mul_f32 v[118:119], v[112:113], v[112:113]
	v_pk_mul_f32 v[158:159], v[152:153], v[152:153]
	v_pk_mul_f32 v[172:173], v[166:167], v[166:167]
	v_pk_mul_f32 v[204:205], v[198:199], v[198:199]
	v_rcp_f32_e32 v116, v116
	v_rcp_f32_e32 v156, v156
	v_rcp_f32_e32 v170, v170
	v_rcp_f32_e32 v202, v202
	v_pk_mul_f32 v[118:119], v[118:119], v[126:127]
	v_pk_mul_f32 v[158:159], v[158:159], v[126:127]
	v_pk_mul_f32 v[172:173], v[172:173], v[126:127]
	v_pk_mul_f32 v[204:205], v[204:205], v[126:127]
	v_pk_mul_f32 v[114:115], v[114:115], v[116:117] op_sel:[1,0] op_sel_hi:[0,0]
	v_pk_mul_f32 v[154:155], v[154:155], v[156:157] op_sel:[1,0] op_sel_hi:[0,0]
	v_pk_mul_f32 v[168:169], v[168:169], v[170:171] op_sel:[1,0] op_sel_hi:[0,0]
	v_pk_mul_f32 v[200:201], v[200:201], v[202:203] op_sel:[1,0] op_sel_hi:[0,0]
	v_exp_f32_e32 v118, v118
	v_exp_f32_e32 v119, v119
	v_exp_f32_e32 v158, v158
	v_exp_f32_e32 v159, v159
	v_exp_f32_e32 v172, v172
	v_exp_f32_e32 v173, v173
	v_exp_f32_e32 v204, v204
	v_exp_f32_e32 v205, v205
	v_pk_fma_f32 v[120:121], v[114:115], s[74:75], v[180:181] op_sel_hi:[1,0,0]
	v_pk_fma_f32 v[160:161], v[154:155], s[74:75], v[180:181] op_sel_hi:[1,0,0]
	v_pk_fma_f32 v[174:175], v[168:169], s[74:75], v[180:181] op_sel_hi:[1,0,0]
	v_pk_fma_f32 v[206:207], v[200:201], s[74:75], v[180:181] op_sel_hi:[1,0,0]
	v_pk_fma_f32 v[120:121], v[114:115], v[120:121], s[78:79] op_sel_hi:[1,1,0]
	v_pk_fma_f32 v[160:161], v[154:155], v[160:161], s[78:79] op_sel_hi:[1,1,0]
	v_pk_fma_f32 v[174:175], v[168:169], v[174:175], s[78:79] op_sel_hi:[1,1,0]
	v_pk_fma_f32 v[206:207], v[200:201], v[206:207], s[78:79] op_sel_hi:[1,1,0]
	v_pk_fma_f32 v[120:121], v[114:115], v[120:121], s[80:81] op_sel_hi:[1,1,0]
	v_pk_fma_f32 v[160:161], v[154:155], v[160:161], s[80:81] op_sel_hi:[1,1,0]
	v_pk_fma_f32 v[174:175], v[168:169], v[174:175], s[80:81] op_sel_hi:[1,1,0]
	v_pk_fma_f32 v[206:207], v[200:201], v[206:207], s[80:81] op_sel_hi:[1,1,0]
	v_pk_fma_f32 v[120:121], v[114:115], v[120:121], s[82:83] op_sel_hi:[1,1,0]
	v_pk_fma_f32 v[160:161], v[154:155], v[160:161], s[82:83] op_sel_hi:[1,1,0]
	v_pk_fma_f32 v[174:175], v[168:169], v[174:175], s[82:83] op_sel_hi:[1,1,0]
	v_pk_fma_f32 v[206:207], v[200:201], v[206:207], s[82:83] op_sel_hi:[1,1,0]
	v_pk_mul_f32 v[120:121], v[114:115], v[120:121]
	v_pk_mul_f32 v[160:161], v[154:155], v[160:161]
	v_pk_mul_f32 v[174:175], v[168:169], v[174:175]
	v_pk_mul_f32 v[206:207], v[200:201], v[206:207]
	v_pk_fma_f32 v[118:119], v[118:119], v[120:121], 1.0 op_sel_hi:[1,1,0] neg_lo:[1,0,0] neg_hi:[1,0,0]
	v_pk_fma_f32 v[158:159], v[158:159], v[160:161], 1.0 op_sel_hi:[1,1,0] neg_lo:[1,0,0] neg_hi:[1,0,0]
	v_pk_fma_f32 v[172:173], v[172:173], v[174:175], 1.0 op_sel_hi:[1,1,0] neg_lo:[1,0,0] neg_hi:[1,0,0]
	v_pk_fma_f32 v[204:205], v[204:205], v[206:207], 1.0 op_sel_hi:[1,1,0] neg_lo:[1,0,0] neg_hi:[1,0,0]
	v_bfi_b32 v119, s34, v119, v113
	v_bfi_b32 v118, s34, v118, v112
	v_bfi_b32 v159, s34, v159, v153
	v_bfi_b32 v158, s34, v158, v152
	v_bfi_b32 v173, s34, v173, v167
	v_bfi_b32 v172, s34, v172, v166
	v_bfi_b32 v205, s34, v205, v199
	v_bfi_b32 v204, s34, v204, v198
	v_lshlrev_b32_e32 v124, 16, v64
	v_and_b32_e32 v125, 0xffff0000, v64
	v_lshlrev_b32_e32 v164, 16, v65
	v_and_b32_e32 v165, 0xffff0000, v65
	v_lshlrev_b32_e32 v178, 16, v66
	v_and_b32_e32 v179, 0xffff0000, v66
	v_lshlrev_b32_e32 v210, 16, v67
	v_and_b32_e32 v211, 0xffff0000, v67
	v_pk_fma_f32 v[112:113], v[112:113], v[118:119], v[112:113]
	v_pk_fma_f32 v[152:153], v[152:153], v[158:159], v[152:153]
	v_pk_fma_f32 v[166:167], v[166:167], v[172:173], v[166:167]
	v_pk_fma_f32 v[198:199], v[198:199], v[204:205], v[198:199]
	v_pk_mul_f32 v[112:113], v[112:113], v[124:125]
	v_pk_mul_f32 v[152:153], v[152:153], v[164:165]
	v_pk_mul_f32 v[166:167], v[166:167], v[178:179]
	v_pk_mul_f32 v[198:199], v[198:199], v[210:211]
	v_cvt_pk_bf16_f32 v224, v112, v113
	v_cvt_pk_bf16_f32 v225, v152, v153
	v_cvt_pk_bf16_f32 v226, v166, v167
	v_cvt_pk_bf16_f32 v227, v198, v199
	global_store_dwordx4 v[228:229], v[224:227], off nt
	v_lshl_add_u64 v[228:229], v[228:229], 0, s[98:99]
	v_lshlrev_b32_e32 v104, 16, v36
	v_and_b32_e32 v105, 0xffff0000, v36
	v_lshlrev_b32_e32 v106, 16, v37
	v_and_b32_e32 v107, 0xffff0000, v37
	v_lshlrev_b32_e32 v108, 16, v38
	v_and_b32_e32 v109, 0xffff0000, v38
	v_lshlrev_b32_e32 v110, 16, v39
	v_and_b32_e32 v111, 0xffff0000, v39
	v_pk_fma_f32 v[112:113], v[234:235], v[88:89], v[218:219]
	v_pk_fma_f32 v[152:153], v[236:237], v[90:91], v[220:221]
	v_pk_fma_f32 v[166:167], v[230:231], v[92:93], v[214:215]
	v_pk_fma_f32 v[198:199], v[232:233], v[94:95], v[216:217]
	v_pk_fma_f32 v[112:113], v[238:239], v[96:97], v[112:113]
	v_pk_fma_f32 v[152:153], v[240:241], v[98:99], v[152:153]
	v_pk_fma_f32 v[166:167], v[242:243], v[100:101], v[166:167]
	v_pk_fma_f32 v[198:199], v[244:245], v[102:103], v[198:199]
	v_pk_fma_f32 v[112:113], v[246:247], v[104:105], v[112:113]
	v_pk_fma_f32 v[152:153], v[248:249], v[106:107], v[152:153]
	v_pk_fma_f32 v[166:167], v[250:251], v[108:109], v[166:167]
	v_pk_fma_f32 v[198:199], v[252:253], v[110:111], v[198:199]
	v_fma_f32 v114, |v112|, v183, 1.0
	v_fma_f32 v115, |v113|, v183, 1.0
	v_fma_f32 v154, |v152|, v183, 1.0
	v_fma_f32 v155, |v153|, v183, 1.0
	v_fma_f32 v168, |v166|, v183, 1.0
	v_fma_f32 v169, |v167|, v183, 1.0
	v_fma_f32 v200, |v198|, v183, 1.0
	v_fma_f32 v201, |v199|, v183, 1.0
	v_mul_f32_e32 v116, v114, v115
	v_mul_f32_e32 v156, v154, v155
	v_mul_f32_e32 v170, v168, v169
	v_mul_f32_e32 v202, v200, v201
	v_pk_mul_f32 v[118:119], v[112:113], v[112:113]
	v_pk_mul_f32 v[158:159], v[152:153], v[152:153]
	v_pk_mul_f32 v[172:173], v[166:167], v[166:167]
	v_pk_mul_f32 v[204:205], v[198:199], v[198:199]
	v_rcp_f32_e32 v116, v116
	v_rcp_f32_e32 v156, v156
	v_rcp_f32_e32 v170, v170
	v_rcp_f32_e32 v202, v202
	v_pk_mul_f32 v[118:119], v[118:119], v[126:127]
	v_pk_mul_f32 v[158:159], v[158:159], v[126:127]
	v_pk_mul_f32 v[172:173], v[172:173], v[126:127]
	v_pk_mul_f32 v[204:205], v[204:205], v[126:127]
	v_pk_mul_f32 v[114:115], v[114:115], v[116:117] op_sel:[1,0] op_sel_hi:[0,0]
	v_pk_mul_f32 v[154:155], v[154:155], v[156:157] op_sel:[1,0] op_sel_hi:[0,0]
	v_pk_mul_f32 v[168:169], v[168:169], v[170:171] op_sel:[1,0] op_sel_hi:[0,0]
	v_pk_mul_f32 v[200:201], v[200:201], v[202:203] op_sel:[1,0] op_sel_hi:[0,0]
	v_exp_f32_e32 v118, v118
	v_exp_f32_e32 v119, v119
	v_exp_f32_e32 v158, v158
	v_exp_f32_e32 v159, v159
	v_exp_f32_e32 v172, v172
	v_exp_f32_e32 v173, v173
	v_exp_f32_e32 v204, v204
	v_exp_f32_e32 v205, v205
	v_pk_fma_f32 v[120:121], v[114:115], s[74:75], v[180:181] op_sel_hi:[1,0,0]
	v_pk_fma_f32 v[160:161], v[154:155], s[74:75], v[180:181] op_sel_hi:[1,0,0]
	v_pk_fma_f32 v[174:175], v[168:169], s[74:75], v[180:181] op_sel_hi:[1,0,0]
	v_pk_fma_f32 v[206:207], v[200:201], s[74:75], v[180:181] op_sel_hi:[1,0,0]
	v_pk_fma_f32 v[120:121], v[114:115], v[120:121], s[78:79] op_sel_hi:[1,1,0]
	v_pk_fma_f32 v[160:161], v[154:155], v[160:161], s[78:79] op_sel_hi:[1,1,0]
	v_pk_fma_f32 v[174:175], v[168:169], v[174:175], s[78:79] op_sel_hi:[1,1,0]
	v_pk_fma_f32 v[206:207], v[200:201], v[206:207], s[78:79] op_sel_hi:[1,1,0]
	v_pk_fma_f32 v[120:121], v[114:115], v[120:121], s[80:81] op_sel_hi:[1,1,0]
	v_pk_fma_f32 v[160:161], v[154:155], v[160:161], s[80:81] op_sel_hi:[1,1,0]
	v_pk_fma_f32 v[174:175], v[168:169], v[174:175], s[80:81] op_sel_hi:[1,1,0]
	v_pk_fma_f32 v[206:207], v[200:201], v[206:207], s[80:81] op_sel_hi:[1,1,0]
	v_pk_fma_f32 v[120:121], v[114:115], v[120:121], s[82:83] op_sel_hi:[1,1,0]
	v_pk_fma_f32 v[160:161], v[154:155], v[160:161], s[82:83] op_sel_hi:[1,1,0]
	v_pk_fma_f32 v[174:175], v[168:169], v[174:175], s[82:83] op_sel_hi:[1,1,0]
	v_pk_fma_f32 v[206:207], v[200:201], v[206:207], s[82:83] op_sel_hi:[1,1,0]
	v_pk_mul_f32 v[120:121], v[114:115], v[120:121]
	v_pk_mul_f32 v[160:161], v[154:155], v[160:161]
	v_pk_mul_f32 v[174:175], v[168:169], v[174:175]
	v_pk_mul_f32 v[206:207], v[200:201], v[206:207]
	v_pk_fma_f32 v[118:119], v[118:119], v[120:121], 1.0 op_sel_hi:[1,1,0] neg_lo:[1,0,0] neg_hi:[1,0,0]
	v_pk_fma_f32 v[158:159], v[158:159], v[160:161], 1.0 op_sel_hi:[1,1,0] neg_lo:[1,0,0] neg_hi:[1,0,0]
	v_pk_fma_f32 v[172:173], v[172:173], v[174:175], 1.0 op_sel_hi:[1,1,0] neg_lo:[1,0,0] neg_hi:[1,0,0]
	v_pk_fma_f32 v[204:205], v[204:205], v[206:207], 1.0 op_sel_hi:[1,1,0] neg_lo:[1,0,0] neg_hi:[1,0,0]
	v_bfi_b32 v119, s34, v119, v113
	v_bfi_b32 v118, s34, v118, v112
	v_bfi_b32 v159, s34, v159, v153
	v_bfi_b32 v158, s34, v158, v152
	v_bfi_b32 v173, s34, v173, v167
	v_bfi_b32 v172, s34, v172, v166
	v_bfi_b32 v205, s34, v205, v199
	v_bfi_b32 v204, s34, v204, v198
	v_lshlrev_b32_e32 v124, 16, v68
	v_and_b32_e32 v125, 0xffff0000, v68
	v_lshlrev_b32_e32 v164, 16, v69
	v_and_b32_e32 v165, 0xffff0000, v69
	v_lshlrev_b32_e32 v178, 16, v70
	v_and_b32_e32 v179, 0xffff0000, v70
	v_lshlrev_b32_e32 v210, 16, v71
	v_and_b32_e32 v211, 0xffff0000, v71
	v_pk_fma_f32 v[112:113], v[112:113], v[118:119], v[112:113]
	v_pk_fma_f32 v[152:153], v[152:153], v[158:159], v[152:153]
	v_pk_fma_f32 v[166:167], v[166:167], v[172:173], v[166:167]
	v_pk_fma_f32 v[198:199], v[198:199], v[204:205], v[198:199]
	v_pk_mul_f32 v[112:113], v[112:113], v[124:125]
	v_pk_mul_f32 v[152:153], v[152:153], v[164:165]
	v_pk_mul_f32 v[166:167], v[166:167], v[178:179]
	v_pk_mul_f32 v[198:199], v[198:199], v[210:211]
	v_cvt_pk_bf16_f32 v224, v112, v113
	v_cvt_pk_bf16_f32 v225, v152, v153
	v_cvt_pk_bf16_f32 v226, v166, v167
	v_cvt_pk_bf16_f32 v227, v198, v199
	global_store_dwordx4 v[228:229], v[224:227], off nt
	v_lshl_add_u64 v[228:229], v[228:229], 0, s[98:99]
	v_lshlrev_b32_e32 v88, 16, v40
	v_and_b32_e32 v89, 0xffff0000, v40
	v_lshlrev_b32_e32 v90, 16, v41
	v_and_b32_e32 v91, 0xffff0000, v41
	v_lshlrev_b32_e32 v92, 16, v42
	v_and_b32_e32 v93, 0xffff0000, v42
	v_lshlrev_b32_e32 v94, 16, v43
	v_and_b32_e32 v95, 0xffff0000, v43
	v_pk_fma_f32 v[112:113], v[234:235], v[96:97], v[218:219]
	v_pk_fma_f32 v[152:153], v[236:237], v[98:99], v[220:221]
	v_pk_fma_f32 v[166:167], v[230:231], v[100:101], v[214:215]
	v_pk_fma_f32 v[198:199], v[232:233], v[102:103], v[216:217]
	v_pk_fma_f32 v[112:113], v[238:239], v[104:105], v[112:113]
	v_pk_fma_f32 v[152:153], v[240:241], v[106:107], v[152:153]
	v_pk_fma_f32 v[166:167], v[242:243], v[108:109], v[166:167]
	v_pk_fma_f32 v[198:199], v[244:245], v[110:111], v[198:199]
	v_pk_fma_f32 v[112:113], v[246:247], v[88:89], v[112:113]
	v_pk_fma_f32 v[152:153], v[248:249], v[90:91], v[152:153]
	v_pk_fma_f32 v[166:167], v[250:251], v[92:93], v[166:167]
	v_pk_fma_f32 v[198:199], v[252:253], v[94:95], v[198:199]
	v_fma_f32 v114, |v112|, v183, 1.0
	v_fma_f32 v115, |v113|, v183, 1.0
	v_fma_f32 v154, |v152|, v183, 1.0
	v_fma_f32 v155, |v153|, v183, 1.0
	v_fma_f32 v168, |v166|, v183, 1.0
	v_fma_f32 v169, |v167|, v183, 1.0
	v_fma_f32 v200, |v198|, v183, 1.0
	v_fma_f32 v201, |v199|, v183, 1.0
	v_mul_f32_e32 v116, v114, v115
	v_mul_f32_e32 v156, v154, v155
	v_mul_f32_e32 v170, v168, v169
	v_mul_f32_e32 v202, v200, v201
	v_pk_mul_f32 v[118:119], v[112:113], v[112:113]
	v_pk_mul_f32 v[158:159], v[152:153], v[152:153]
	v_pk_mul_f32 v[172:173], v[166:167], v[166:167]
	v_pk_mul_f32 v[204:205], v[198:199], v[198:199]
	v_rcp_f32_e32 v116, v116
	v_rcp_f32_e32 v156, v156
	v_rcp_f32_e32 v170, v170
	v_rcp_f32_e32 v202, v202
	v_pk_mul_f32 v[118:119], v[118:119], v[126:127]
	v_pk_mul_f32 v[158:159], v[158:159], v[126:127]
	v_pk_mul_f32 v[172:173], v[172:173], v[126:127]
	v_pk_mul_f32 v[204:205], v[204:205], v[126:127]
	v_pk_mul_f32 v[114:115], v[114:115], v[116:117] op_sel:[1,0] op_sel_hi:[0,0]
	v_pk_mul_f32 v[154:155], v[154:155], v[156:157] op_sel:[1,0] op_sel_hi:[0,0]
	v_pk_mul_f32 v[168:169], v[168:169], v[170:171] op_sel:[1,0] op_sel_hi:[0,0]
	v_pk_mul_f32 v[200:201], v[200:201], v[202:203] op_sel:[1,0] op_sel_hi:[0,0]
	v_exp_f32_e32 v118, v118
	v_exp_f32_e32 v119, v119
	v_exp_f32_e32 v158, v158
	v_exp_f32_e32 v159, v159
	v_exp_f32_e32 v172, v172
	v_exp_f32_e32 v173, v173
	v_exp_f32_e32 v204, v204
	v_exp_f32_e32 v205, v205
	v_pk_fma_f32 v[120:121], v[114:115], s[74:75], v[180:181] op_sel_hi:[1,0,0]
	v_pk_fma_f32 v[160:161], v[154:155], s[74:75], v[180:181] op_sel_hi:[1,0,0]
	v_pk_fma_f32 v[174:175], v[168:169], s[74:75], v[180:181] op_sel_hi:[1,0,0]
	v_pk_fma_f32 v[206:207], v[200:201], s[74:75], v[180:181] op_sel_hi:[1,0,0]
	v_pk_fma_f32 v[120:121], v[114:115], v[120:121], s[78:79] op_sel_hi:[1,1,0]
	v_pk_fma_f32 v[160:161], v[154:155], v[160:161], s[78:79] op_sel_hi:[1,1,0]
	v_pk_fma_f32 v[174:175], v[168:169], v[174:175], s[78:79] op_sel_hi:[1,1,0]
	v_pk_fma_f32 v[206:207], v[200:201], v[206:207], s[78:79] op_sel_hi:[1,1,0]
	v_pk_fma_f32 v[120:121], v[114:115], v[120:121], s[80:81] op_sel_hi:[1,1,0]
	v_pk_fma_f32 v[160:161], v[154:155], v[160:161], s[80:81] op_sel_hi:[1,1,0]
	v_pk_fma_f32 v[174:175], v[168:169], v[174:175], s[80:81] op_sel_hi:[1,1,0]
	v_pk_fma_f32 v[206:207], v[200:201], v[206:207], s[80:81] op_sel_hi:[1,1,0]
	v_pk_fma_f32 v[120:121], v[114:115], v[120:121], s[82:83] op_sel_hi:[1,1,0]
	v_pk_fma_f32 v[160:161], v[154:155], v[160:161], s[82:83] op_sel_hi:[1,1,0]
	v_pk_fma_f32 v[174:175], v[168:169], v[174:175], s[82:83] op_sel_hi:[1,1,0]
	v_pk_fma_f32 v[206:207], v[200:201], v[206:207], s[82:83] op_sel_hi:[1,1,0]
	v_pk_mul_f32 v[120:121], v[114:115], v[120:121]
	v_pk_mul_f32 v[160:161], v[154:155], v[160:161]
	v_pk_mul_f32 v[174:175], v[168:169], v[174:175]
	v_pk_mul_f32 v[206:207], v[200:201], v[206:207]
	v_pk_fma_f32 v[118:119], v[118:119], v[120:121], 1.0 op_sel_hi:[1,1,0] neg_lo:[1,0,0] neg_hi:[1,0,0]
	v_pk_fma_f32 v[158:159], v[158:159], v[160:161], 1.0 op_sel_hi:[1,1,0] neg_lo:[1,0,0] neg_hi:[1,0,0]
	v_pk_fma_f32 v[172:173], v[172:173], v[174:175], 1.0 op_sel_hi:[1,1,0] neg_lo:[1,0,0] neg_hi:[1,0,0]
	v_pk_fma_f32 v[204:205], v[204:205], v[206:207], 1.0 op_sel_hi:[1,1,0] neg_lo:[1,0,0] neg_hi:[1,0,0]
	v_bfi_b32 v119, s34, v119, v113
	v_bfi_b32 v118, s34, v118, v112
	v_bfi_b32 v159, s34, v159, v153
	v_bfi_b32 v158, s34, v158, v152
	v_bfi_b32 v173, s34, v173, v167
	v_bfi_b32 v172, s34, v172, v166
	v_bfi_b32 v205, s34, v205, v199
	v_bfi_b32 v204, s34, v204, v198
	v_lshlrev_b32_e32 v124, 16, v72
	v_and_b32_e32 v125, 0xffff0000, v72
	v_lshlrev_b32_e32 v164, 16, v73
	v_and_b32_e32 v165, 0xffff0000, v73
	v_lshlrev_b32_e32 v178, 16, v74
	v_and_b32_e32 v179, 0xffff0000, v74
	v_lshlrev_b32_e32 v210, 16, v75
	v_and_b32_e32 v211, 0xffff0000, v75
	v_pk_fma_f32 v[112:113], v[112:113], v[118:119], v[112:113]
	v_pk_fma_f32 v[152:153], v[152:153], v[158:159], v[152:153]
	v_pk_fma_f32 v[166:167], v[166:167], v[172:173], v[166:167]
	v_pk_fma_f32 v[198:199], v[198:199], v[204:205], v[198:199]
	v_pk_mul_f32 v[112:113], v[112:113], v[124:125]
	v_pk_mul_f32 v[152:153], v[152:153], v[164:165]
	v_pk_mul_f32 v[166:167], v[166:167], v[178:179]
	v_pk_mul_f32 v[198:199], v[198:199], v[210:211]
	v_cvt_pk_bf16_f32 v224, v112, v113
	v_cvt_pk_bf16_f32 v225, v152, v153
	v_cvt_pk_bf16_f32 v226, v166, v167
	v_cvt_pk_bf16_f32 v227, v198, v199
	global_store_dwordx4 v[228:229], v[224:227], off nt
	v_lshl_add_u64 v[228:229], v[228:229], 0, s[98:99]
	v_lshlrev_b32_e32 v96, 16, v44
	v_and_b32_e32 v97, 0xffff0000, v44
	v_lshlrev_b32_e32 v98, 16, v45
	v_and_b32_e32 v99, 0xffff0000, v45
	v_lshlrev_b32_e32 v100, 16, v46
	v_and_b32_e32 v101, 0xffff0000, v46
	v_lshlrev_b32_e32 v102, 16, v47
	v_and_b32_e32 v103, 0xffff0000, v47
	v_pk_fma_f32 v[112:113], v[234:235], v[104:105], v[218:219]
	v_pk_fma_f32 v[152:153], v[236:237], v[106:107], v[220:221]
	v_pk_fma_f32 v[166:167], v[230:231], v[108:109], v[214:215]
	v_pk_fma_f32 v[198:199], v[232:233], v[110:111], v[216:217]
	v_pk_fma_f32 v[112:113], v[238:239], v[88:89], v[112:113]
	v_pk_fma_f32 v[152:153], v[240:241], v[90:91], v[152:153]
	v_pk_fma_f32 v[166:167], v[242:243], v[92:93], v[166:167]
	v_pk_fma_f32 v[198:199], v[244:245], v[94:95], v[198:199]
	v_pk_fma_f32 v[112:113], v[246:247], v[96:97], v[112:113]
	v_pk_fma_f32 v[152:153], v[248:249], v[98:99], v[152:153]
	v_pk_fma_f32 v[166:167], v[250:251], v[100:101], v[166:167]
	v_pk_fma_f32 v[198:199], v[252:253], v[102:103], v[198:199]
	v_fma_f32 v114, |v112|, v183, 1.0
	v_fma_f32 v115, |v113|, v183, 1.0
	v_fma_f32 v154, |v152|, v183, 1.0
	v_fma_f32 v155, |v153|, v183, 1.0
	v_fma_f32 v168, |v166|, v183, 1.0
	v_fma_f32 v169, |v167|, v183, 1.0
	v_fma_f32 v200, |v198|, v183, 1.0
	v_fma_f32 v201, |v199|, v183, 1.0
	v_mul_f32_e32 v116, v114, v115
	v_mul_f32_e32 v156, v154, v155
	v_mul_f32_e32 v170, v168, v169
	v_mul_f32_e32 v202, v200, v201
	v_pk_mul_f32 v[118:119], v[112:113], v[112:113]
	v_pk_mul_f32 v[158:159], v[152:153], v[152:153]
	v_pk_mul_f32 v[172:173], v[166:167], v[166:167]
	v_pk_mul_f32 v[204:205], v[198:199], v[198:199]
	v_rcp_f32_e32 v116, v116
	v_rcp_f32_e32 v156, v156
	v_rcp_f32_e32 v170, v170
	v_rcp_f32_e32 v202, v202
	v_pk_mul_f32 v[118:119], v[118:119], v[126:127]
	v_pk_mul_f32 v[158:159], v[158:159], v[126:127]
	v_pk_mul_f32 v[172:173], v[172:173], v[126:127]
	v_pk_mul_f32 v[204:205], v[204:205], v[126:127]
	v_pk_mul_f32 v[114:115], v[114:115], v[116:117] op_sel:[1,0] op_sel_hi:[0,0]
	v_pk_mul_f32 v[154:155], v[154:155], v[156:157] op_sel:[1,0] op_sel_hi:[0,0]
	v_pk_mul_f32 v[168:169], v[168:169], v[170:171] op_sel:[1,0] op_sel_hi:[0,0]
	v_pk_mul_f32 v[200:201], v[200:201], v[202:203] op_sel:[1,0] op_sel_hi:[0,0]
	v_exp_f32_e32 v118, v118
	v_exp_f32_e32 v119, v119
	v_exp_f32_e32 v158, v158
	v_exp_f32_e32 v159, v159
	v_exp_f32_e32 v172, v172
	v_exp_f32_e32 v173, v173
	v_exp_f32_e32 v204, v204
	v_exp_f32_e32 v205, v205
	v_pk_fma_f32 v[120:121], v[114:115], s[74:75], v[180:181] op_sel_hi:[1,0,0]
	v_pk_fma_f32 v[160:161], v[154:155], s[74:75], v[180:181] op_sel_hi:[1,0,0]
	v_pk_fma_f32 v[174:175], v[168:169], s[74:75], v[180:181] op_sel_hi:[1,0,0]
	v_pk_fma_f32 v[206:207], v[200:201], s[74:75], v[180:181] op_sel_hi:[1,0,0]
	v_pk_fma_f32 v[120:121], v[114:115], v[120:121], s[78:79] op_sel_hi:[1,1,0]
	v_pk_fma_f32 v[160:161], v[154:155], v[160:161], s[78:79] op_sel_hi:[1,1,0]
	v_pk_fma_f32 v[174:175], v[168:169], v[174:175], s[78:79] op_sel_hi:[1,1,0]
	v_pk_fma_f32 v[206:207], v[200:201], v[206:207], s[78:79] op_sel_hi:[1,1,0]
	v_pk_fma_f32 v[120:121], v[114:115], v[120:121], s[80:81] op_sel_hi:[1,1,0]
	v_pk_fma_f32 v[160:161], v[154:155], v[160:161], s[80:81] op_sel_hi:[1,1,0]
	v_pk_fma_f32 v[174:175], v[168:169], v[174:175], s[80:81] op_sel_hi:[1,1,0]
	v_pk_fma_f32 v[206:207], v[200:201], v[206:207], s[80:81] op_sel_hi:[1,1,0]
	v_pk_fma_f32 v[120:121], v[114:115], v[120:121], s[82:83] op_sel_hi:[1,1,0]
	v_pk_fma_f32 v[160:161], v[154:155], v[160:161], s[82:83] op_sel_hi:[1,1,0]
	v_pk_fma_f32 v[174:175], v[168:169], v[174:175], s[82:83] op_sel_hi:[1,1,0]
	v_pk_fma_f32 v[206:207], v[200:201], v[206:207], s[82:83] op_sel_hi:[1,1,0]
	v_pk_mul_f32 v[120:121], v[114:115], v[120:121]
	v_pk_mul_f32 v[160:161], v[154:155], v[160:161]
	v_pk_mul_f32 v[174:175], v[168:169], v[174:175]
	v_pk_mul_f32 v[206:207], v[200:201], v[206:207]
	v_pk_fma_f32 v[118:119], v[118:119], v[120:121], 1.0 op_sel_hi:[1,1,0] neg_lo:[1,0,0] neg_hi:[1,0,0]
	v_pk_fma_f32 v[158:159], v[158:159], v[160:161], 1.0 op_sel_hi:[1,1,0] neg_lo:[1,0,0] neg_hi:[1,0,0]
	v_pk_fma_f32 v[172:173], v[172:173], v[174:175], 1.0 op_sel_hi:[1,1,0] neg_lo:[1,0,0] neg_hi:[1,0,0]
	v_pk_fma_f32 v[204:205], v[204:205], v[206:207], 1.0 op_sel_hi:[1,1,0] neg_lo:[1,0,0] neg_hi:[1,0,0]
	v_bfi_b32 v119, s34, v119, v113
	v_bfi_b32 v118, s34, v118, v112
	v_bfi_b32 v159, s34, v159, v153
	v_bfi_b32 v158, s34, v158, v152
	v_bfi_b32 v173, s34, v173, v167
	v_bfi_b32 v172, s34, v172, v166
	v_bfi_b32 v205, s34, v205, v199
	v_bfi_b32 v204, s34, v204, v198
	v_lshlrev_b32_e32 v124, 16, v76
	v_and_b32_e32 v125, 0xffff0000, v76
	v_lshlrev_b32_e32 v164, 16, v77
	v_and_b32_e32 v165, 0xffff0000, v77
	v_lshlrev_b32_e32 v178, 16, v78
	v_and_b32_e32 v179, 0xffff0000, v78
	v_lshlrev_b32_e32 v210, 16, v79
	v_and_b32_e32 v211, 0xffff0000, v79
	v_pk_fma_f32 v[112:113], v[112:113], v[118:119], v[112:113]
	v_pk_fma_f32 v[152:153], v[152:153], v[158:159], v[152:153]
	v_pk_fma_f32 v[166:167], v[166:167], v[172:173], v[166:167]
	v_pk_fma_f32 v[198:199], v[198:199], v[204:205], v[198:199]
	v_pk_mul_f32 v[112:113], v[112:113], v[124:125]
	v_pk_mul_f32 v[152:153], v[152:153], v[164:165]
	v_pk_mul_f32 v[166:167], v[166:167], v[178:179]
	v_pk_mul_f32 v[198:199], v[198:199], v[210:211]
	v_cvt_pk_bf16_f32 v224, v112, v113
	v_cvt_pk_bf16_f32 v225, v152, v153
	v_cvt_pk_bf16_f32 v226, v166, v167
	v_cvt_pk_bf16_f32 v227, v198, v199
	global_store_dwordx4 v[228:229], v[224:227], off nt
	v_lshl_add_u64 v[228:229], v[228:229], 0, s[98:99]
	v_lshlrev_b32_e32 v104, 16, v48
	v_and_b32_e32 v105, 0xffff0000, v48
	v_lshlrev_b32_e32 v106, 16, v49
	v_and_b32_e32 v107, 0xffff0000, v49
	v_lshlrev_b32_e32 v108, 16, v50
	v_and_b32_e32 v109, 0xffff0000, v50
	v_lshlrev_b32_e32 v110, 16, v51
	v_and_b32_e32 v111, 0xffff0000, v51
	v_pk_fma_f32 v[112:113], v[234:235], v[88:89], v[218:219]
	v_pk_fma_f32 v[152:153], v[236:237], v[90:91], v[220:221]
	v_pk_fma_f32 v[166:167], v[230:231], v[92:93], v[214:215]
	v_pk_fma_f32 v[198:199], v[232:233], v[94:95], v[216:217]
	v_pk_fma_f32 v[112:113], v[238:239], v[96:97], v[112:113]
	v_pk_fma_f32 v[152:153], v[240:241], v[98:99], v[152:153]
	v_pk_fma_f32 v[166:167], v[242:243], v[100:101], v[166:167]
	v_pk_fma_f32 v[198:199], v[244:245], v[102:103], v[198:199]
	v_pk_fma_f32 v[112:113], v[246:247], v[104:105], v[112:113]
	v_pk_fma_f32 v[152:153], v[248:249], v[106:107], v[152:153]
	v_pk_fma_f32 v[166:167], v[250:251], v[108:109], v[166:167]
	v_pk_fma_f32 v[198:199], v[252:253], v[110:111], v[198:199]
	v_fma_f32 v114, |v112|, v183, 1.0
	v_fma_f32 v115, |v113|, v183, 1.0
	v_fma_f32 v154, |v152|, v183, 1.0
	v_fma_f32 v155, |v153|, v183, 1.0
	v_fma_f32 v168, |v166|, v183, 1.0
	v_fma_f32 v169, |v167|, v183, 1.0
	v_fma_f32 v200, |v198|, v183, 1.0
	v_fma_f32 v201, |v199|, v183, 1.0
	v_mul_f32_e32 v116, v114, v115
	v_mul_f32_e32 v156, v154, v155
	v_mul_f32_e32 v170, v168, v169
	v_mul_f32_e32 v202, v200, v201
	v_pk_mul_f32 v[118:119], v[112:113], v[112:113]
	v_pk_mul_f32 v[158:159], v[152:153], v[152:153]
	v_pk_mul_f32 v[172:173], v[166:167], v[166:167]
	v_pk_mul_f32 v[204:205], v[198:199], v[198:199]
	v_rcp_f32_e32 v116, v116
	v_rcp_f32_e32 v156, v156
	v_rcp_f32_e32 v170, v170
	v_rcp_f32_e32 v202, v202
	v_pk_mul_f32 v[118:119], v[118:119], v[126:127]
	v_pk_mul_f32 v[158:159], v[158:159], v[126:127]
	v_pk_mul_f32 v[172:173], v[172:173], v[126:127]
	v_pk_mul_f32 v[204:205], v[204:205], v[126:127]
	v_pk_mul_f32 v[114:115], v[114:115], v[116:117] op_sel:[1,0] op_sel_hi:[0,0]
	v_pk_mul_f32 v[154:155], v[154:155], v[156:157] op_sel:[1,0] op_sel_hi:[0,0]
	v_pk_mul_f32 v[168:169], v[168:169], v[170:171] op_sel:[1,0] op_sel_hi:[0,0]
	v_pk_mul_f32 v[200:201], v[200:201], v[202:203] op_sel:[1,0] op_sel_hi:[0,0]
	v_exp_f32_e32 v118, v118
	v_exp_f32_e32 v119, v119
	v_exp_f32_e32 v158, v158
	v_exp_f32_e32 v159, v159
	v_exp_f32_e32 v172, v172
	v_exp_f32_e32 v173, v173
	v_exp_f32_e32 v204, v204
	v_exp_f32_e32 v205, v205
	v_pk_fma_f32 v[120:121], v[114:115], s[74:75], v[180:181] op_sel_hi:[1,0,0]
	v_pk_fma_f32 v[160:161], v[154:155], s[74:75], v[180:181] op_sel_hi:[1,0,0]
	v_pk_fma_f32 v[174:175], v[168:169], s[74:75], v[180:181] op_sel_hi:[1,0,0]
	v_pk_fma_f32 v[206:207], v[200:201], s[74:75], v[180:181] op_sel_hi:[1,0,0]
	v_pk_fma_f32 v[120:121], v[114:115], v[120:121], s[78:79] op_sel_hi:[1,1,0]
	v_pk_fma_f32 v[160:161], v[154:155], v[160:161], s[78:79] op_sel_hi:[1,1,0]
	v_pk_fma_f32 v[174:175], v[168:169], v[174:175], s[78:79] op_sel_hi:[1,1,0]
	v_pk_fma_f32 v[206:207], v[200:201], v[206:207], s[78:79] op_sel_hi:[1,1,0]
	v_pk_fma_f32 v[120:121], v[114:115], v[120:121], s[80:81] op_sel_hi:[1,1,0]
	v_pk_fma_f32 v[160:161], v[154:155], v[160:161], s[80:81] op_sel_hi:[1,1,0]
	v_pk_fma_f32 v[174:175], v[168:169], v[174:175], s[80:81] op_sel_hi:[1,1,0]
	v_pk_fma_f32 v[206:207], v[200:201], v[206:207], s[80:81] op_sel_hi:[1,1,0]
	v_pk_fma_f32 v[120:121], v[114:115], v[120:121], s[82:83] op_sel_hi:[1,1,0]
	v_pk_fma_f32 v[160:161], v[154:155], v[160:161], s[82:83] op_sel_hi:[1,1,0]
	v_pk_fma_f32 v[174:175], v[168:169], v[174:175], s[82:83] op_sel_hi:[1,1,0]
	v_pk_fma_f32 v[206:207], v[200:201], v[206:207], s[82:83] op_sel_hi:[1,1,0]
	v_pk_mul_f32 v[120:121], v[114:115], v[120:121]
	v_pk_mul_f32 v[160:161], v[154:155], v[160:161]
	v_pk_mul_f32 v[174:175], v[168:169], v[174:175]
	v_pk_mul_f32 v[206:207], v[200:201], v[206:207]
	v_pk_fma_f32 v[118:119], v[118:119], v[120:121], 1.0 op_sel_hi:[1,1,0] neg_lo:[1,0,0] neg_hi:[1,0,0]
	v_pk_fma_f32 v[158:159], v[158:159], v[160:161], 1.0 op_sel_hi:[1,1,0] neg_lo:[1,0,0] neg_hi:[1,0,0]
	v_pk_fma_f32 v[172:173], v[172:173], v[174:175], 1.0 op_sel_hi:[1,1,0] neg_lo:[1,0,0] neg_hi:[1,0,0]
	v_pk_fma_f32 v[204:205], v[204:205], v[206:207], 1.0 op_sel_hi:[1,1,0] neg_lo:[1,0,0] neg_hi:[1,0,0]
	v_bfi_b32 v119, s34, v119, v113
	v_bfi_b32 v118, s34, v118, v112
	v_bfi_b32 v159, s34, v159, v153
	v_bfi_b32 v158, s34, v158, v152
	v_bfi_b32 v173, s34, v173, v167
	v_bfi_b32 v172, s34, v172, v166
	v_bfi_b32 v205, s34, v205, v199
	v_bfi_b32 v204, s34, v204, v198
	v_lshlrev_b32_e32 v124, 16, v80
	v_and_b32_e32 v125, 0xffff0000, v80
	v_lshlrev_b32_e32 v164, 16, v81
	v_and_b32_e32 v165, 0xffff0000, v81
	v_lshlrev_b32_e32 v178, 16, v82
	v_and_b32_e32 v179, 0xffff0000, v82
	v_lshlrev_b32_e32 v210, 16, v83
	v_and_b32_e32 v211, 0xffff0000, v83
	v_pk_fma_f32 v[112:113], v[112:113], v[118:119], v[112:113]
	v_pk_fma_f32 v[152:153], v[152:153], v[158:159], v[152:153]
	v_pk_fma_f32 v[166:167], v[166:167], v[172:173], v[166:167]
	v_pk_fma_f32 v[198:199], v[198:199], v[204:205], v[198:199]
	v_pk_mul_f32 v[112:113], v[112:113], v[124:125]
	v_pk_mul_f32 v[152:153], v[152:153], v[164:165]
	v_pk_mul_f32 v[166:167], v[166:167], v[178:179]
	v_pk_mul_f32 v[198:199], v[198:199], v[210:211]
	v_cvt_pk_bf16_f32 v224, v112, v113
	v_cvt_pk_bf16_f32 v225, v152, v153
	v_cvt_pk_bf16_f32 v226, v166, v167
	v_cvt_pk_bf16_f32 v227, v198, v199
	global_store_dwordx4 v[228:229], v[224:227], off nt
	v_lshl_add_u64 v[228:229], v[228:229], 0, s[98:99]
	v_lshlrev_b32_e32 v88, 16, v52
	v_and_b32_e32 v89, 0xffff0000, v52
	v_lshlrev_b32_e32 v90, 16, v53
	v_and_b32_e32 v91, 0xffff0000, v53
	v_lshlrev_b32_e32 v92, 16, v54
	v_and_b32_e32 v93, 0xffff0000, v54
	v_lshlrev_b32_e32 v94, 16, v55
	v_and_b32_e32 v95, 0xffff0000, v55
	v_pk_fma_f32 v[112:113], v[234:235], v[96:97], v[218:219]
	v_pk_fma_f32 v[152:153], v[236:237], v[98:99], v[220:221]
	v_pk_fma_f32 v[166:167], v[230:231], v[100:101], v[214:215]
	v_pk_fma_f32 v[198:199], v[232:233], v[102:103], v[216:217]
	v_pk_fma_f32 v[112:113], v[238:239], v[104:105], v[112:113]
	v_pk_fma_f32 v[152:153], v[240:241], v[106:107], v[152:153]
	v_pk_fma_f32 v[166:167], v[242:243], v[108:109], v[166:167]
	v_pk_fma_f32 v[198:199], v[244:245], v[110:111], v[198:199]
	v_pk_fma_f32 v[112:113], v[246:247], v[88:89], v[112:113]
	v_pk_fma_f32 v[152:153], v[248:249], v[90:91], v[152:153]
	v_pk_fma_f32 v[166:167], v[250:251], v[92:93], v[166:167]
	v_pk_fma_f32 v[198:199], v[252:253], v[94:95], v[198:199]
	v_fma_f32 v114, |v112|, v183, 1.0
	v_fma_f32 v115, |v113|, v183, 1.0
	v_fma_f32 v154, |v152|, v183, 1.0
	v_fma_f32 v155, |v153|, v183, 1.0
	v_fma_f32 v168, |v166|, v183, 1.0
	v_fma_f32 v169, |v167|, v183, 1.0
	v_fma_f32 v200, |v198|, v183, 1.0
	v_fma_f32 v201, |v199|, v183, 1.0
	v_mul_f32_e32 v116, v114, v115
	v_mul_f32_e32 v156, v154, v155
	v_mul_f32_e32 v170, v168, v169
	v_mul_f32_e32 v202, v200, v201
	v_pk_mul_f32 v[118:119], v[112:113], v[112:113]
	v_pk_mul_f32 v[158:159], v[152:153], v[152:153]
	v_pk_mul_f32 v[172:173], v[166:167], v[166:167]
	v_pk_mul_f32 v[204:205], v[198:199], v[198:199]
	v_rcp_f32_e32 v116, v116
	v_rcp_f32_e32 v156, v156
	v_rcp_f32_e32 v170, v170
	v_rcp_f32_e32 v202, v202
	v_pk_mul_f32 v[118:119], v[118:119], v[126:127]
	v_pk_mul_f32 v[158:159], v[158:159], v[126:127]
	v_pk_mul_f32 v[172:173], v[172:173], v[126:127]
	v_pk_mul_f32 v[204:205], v[204:205], v[126:127]
	v_pk_mul_f32 v[114:115], v[114:115], v[116:117] op_sel:[1,0] op_sel_hi:[0,0]
	v_pk_mul_f32 v[154:155], v[154:155], v[156:157] op_sel:[1,0] op_sel_hi:[0,0]
	v_pk_mul_f32 v[168:169], v[168:169], v[170:171] op_sel:[1,0] op_sel_hi:[0,0]
	v_pk_mul_f32 v[200:201], v[200:201], v[202:203] op_sel:[1,0] op_sel_hi:[0,0]
	v_exp_f32_e32 v118, v118
	v_exp_f32_e32 v119, v119
	v_exp_f32_e32 v158, v158
	v_exp_f32_e32 v159, v159
	v_exp_f32_e32 v172, v172
	v_exp_f32_e32 v173, v173
	v_exp_f32_e32 v204, v204
	v_exp_f32_e32 v205, v205
	v_pk_fma_f32 v[120:121], v[114:115], s[74:75], v[180:181] op_sel_hi:[1,0,0]
	v_pk_fma_f32 v[160:161], v[154:155], s[74:75], v[180:181] op_sel_hi:[1,0,0]
	v_pk_fma_f32 v[174:175], v[168:169], s[74:75], v[180:181] op_sel_hi:[1,0,0]
	v_pk_fma_f32 v[206:207], v[200:201], s[74:75], v[180:181] op_sel_hi:[1,0,0]
	v_pk_fma_f32 v[120:121], v[114:115], v[120:121], s[78:79] op_sel_hi:[1,1,0]
	v_pk_fma_f32 v[160:161], v[154:155], v[160:161], s[78:79] op_sel_hi:[1,1,0]
	v_pk_fma_f32 v[174:175], v[168:169], v[174:175], s[78:79] op_sel_hi:[1,1,0]
	v_pk_fma_f32 v[206:207], v[200:201], v[206:207], s[78:79] op_sel_hi:[1,1,0]
	v_pk_fma_f32 v[120:121], v[114:115], v[120:121], s[80:81] op_sel_hi:[1,1,0]
	v_pk_fma_f32 v[160:161], v[154:155], v[160:161], s[80:81] op_sel_hi:[1,1,0]
	v_pk_fma_f32 v[174:175], v[168:169], v[174:175], s[80:81] op_sel_hi:[1,1,0]
	v_pk_fma_f32 v[206:207], v[200:201], v[206:207], s[80:81] op_sel_hi:[1,1,0]
	v_pk_fma_f32 v[120:121], v[114:115], v[120:121], s[82:83] op_sel_hi:[1,1,0]
	v_pk_fma_f32 v[160:161], v[154:155], v[160:161], s[82:83] op_sel_hi:[1,1,0]
	v_pk_fma_f32 v[174:175], v[168:169], v[174:175], s[82:83] op_sel_hi:[1,1,0]
	v_pk_fma_f32 v[206:207], v[200:201], v[206:207], s[82:83] op_sel_hi:[1,1,0]
	v_pk_mul_f32 v[120:121], v[114:115], v[120:121]
	v_pk_mul_f32 v[160:161], v[154:155], v[160:161]
	v_pk_mul_f32 v[174:175], v[168:169], v[174:175]
	v_pk_mul_f32 v[206:207], v[200:201], v[206:207]
	v_pk_fma_f32 v[118:119], v[118:119], v[120:121], 1.0 op_sel_hi:[1,1,0] neg_lo:[1,0,0] neg_hi:[1,0,0]
	v_pk_fma_f32 v[158:159], v[158:159], v[160:161], 1.0 op_sel_hi:[1,1,0] neg_lo:[1,0,0] neg_hi:[1,0,0]
	v_pk_fma_f32 v[172:173], v[172:173], v[174:175], 1.0 op_sel_hi:[1,1,0] neg_lo:[1,0,0] neg_hi:[1,0,0]
	v_pk_fma_f32 v[204:205], v[204:205], v[206:207], 1.0 op_sel_hi:[1,1,0] neg_lo:[1,0,0] neg_hi:[1,0,0]
	v_bfi_b32 v119, s34, v119, v113
	v_bfi_b32 v118, s34, v118, v112
	v_bfi_b32 v159, s34, v159, v153
	v_bfi_b32 v158, s34, v158, v152
	v_bfi_b32 v173, s34, v173, v167
	v_bfi_b32 v172, s34, v172, v166
	v_bfi_b32 v205, s34, v205, v199
	v_bfi_b32 v204, s34, v204, v198
	v_lshlrev_b32_e32 v124, 16, v84
	v_and_b32_e32 v125, 0xffff0000, v84
	v_lshlrev_b32_e32 v164, 16, v85
	v_and_b32_e32 v165, 0xffff0000, v85
	v_lshlrev_b32_e32 v178, 16, v86
	v_and_b32_e32 v179, 0xffff0000, v86
	v_lshlrev_b32_e32 v210, 16, v87
	v_and_b32_e32 v211, 0xffff0000, v87
	v_pk_fma_f32 v[112:113], v[112:113], v[118:119], v[112:113]
	v_pk_fma_f32 v[152:153], v[152:153], v[158:159], v[152:153]
	v_pk_fma_f32 v[166:167], v[166:167], v[172:173], v[166:167]
	v_pk_fma_f32 v[198:199], v[198:199], v[204:205], v[198:199]
	v_pk_mul_f32 v[112:113], v[112:113], v[124:125]
	v_pk_mul_f32 v[152:153], v[152:153], v[164:165]
	v_pk_mul_f32 v[166:167], v[166:167], v[178:179]
	v_pk_mul_f32 v[198:199], v[198:199], v[210:211]
	v_cvt_pk_bf16_f32 v224, v112, v113
	v_cvt_pk_bf16_f32 v225, v152, v153
	v_cvt_pk_bf16_f32 v226, v166, v167
	v_cvt_pk_bf16_f32 v227, v198, v199
	v_cmp_ne_u32_e32 vcc, 31, v212
	s_and_saveexec_b64 s[100:101], vcc
	global_store_dwordx4 v[228:229], v[224:227], off nt
	s_mov_b64 exec, s[100:101]
	s_bitcmp1_b32 s32, 2
	s_mov_b32 s32, 0
	s_cbranch_scc0 .Lup_rows_ret1
	s_branch .Lup_rows_ret2
.Lup_rows_b:
	s_mov_b32 s98, 0x1600
	s_mov_b32 s99, 0
	s_waitcnt lgkmcnt(0)
	v_lshlrev_b32_e32 v88, 16, v16
	v_and_b32_e32 v89, 0xffff0000, v16
	v_lshlrev_b32_e32 v90, 16, v17
	v_and_b32_e32 v91, 0xffff0000, v17
	v_lshlrev_b32_e32 v92, 16, v18
	v_and_b32_e32 v93, 0xffff0000, v18
	v_lshlrev_b32_e32 v94, 16, v19
	v_and_b32_e32 v95, 0xffff0000, v19
	v_lshlrev_b32_e32 v96, 16, v20
	v_and_b32_e32 v97, 0xffff0000, v20
	v_lshlrev_b32_e32 v98, 16, v21
	v_and_b32_e32 v99, 0xffff0000, v21
	v_lshlrev_b32_e32 v100, 16, v22
	v_and_b32_e32 v101, 0xffff0000, v22
	v_lshlrev_b32_e32 v102, 16, v23
	v_and_b32_e32 v103, 0xffff0000, v23
	v_lshlrev_b32_e32 v104, 16, v24
	v_and_b32_e32 v105, 0xffff0000, v24
	v_lshlrev_b32_e32 v106, 16, v25
	v_and_b32_e32 v107, 0xffff0000, v25
	v_lshlrev_b32_e32 v108, 16, v26
	v_and_b32_e32 v109, 0xffff0000, v26
	v_lshlrev_b32_e32 v110, 16, v27
	v_and_b32_e32 v111, 0xffff0000, v27
	v_pk_fma_f32 v[112:113], v[234:235], v[88:89], v[218:219]
	v_pk_fma_f32 v[152:153], v[236:237], v[90:91], v[220:221]
	v_pk_fma_f32 v[166:167], v[230:231], v[92:93], v[214:215]
	v_pk_fma_f32 v[198:199], v[232:233], v[94:95], v[216:217]
	v_pk_fma_f32 v[112:113], v[238:239], v[96:97], v[112:113]
	v_pk_fma_f32 v[152:153], v[240:241], v[98:99], v[152:153]
	v_pk_fma_f32 v[166:167], v[242:243], v[100:101], v[166:167]
	v_pk_fma_f32 v[198:199], v[244:245], v[102:103], v[198:199]
	v_pk_fma_f32 v[112:113], v[246:247], v[104:105], v[112:113]
	v_pk_fma_f32 v[152:153], v[248:249], v[106:107], v[152:153]
	v_pk_fma_f32 v[166:167], v[250:251], v[108:109], v[166:167]
	v_pk_fma_f32 v[198:199], v[252:253], v[110:111], v[198:199]
	v_add_u32_e32 v13, 0, v14
	v_and_b32_e32 v13, 0xfff, v13
	v_cmp_eq_u32_e32 vcc, 0, v13
	s_and_saveexec_b64 s[100:101], vcc
	s_cbranch_execz .Lup_b0_nolo
	v_pk_fma_f32 v[112:113], v[238:239], v[96:97], v[218:219]
	v_pk_fma_f32 v[152:153], v[240:241], v[98:99], v[220:221]
	v_pk_fma_f32 v[166:167], v[242:243], v[100:101], v[214:215]
	v_pk_fma_f32 v[198:199], v[244:245], v[102:103], v[216:217]
	v_pk_fma_f32 v[112:113], v[246:247], v[104:105], v[112:113]
	v_pk_fma_f32 v[152:153], v[248:249], v[106:107], v[152:153]
	v_pk_fma_f32 v[166:167], v[250:251], v[108:109], v[166:167]
	v_pk_fma_f32 v[198:199], v[252:253], v[110:111], v[198:199]
.Lup_b0_nolo:
	s_mov_b64 exec, s[100:101]
	v_cmp_eq_u32_e32 vcc, 0xfff, v13
	s_and_saveexec_b64 s[100:101], vcc
	s_cbranch_execz .Lup_b0_nohi
	v_pk_fma_f32 v[112:113], v[234:235], v[88:89], v[218:219]
	v_pk_fma_f32 v[152:153], v[236:237], v[90:91], v[220:221]
	v_pk_fma_f32 v[166:167], v[230:231], v[92:93], v[214:215]
	v_pk_fma_f32 v[198:199], v[232:233], v[94:95], v[216:217]
	v_pk_fma_f32 v[112:113], v[238:239], v[96:97], v[112:113]
	v_pk_fma_f32 v[152:153], v[240:241], v[98:99], v[152:153]
	v_pk_fma_f32 v[166:167], v[242:243], v[100:101], v[166:167]
	v_pk_fma_f32 v[198:199], v[244:245], v[102:103], v[198:199]
.Lup_b0_nohi:
	s_mov_b64 exec, s[100:101]
	v_fma_f32 v114, |v112|, v183, 1.0
	v_fma_f32 v115, |v113|, v183, 1.0
	v_fma_f32 v154, |v152|, v183, 1.0
	v_fma_f32 v155, |v153|, v183, 1.0
	v_fma_f32 v168, |v166|, v183, 1.0
	v_fma_f32 v169, |v167|, v183, 1.0
	v_fma_f32 v200, |v198|, v183, 1.0
	v_fma_f32 v201, |v199|, v183, 1.0
	v_mul_f32_e32 v116, v114, v115
	v_mul_f32_e32 v156, v154, v155
	v_mul_f32_e32 v170, v168, v169
	v_mul_f32_e32 v202, v200, v201
	v_pk_mul_f32 v[118:119], v[112:113], v[112:113]
	v_pk_mul_f32 v[158:159], v[152:153], v[152:153]
	v_pk_mul_f32 v[172:173], v[166:167], v[166:167]
	v_pk_mul_f32 v[204:205], v[198:199], v[198:199]
	v_rcp_f32_e32 v116, v116
	v_rcp_f32_e32 v156, v156
	v_rcp_f32_e32 v170, v170
	v_rcp_f32_e32 v202, v202
	v_pk_mul_f32 v[118:119], v[118:119], v[126:127]
	v_pk_mul_f32 v[158:159], v[158:159], v[126:127]
	v_pk_mul_f32 v[172:173], v[172:173], v[126:127]
	v_pk_mul_f32 v[204:205], v[204:205], v[126:127]
	v_pk_mul_f32 v[114:115], v[114:115], v[116:117] op_sel:[1,0] op_sel_hi:[0,0]
	v_pk_mul_f32 v[154:155], v[154:155], v[156:157] op_sel:[1,0] op_sel_hi:[0,0]
	v_pk_mul_f32 v[168:169], v[168:169], v[170:171] op_sel:[1,0] op_sel_hi:[0,0]
	v_pk_mul_f32 v[200:201], v[200:201], v[202:203] op_sel:[1,0] op_sel_hi:[0,0]
	v_exp_f32_e32 v118, v118
	v_exp_f32_e32 v119, v119
	v_exp_f32_e32 v158, v158
	v_exp_f32_e32 v159, v159
	v_exp_f32_e32 v172, v172
	v_exp_f32_e32 v173, v173
	v_exp_f32_e32 v204, v204
	v_exp_f32_e32 v205, v205
	v_pk_fma_f32 v[120:121], v[114:115], s[74:75], v[180:181] op_sel_hi:[1,0,0]
	v_pk_fma_f32 v[160:161], v[154:155], s[74:75], v[180:181] op_sel_hi:[1,0,0]
	v_pk_fma_f32 v[174:175], v[168:169], s[74:75], v[180:181] op_sel_hi:[1,0,0]
	v_pk_fma_f32 v[206:207], v[200:201], s[74:75], v[180:181] op_sel_hi:[1,0,0]
	v_pk_fma_f32 v[120:121], v[114:115], v[120:121], s[78:79] op_sel_hi:[1,1,0]
	v_pk_fma_f32 v[160:161], v[154:155], v[160:161], s[78:79] op_sel_hi:[1,1,0]
	v_pk_fma_f32 v[174:175], v[168:169], v[174:175], s[78:79] op_sel_hi:[1,1,0]
	v_pk_fma_f32 v[206:207], v[200:201], v[206:207], s[78:79] op_sel_hi:[1,1,0]
	v_pk_fma_f32 v[120:121], v[114:115], v[120:121], s[80:81] op_sel_hi:[1,1,0]
	v_pk_fma_f32 v[160:161], v[154:155], v[160:161], s[80:81] op_sel_hi:[1,1,0]
	v_pk_fma_f32 v[174:175], v[168:169], v[174:175], s[80:81] op_sel_hi:[1,1,0]
	v_pk_fma_f32 v[206:207], v[200:201], v[206:207], s[80:81] op_sel_hi:[1,1,0]
	v_pk_fma_f32 v[120:121], v[114:115], v[120:121], s[82:83] op_sel_hi:[1,1,0]
	v_pk_fma_f32 v[160:161], v[154:155], v[160:161], s[82:83] op_sel_hi:[1,1,0]
	v_pk_fma_f32 v[174:175], v[168:169], v[174:175], s[82:83] op_sel_hi:[1,1,0]
	v_pk_fma_f32 v[206:207], v[200:201], v[206:207], s[82:83] op_sel_hi:[1,1,0]
	v_pk_mul_f32 v[120:121], v[114:115], v[120:121]
	v_pk_mul_f32 v[160:161], v[154:155], v[160:161]
	v_pk_mul_f32 v[174:175], v[168:169], v[174:175]
	v_pk_mul_f32 v[206:207], v[200:201], v[206:207]
	v_pk_fma_f32 v[118:119], v[118:119], v[120:121], 1.0 op_sel_hi:[1,1,0] neg_lo:[1,0,0] neg_hi:[1,0,0]
	v_pk_fma_f32 v[158:159], v[158:159], v[160:161], 1.0 op_sel_hi:[1,1,0] neg_lo:[1,0,0] neg_hi:[1,0,0]
	v_pk_fma_f32 v[172:173], v[172:173], v[174:175], 1.0 op_sel_hi:[1,1,0] neg_lo:[1,0,0] neg_hi:[1,0,0]
	v_pk_fma_f32 v[204:205], v[204:205], v[206:207], 1.0 op_sel_hi:[1,1,0] neg_lo:[1,0,0] neg_hi:[1,0,0]
	v_bfi_b32 v119, s34, v119, v113
	v_bfi_b32 v118, s34, v118, v112
	v_bfi_b32 v159, s34, v159, v153
	v_bfi_b32 v158, s34, v158, v152
	v_bfi_b32 v173, s34, v173, v167
	v_bfi_b32 v172, s34, v172, v166
	v_bfi_b32 v205, s34, v205, v199
	v_bfi_b32 v204, s34, v204, v198
	v_lshlrev_b32_e32 v124, 16, v56
	v_and_b32_e32 v125, 0xffff0000, v56
	v_lshlrev_b32_e32 v164, 16, v57
	v_and_b32_e32 v165, 0xffff0000, v57
	v_lshlrev_b32_e32 v178, 16, v58
	v_and_b32_e32 v179, 0xffff0000, v58
	v_lshlrev_b32_e32 v210, 16, v59
	v_and_b32_e32 v211, 0xffff0000, v59
	v_pk_fma_f32 v[112:113], v[112:113], v[118:119], v[112:113]
	v_pk_fma_f32 v[152:153], v[152:153], v[158:159], v[152:153]
	v_pk_fma_f32 v[166:167], v[166:167], v[172:173], v[166:167]
	v_pk_fma_f32 v[198:199], v[198:199], v[204:205], v[198:199]
	v_pk_mul_f32 v[112:113], v[112:113], v[124:125]
	v_pk_mul_f32 v[152:153], v[152:153], v[164:165]
	v_pk_mul_f32 v[166:167], v[166:167], v[178:179]
	v_pk_mul_f32 v[198:199], v[198:199], v[210:211]
	v_cvt_pk_bf16_f32 v224, v112, v113
	v_cvt_pk_bf16_f32 v225, v152, v153
	v_cvt_pk_bf16_f32 v226, v166, v167
	v_cvt_pk_bf16_f32 v227, v198, v199
	v_cmp_ne_u32_e32 vcc, 0, v212
	s_and_saveexec_b64 s[100:101], vcc
	global_store_dwordx4 v[228:229], v[224:227], off nt
	s_mov_b64 exec, s[100:101]
	v_lshl_add_u64 v[228:229], v[228:229], 0, s[98:99]
	v_lshlrev_b32_e32 v88, 16, v28
	v_and_b32_e32 v89, 0xffff0000, v28
	v_lshlrev_b32_e32 v90, 16, v29
	v_and_b32_e32 v91, 0xffff0000, v29
	v_lshlrev_b32_e32 v92, 16, v30
	v_and_b32_e32 v93, 0xffff0000, v30
	v_lshlrev_b32_e32 v94, 16, v31
	v_and_b32_e32 v95, 0xffff0000, v31
	v_pk_fma_f32 v[112:113], v[234:235], v[96:97], v[218:219]
	v_pk_fma_f32 v[152:153], v[236:237], v[98:99], v[220:221]
	v_pk_fma_f32 v[166:167], v[230:231], v[100:101], v[214:215]
	v_pk_fma_f32 v[198:199], v[232:233], v[102:103], v[216:217]
	v_pk_fma_f32 v[112:113], v[238:239], v[104:105], v[112:113]
	v_pk_fma_f32 v[152:153], v[240:241], v[106:107], v[152:153]
	v_pk_fma_f32 v[166:167], v[242:243], v[108:109], v[166:167]
	v_pk_fma_f32 v[198:199], v[244:245], v[110:111], v[198:199]
	v_pk_fma_f32 v[112:113], v[246:247], v[88:89], v[112:113]
	v_pk_fma_f32 v[152:153], v[248:249], v[90:91], v[152:153]
	v_pk_fma_f32 v[166:167], v[250:251], v[92:93], v[166:167]
	v_pk_fma_f32 v[198:199], v[252:253], v[94:95], v[198:199]
	v_add_u32_e32 v13, 1, v14
	v_and_b32_e32 v13, 0xfff, v13
	v_cmp_eq_u32_e32 vcc, 0, v13
	s_and_saveexec_b64 s[100:101], vcc
	s_cbranch_execz .Lup_b1_nolo
	v_pk_fma_f32 v[112:113], v[238:239], v[104:105], v[218:219]
	v_pk_fma_f32 v[152:153], v[240:241], v[106:107], v[220:221]
	v_pk_fma_f32 v[166:167], v[242:243], v[108:109], v[214:215]
	v_pk_fma_f32 v[198:199], v[244:245], v[110:111], v[216:217]
	v_pk_fma_f32 v[112:113], v[246:247], v[88:89], v[112:113]
	v_pk_fma_f32 v[152:153], v[248:249], v[90:91], v[152:153]
	v_pk_fma_f32 v[166:167], v[250:251], v[92:93], v[166:167]
	v_pk_fma_f32 v[198:199], v[252:253], v[94:95], v[198:199]
.Lup_b1_nolo:
	s_mov_b64 exec, s[100:101]
	v_cmp_eq_u32_e32 vcc, 0xfff, v13
	s_and_saveexec_b64 s[100:101], vcc
	s_cbranch_execz .Lup_b1_nohi
	v_pk_fma_f32 v[112:113], v[234:235], v[96:97], v[218:219]
	v_pk_fma_f32 v[152:153], v[236:237], v[98:99], v[220:221]
	v_pk_fma_f32 v[166:167], v[230:231], v[100:101], v[214:215]
	v_pk_fma_f32 v[198:199], v[232:233], v[102:103], v[216:217]
	v_pk_fma_f32 v[112:113], v[238:239], v[104:105], v[112:113]
	v_pk_fma_f32 v[152:153], v[240:241], v[106:107], v[152:153]
	v_pk_fma_f32 v[166:167], v[242:243], v[108:109], v[166:167]
	v_pk_fma_f32 v[198:199], v[244:245], v[110:111], v[198:199]
.Lup_b1_nohi:
	s_mov_b64 exec, s[100:101]
	v_fma_f32 v114, |v112|, v183, 1.0
	v_fma_f32 v115, |v113|, v183, 1.0
	v_fma_f32 v154, |v152|, v183, 1.0
	v_fma_f32 v155, |v153|, v183, 1.0
	v_fma_f32 v168, |v166|, v183, 1.0
	v_fma_f32 v169, |v167|, v183, 1.0
	v_fma_f32 v200, |v198|, v183, 1.0
	v_fma_f32 v201, |v199|, v183, 1.0
	v_mul_f32_e32 v116, v114, v115
	v_mul_f32_e32 v156, v154, v155
	v_mul_f32_e32 v170, v168, v169
	v_mul_f32_e32 v202, v200, v201
	v_pk_mul_f32 v[118:119], v[112:113], v[112:113]
	v_pk_mul_f32 v[158:159], v[152:153], v[152:153]
	v_pk_mul_f32 v[172:173], v[166:167], v[166:167]
	v_pk_mul_f32 v[204:205], v[198:199], v[198:199]
	v_rcp_f32_e32 v116, v116
	v_rcp_f32_e32 v156, v156
	v_rcp_f32_e32 v170, v170
	v_rcp_f32_e32 v202, v202
	v_pk_mul_f32 v[118:119], v[118:119], v[126:127]
	v_pk_mul_f32 v[158:159], v[158:159], v[126:127]
	v_pk_mul_f32 v[172:173], v[172:173], v[126:127]
	v_pk_mul_f32 v[204:205], v[204:205], v[126:127]
	v_pk_mul_f32 v[114:115], v[114:115], v[116:117] op_sel:[1,0] op_sel_hi:[0,0]
	v_pk_mul_f32 v[154:155], v[154:155], v[156:157] op_sel:[1,0] op_sel_hi:[0,0]
	v_pk_mul_f32 v[168:169], v[168:169], v[170:171] op_sel:[1,0] op_sel_hi:[0,0]
	v_pk_mul_f32 v[200:201], v[200:201], v[202:203] op_sel:[1,0] op_sel_hi:[0,0]
	v_exp_f32_e32 v118, v118
	v_exp_f32_e32 v119, v119
	v_exp_f32_e32 v158, v158
	v_exp_f32_e32 v159, v159
	v_exp_f32_e32 v172, v172
	v_exp_f32_e32 v173, v173
	v_exp_f32_e32 v204, v204
	v_exp_f32_e32 v205, v205
	v_pk_fma_f32 v[120:121], v[114:115], s[74:75], v[180:181] op_sel_hi:[1,0,0]
	v_pk_fma_f32 v[160:161], v[154:155], s[74:75], v[180:181] op_sel_hi:[1,0,0]
	v_pk_fma_f32 v[174:175], v[168:169], s[74:75], v[180:181] op_sel_hi:[1,0,0]
	v_pk_fma_f32 v[206:207], v[200:201], s[74:75], v[180:181] op_sel_hi:[1,0,0]
	v_pk_fma_f32 v[120:121], v[114:115], v[120:121], s[78:79] op_sel_hi:[1,1,0]
	v_pk_fma_f32 v[160:161], v[154:155], v[160:161], s[78:79] op_sel_hi:[1,1,0]
	v_pk_fma_f32 v[174:175], v[168:169], v[174:175], s[78:79] op_sel_hi:[1,1,0]
	v_pk_fma_f32 v[206:207], v[200:201], v[206:207], s[78:79] op_sel_hi:[1,1,0]
	v_pk_fma_f32 v[120:121], v[114:115], v[120:121], s[80:81] op_sel_hi:[1,1,0]
	v_pk_fma_f32 v[160:161], v[154:155], v[160:161], s[80:81] op_sel_hi:[1,1,0]
	v_pk_fma_f32 v[174:175], v[168:169], v[174:175], s[80:81] op_sel_hi:[1,1,0]
	v_pk_fma_f32 v[206:207], v[200:201], v[206:207], s[80:81] op_sel_hi:[1,1,0]
	v_pk_fma_f32 v[120:121], v[114:115], v[120:121], s[82:83] op_sel_hi:[1,1,0]
	v_pk_fma_f32 v[160:161], v[154:155], v[160:161], s[82:83] op_sel_hi:[1,1,0]
	v_pk_fma_f32 v[174:175], v[168:169], v[174:175], s[82:83] op_sel_hi:[1,1,0]
	v_pk_fma_f32 v[206:207], v[200:201], v[206:207], s[82:83] op_sel_hi:[1,1,0]
	v_pk_mul_f32 v[120:121], v[114:115], v[120:121]
	v_pk_mul_f32 v[160:161], v[154:155], v[160:161]
	v_pk_mul_f32 v[174:175], v[168:169], v[174:175]
	v_pk_mul_f32 v[206:207], v[200:201], v[206:207]
	v_pk_fma_f32 v[118:119], v[118:119], v[120:121], 1.0 op_sel_hi:[1,1,0] neg_lo:[1,0,0] neg_hi:[1,0,0]
	v_pk_fma_f32 v[158:159], v[158:159], v[160:161], 1.0 op_sel_hi:[1,1,0] neg_lo:[1,0,0] neg_hi:[1,0,0]
	v_pk_fma_f32 v[172:173], v[172:173], v[174:175], 1.0 op_sel_hi:[1,1,0] neg_lo:[1,0,0] neg_hi:[1,0,0]
	v_pk_fma_f32 v[204:205], v[204:205], v[206:207], 1.0 op_sel_hi:[1,1,0] neg_lo:[1,0,0] neg_hi:[1,0,0]
	v_bfi_b32 v119, s34, v119, v113
	v_bfi_b32 v118, s34, v118, v112
	v_bfi_b32 v159, s34, v159, v153
	v_bfi_b32 v158, s34, v158, v152
	v_bfi_b32 v173, s34, v173, v167
	v_bfi_b32 v172, s34, v172, v166
	v_bfi_b32 v205, s34, v205, v199
	v_bfi_b32 v204, s34, v204, v198
	v_lshlrev_b32_e32 v124, 16, v60
	v_and_b32_e32 v125, 0xffff0000, v60
	v_lshlrev_b32_e32 v164, 16, v61
	v_and_b32_e32 v165, 0xffff0000, v61
	v_lshlrev_b32_e32 v178, 16, v62
	v_and_b32_e32 v179, 0xffff0000, v62
	v_lshlrev_b32_e32 v210, 16, v63
	v_and_b32_e32 v211, 0xffff0000, v63
	v_pk_fma_f32 v[112:113], v[112:113], v[118:119], v[112:113]
	v_pk_fma_f32 v[152:153], v[152:153], v[158:159], v[152:153]
	v_pk_fma_f32 v[166:167], v[166:167], v[172:173], v[166:167]
	v_pk_fma_f32 v[198:199], v[198:199], v[204:205], v[198:199]
	v_pk_mul_f32 v[112:113], v[112:113], v[124:125]
	v_pk_mul_f32 v[152:153], v[152:153], v[164:165]
	v_pk_mul_f32 v[166:167], v[166:167], v[178:179]
	v_pk_mul_f32 v[198:199], v[198:199], v[210:211]
	v_cvt_pk_bf16_f32 v224, v112, v113
	v_cvt_pk_bf16_f32 v225, v152, v153
	v_cvt_pk_bf16_f32 v226, v166, v167
	v_cvt_pk_bf16_f32 v227, v198, v199
	global_store_dwordx4 v[228:229], v[224:227], off nt
	v_lshl_add_u64 v[228:229], v[228:229], 0, s[98:99]
	v_lshlrev_b32_e32 v96, 16, v32
	v_and_b32_e32 v97, 0xffff0000, v32
	v_lshlrev_b32_e32 v98, 16, v33
	v_and_b32_e32 v99, 0xffff0000, v33
	v_lshlrev_b32_e32 v100, 16, v34
	v_and_b32_e32 v101, 0xffff0000, v34
	v_lshlrev_b32_e32 v102, 16, v35
	v_and_b32_e32 v103, 0xffff0000, v35
	v_pk_fma_f32 v[112:113], v[234:235], v[104:105], v[218:219]
	v_pk_fma_f32 v[152:153], v[236:237], v[106:107], v[220:221]
	v_pk_fma_f32 v[166:167], v[230:231], v[108:109], v[214:215]
	v_pk_fma_f32 v[198:199], v[232:233], v[110:111], v[216:217]
	v_pk_fma_f32 v[112:113], v[238:239], v[88:89], v[112:113]
	v_pk_fma_f32 v[152:153], v[240:241], v[90:91], v[152:153]
	v_pk_fma_f32 v[166:167], v[242:243], v[92:93], v[166:167]
	v_pk_fma_f32 v[198:199], v[244:245], v[94:95], v[198:199]
	v_pk_fma_f32 v[112:113], v[246:247], v[96:97], v[112:113]
	v_pk_fma_f32 v[152:153], v[248:249], v[98:99], v[152:153]
	v_pk_fma_f32 v[166:167], v[250:251], v[100:101], v[166:167]
	v_pk_fma_f32 v[198:199], v[252:253], v[102:103], v[198:199]
	v_add_u32_e32 v13, 2, v14
	v_and_b32_e32 v13, 0xfff, v13
	v_cmp_eq_u32_e32 vcc, 0, v13
	s_and_saveexec_b64 s[100:101], vcc
	s_cbranch_execz .Lup_b2_nolo
	v_pk_fma_f32 v[112:113], v[238:239], v[88:89], v[218:219]
	v_pk_fma_f32 v[152:153], v[240:241], v[90:91], v[220:221]
	v_pk_fma_f32 v[166:167], v[242:243], v[92:93], v[214:215]
	v_pk_fma_f32 v[198:199], v[244:245], v[94:95], v[216:217]
	v_pk_fma_f32 v[112:113], v[246:247], v[96:97], v[112:113]
	v_pk_fma_f32 v[152:153], v[248:249], v[98:99], v[152:153]
	v_pk_fma_f32 v[166:167], v[250:251], v[100:101], v[166:167]
	v_pk_fma_f32 v[198:199], v[252:253], v[102:103], v[198:199]
.Lup_b2_nolo:
	s_mov_b64 exec, s[100:101]
	v_cmp_eq_u32_e32 vcc, 0xfff, v13
	s_and_saveexec_b64 s[100:101], vcc
	s_cbranch_execz .Lup_b2_nohi
	v_pk_fma_f32 v[112:113], v[234:235], v[104:105], v[218:219]
	v_pk_fma_f32 v[152:153], v[236:237], v[106:107], v[220:221]
	v_pk_fma_f32 v[166:167], v[230:231], v[108:109], v[214:215]
	v_pk_fma_f32 v[198:199], v[232:233], v[110:111], v[216:217]
	v_pk_fma_f32 v[112:113], v[238:239], v[88:89], v[112:113]
	v_pk_fma_f32 v[152:153], v[240:241], v[90:91], v[152:153]
	v_pk_fma_f32 v[166:167], v[242:243], v[92:93], v[166:167]
	v_pk_fma_f32 v[198:199], v[244:245], v[94:95], v[198:199]
.Lup_b2_nohi:
	s_mov_b64 exec, s[100:101]
	v_fma_f32 v114, |v112|, v183, 1.0
	v_fma_f32 v115, |v113|, v183, 1.0
	v_fma_f32 v154, |v152|, v183, 1.0
	v_fma_f32 v155, |v153|, v183, 1.0
	v_fma_f32 v168, |v166|, v183, 1.0
	v_fma_f32 v169, |v167|, v183, 1.0
	v_fma_f32 v200, |v198|, v183, 1.0
	v_fma_f32 v201, |v199|, v183, 1.0
	v_mul_f32_e32 v116, v114, v115
	v_mul_f32_e32 v156, v154, v155
	v_mul_f32_e32 v170, v168, v169
	v_mul_f32_e32 v202, v200, v201
	v_pk_mul_f32 v[118:119], v[112:113], v[112:113]
	v_pk_mul_f32 v[158:159], v[152:153], v[152:153]
	v_pk_mul_f32 v[172:173], v[166:167], v[166:167]
	v_pk_mul_f32 v[204:205], v[198:199], v[198:199]
	v_rcp_f32_e32 v116, v116
	v_rcp_f32_e32 v156, v156
	v_rcp_f32_e32 v170, v170
	v_rcp_f32_e32 v202, v202
	v_pk_mul_f32 v[118:119], v[118:119], v[126:127]
	v_pk_mul_f32 v[158:159], v[158:159], v[126:127]
	v_pk_mul_f32 v[172:173], v[172:173], v[126:127]
	v_pk_mul_f32 v[204:205], v[204:205], v[126:127]
	v_pk_mul_f32 v[114:115], v[114:115], v[116:117] op_sel:[1,0] op_sel_hi:[0,0]
	v_pk_mul_f32 v[154:155], v[154:155], v[156:157] op_sel:[1,0] op_sel_hi:[0,0]
	v_pk_mul_f32 v[168:169], v[168:169], v[170:171] op_sel:[1,0] op_sel_hi:[0,0]
	v_pk_mul_f32 v[200:201], v[200:201], v[202:203] op_sel:[1,0] op_sel_hi:[0,0]
	v_exp_f32_e32 v118, v118
	v_exp_f32_e32 v119, v119
	v_exp_f32_e32 v158, v158
	v_exp_f32_e32 v159, v159
	v_exp_f32_e32 v172, v172
	v_exp_f32_e32 v173, v173
	v_exp_f32_e32 v204, v204
	v_exp_f32_e32 v205, v205
	v_pk_fma_f32 v[120:121], v[114:115], s[74:75], v[180:181] op_sel_hi:[1,0,0]
	v_pk_fma_f32 v[160:161], v[154:155], s[74:75], v[180:181] op_sel_hi:[1,0,0]
	v_pk_fma_f32 v[174:175], v[168:169], s[74:75], v[180:181] op_sel_hi:[1,0,0]
	v_pk_fma_f32 v[206:207], v[200:201], s[74:75], v[180:181] op_sel_hi:[1,0,0]
	v_pk_fma_f32 v[120:121], v[114:115], v[120:121], s[78:79] op_sel_hi:[1,1,0]
	v_pk_fma_f32 v[160:161], v[154:155], v[160:161], s[78:79] op_sel_hi:[1,1,0]
	v_pk_fma_f32 v[174:175], v[168:169], v[174:175], s[78:79] op_sel_hi:[1,1,0]
	v_pk_fma_f32 v[206:207], v[200:201], v[206:207], s[78:79] op_sel_hi:[1,1,0]
	v_pk_fma_f32 v[120:121], v[114:115], v[120:121], s[80:81] op_sel_hi:[1,1,0]
	v_pk_fma_f32 v[160:161], v[154:155], v[160:161], s[80:81] op_sel_hi:[1,1,0]
	v_pk_fma_f32 v[174:175], v[168:169], v[174:175], s[80:81] op_sel_hi:[1,1,0]
	v_pk_fma_f32 v[206:207], v[200:201], v[206:207], s[80:81] op_sel_hi:[1,1,0]
	v_pk_fma_f32 v[120:121], v[114:115], v[120:121], s[82:83] op_sel_hi:[1,1,0]
	v_pk_fma_f32 v[160:161], v[154:155], v[160:161], s[82:83] op_sel_hi:[1,1,0]
	v_pk_fma_f32 v[174:175], v[168:169], v[174:175], s[82:83] op_sel_hi:[1,1,0]
	v_pk_fma_f32 v[206:207], v[200:201], v[206:207], s[82:83] op_sel_hi:[1,1,0]
	v_pk_mul_f32 v[120:121], v[114:115], v[120:121]
	v_pk_mul_f32 v[160:161], v[154:155], v[160:161]
	v_pk_mul_f32 v[174:175], v[168:169], v[174:175]
	v_pk_mul_f32 v[206:207], v[200:201], v[206:207]
	v_pk_fma_f32 v[118:119], v[118:119], v[120:121], 1.0 op_sel_hi:[1,1,0] neg_lo:[1,0,0] neg_hi:[1,0,0]
	v_pk_fma_f32 v[158:159], v[158:159], v[160:161], 1.0 op_sel_hi:[1,1,0] neg_lo:[1,0,0] neg_hi:[1,0,0]
	v_pk_fma_f32 v[172:173], v[172:173], v[174:175], 1.0 op_sel_hi:[1,1,0] neg_lo:[1,0,0] neg_hi:[1,0,0]
	v_pk_fma_f32 v[204:205], v[204:205], v[206:207], 1.0 op_sel_hi:[1,1,0] neg_lo:[1,0,0] neg_hi:[1,0,0]
	v_bfi_b32 v119, s34, v119, v113
	v_bfi_b32 v118, s34, v118, v112
	v_bfi_b32 v159, s34, v159, v153
	v_bfi_b32 v158, s34, v158, v152
	v_bfi_b32 v173, s34, v173, v167
	v_bfi_b32 v172, s34, v172, v166
	v_bfi_b32 v205, s34, v205, v199
	v_bfi_b32 v204, s34, v204, v198
	v_lshlrev_b32_e32 v124, 16, v64
	v_and_b32_e32 v125, 0xffff0000, v64
	v_lshlrev_b32_e32 v164, 16, v65
	v_and_b32_e32 v165, 0xffff0000, v65
	v_lshlrev_b32_e32 v178, 16, v66
	v_and_b32_e32 v179, 0xffff0000, v66
	v_lshlrev_b32_e32 v210, 16, v67
	v_and_b32_e32 v211, 0xffff0000, v67
	v_pk_fma_f32 v[112:113], v[112:113], v[118:119], v[112:113]
	v_pk_fma_f32 v[152:153], v[152:153], v[158:159], v[152:153]
	v_pk_fma_f32 v[166:167], v[166:167], v[172:173], v[166:167]
	v_pk_fma_f32 v[198:199], v[198:199], v[204:205], v[198:199]
	v_pk_mul_f32 v[112:113], v[112:113], v[124:125]
	v_pk_mul_f32 v[152:153], v[152:153], v[164:165]
	v_pk_mul_f32 v[166:167], v[166:167], v[178:179]
	v_pk_mul_f32 v[198:199], v[198:199], v[210:211]
	v_cvt_pk_bf16_f32 v224, v112, v113
	v_cvt_pk_bf16_f32 v225, v152, v153
	v_cvt_pk_bf16_f32 v226, v166, v167
	v_cvt_pk_bf16_f32 v227, v198, v199
	global_store_dwordx4 v[228:229], v[224:227], off nt
	v_lshl_add_u64 v[228:229], v[228:229], 0, s[98:99]
	v_lshlrev_b32_e32 v104, 16, v36
	v_and_b32_e32 v105, 0xffff0000, v36
	v_lshlrev_b32_e32 v106, 16, v37
	v_and_b32_e32 v107, 0xffff0000, v37
	v_lshlrev_b32_e32 v108, 16, v38
	v_and_b32_e32 v109, 0xffff0000, v38
	v_lshlrev_b32_e32 v110, 16, v39
	v_and_b32_e32 v111, 0xffff0000, v39
	v_pk_fma_f32 v[112:113], v[234:235], v[88:89], v[218:219]
	v_pk_fma_f32 v[152:153], v[236:237], v[90:91], v[220:221]
	v_pk_fma_f32 v[166:167], v[230:231], v[92:93], v[214:215]
	v_pk_fma_f32 v[198:199], v[232:233], v[94:95], v[216:217]
	v_pk_fma_f32 v[112:113], v[238:239], v[96:97], v[112:113]
	v_pk_fma_f32 v[152:153], v[240:241], v[98:99], v[152:153]
	v_pk_fma_f32 v[166:167], v[242:243], v[100:101], v[166:167]
	v_pk_fma_f32 v[198:199], v[244:245], v[102:103], v[198:199]
	v_pk_fma_f32 v[112:113], v[246:247], v[104:105], v[112:113]
	v_pk_fma_f32 v[152:153], v[248:249], v[106:107], v[152:153]
	v_pk_fma_f32 v[166:167], v[250:251], v[108:109], v[166:167]
	v_pk_fma_f32 v[198:199], v[252:253], v[110:111], v[198:199]
	v_add_u32_e32 v13, 3, v14
	v_and_b32_e32 v13, 0xfff, v13
	v_cmp_eq_u32_e32 vcc, 0, v13
	s_and_saveexec_b64 s[100:101], vcc
	s_cbranch_execz .Lup_b3_nolo
	v_pk_fma_f32 v[112:113], v[238:239], v[96:97], v[218:219]
	v_pk_fma_f32 v[152:153], v[240:241], v[98:99], v[220:221]
	v_pk_fma_f32 v[166:167], v[242:243], v[100:101], v[214:215]
	v_pk_fma_f32 v[198:199], v[244:245], v[102:103], v[216:217]
	v_pk_fma_f32 v[112:113], v[246:247], v[104:105], v[112:113]
	v_pk_fma_f32 v[152:153], v[248:249], v[106:107], v[152:153]
	v_pk_fma_f32 v[166:167], v[250:251], v[108:109], v[166:167]
	v_pk_fma_f32 v[198:199], v[252:253], v[110:111], v[198:199]

.Lup_b3_nohi:
	s_mov_b64 exec, s[100:101]
	v_fma_f32 v114, |v112|, v183, 1.0
	v_fma_f32 v115, |v113|, v183, 1.0
	v_fma_f32 v154, |v152|, v183, 1.0
	v_fma_f32 v155, |v153|, v183, 1.0
	v_fma_f32 v168, |v166|, v183, 1.0
	v_fma_f32 v169, |v167|, v183, 1.0
	v_fma_f32 v200, |v198|, v183, 1.0
	v_fma_f32 v201, |v199|, v183, 1.0
	v_mul_f32_e32 v116, v114, v115
	v_mul_f32_e32 v156, v154, v155
	v_mul_f32_e32 v170, v168, v169
	v_mul_f32_e32 v202, v200, v201
	v_pk_mul_f32 v[118:119], v[112:113], v[112:113]
	v_pk_mul_f32 v[158:159], v[152:153], v[152:153]
	v_pk_mul_f32 v[172:173], v[166:167], v[166:167]
	v_pk_mul_f32 v[204:205], v[198:199], v[198:199]
	v_rcp_f32_e32 v116, v116
	v_rcp_f32_e32 v156, v156
	v_rcp_f32_e32 v170, v170
	v_rcp_f32_e32 v202, v202
	v_pk_mul_f32 v[118:119], v[118:119], v[126:127]
	v_pk_mul_f32 v[158:159], v[158:159], v[126:127]
	v_pk_mul_f32 v[172:173], v[172:173], v[126:127]
	v_pk_mul_f32 v[204:205], v[204:205], v[126:127]
	v_pk_mul_f32 v[114:115], v[114:115], v[116:117] op_sel:[1,0] op_sel_hi:[0,0]
	v_pk_mul_f32 v[154:155], v[154:155], v[156:157] op_sel:[1,0] op_sel_hi:[0,0]
	v_pk_mul_f32 v[168:169], v[168:169], v[170:171] op_sel:[1,0] op_sel_hi:[0,0]
	v_pk_mul_f32 v[200:201], v[200:201], v[202:203] op_sel:[1,0] op_sel_hi:[0,0]
	v_exp_f32_e32 v118, v118
	v_exp_f32_e32 v119, v119
	v_exp_f32_e32 v158, v158
	v_exp_f32_e32 v159, v159
	v_exp_f32_e32 v172, v172
	v_exp_f32_e32 v173, v173
	v_exp_f32_e32 v204, v204
	v_exp_f32_e32 v205, v205
	v_pk_fma_f32 v[120:121], v[114:115], s[74:75], v[180:181] op_sel_hi:[1,0,0]
	v_pk_fma_f32 v[160:161], v[154:155], s[74:75], v[180:181] op_sel_hi:[1,0,0]
	v_pk_fma_f32 v[174:175], v[168:169], s[74:75], v[180:181] op_sel_hi:[1,0,0]
	v_pk_fma_f32 v[206:207], v[200:201], s[74:75], v[180:181] op_sel_hi:[1,0,0]
	v_pk_fma_f32 v[120:121], v[114:115], v[120:121], s[78:79] op_sel_hi:[1,1,0]
	v_pk_fma_f32 v[160:161], v[154:155], v[160:161], s[78:79] op_sel_hi:[1,1,0]
	v_pk_fma_f32 v[174:175], v[168:169], v[174:175], s[78:79] op_sel_hi:[1,1,0]
	v_pk_fma_f32 v[206:207], v[200:201], v[206:207], s[78:79] op_sel_hi:[1,1,0]
	v_pk_fma_f32 v[120:121], v[114:115], v[120:121], s[80:81] op_sel_hi:[1,1,0]
	v_pk_fma_f32 v[160:161], v[154:155], v[160:161], s[80:81] op_sel_hi:[1,1,0]
	v_pk_fma_f32 v[174:175], v[168:169], v[174:175], s[80:81] op_sel_hi:[1,1,0]
	v_pk_fma_f32 v[206:207], v[200:201], v[206:207], s[80:81] op_sel_hi:[1,1,0]
	v_pk_fma_f32 v[120:121], v[114:115], v[120:121], s[82:83] op_sel_hi:[1,1,0]
	v_pk_fma_f32 v[160:161], v[154:155], v[160:161], s[82:83] op_sel_hi:[1,1,0]
	v_pk_fma_f32 v[174:175], v[168:169], v[174:175], s[82:83] op_sel_hi:[1,1,0]
	v_pk_fma_f32 v[206:207], v[200:201], v[206:207], s[82:83] op_sel_hi:[1,1,0]
	v_pk_mul_f32 v[120:121], v[114:115], v[120:121]
	v_pk_mul_f32 v[160:161], v[154:155], v[160:161]
	v_pk_mul_f32 v[174:175], v[168:169], v[174:175]
	v_pk_mul_f32 v[206:207], v[200:201], v[206:207]
	v_pk_fma_f32 v[118:119], v[118:119], v[120:121], 1.0 op_sel_hi:[1,1,0] neg_lo:[1,0,0] neg_hi:[1,0,0]
	v_pk_fma_f32 v[158:159], v[158:159], v[160:161], 1.0 op_sel_hi:[1,1,0] neg_lo:[1,0,0] neg_hi:[1,0,0]
	v_pk_fma_f32 v[172:173], v[172:173], v[174:175], 1.0 op_sel_hi:[1,1,0] neg_lo:[1,0,0] neg_hi:[1,0,0]
	v_pk_fma_f32 v[204:205], v[204:205], v[206:207], 1.0 op_sel_hi:[1,1,0] neg_lo:[1,0,0] neg_hi:[1,0,0]
	v_bfi_b32 v119, s34, v119, v113
	v_bfi_b32 v118, s34, v118, v112
	v_bfi_b32 v159, s34, v159, v153
	v_bfi_b32 v158, s34, v158, v152
	v_bfi_b32 v173, s34, v173, v167
	v_bfi_b32 v172, s34, v172, v166
	v_bfi_b32 v205, s34, v205, v199
	v_bfi_b32 v204, s34, v204, v198
	v_lshlrev_b32_e32 v124, 16, v68
	v_and_b32_e32 v125, 0xffff0000, v68
	v_lshlrev_b32_e32 v164, 16, v69
	v_and_b32_e32 v165, 0xffff0000, v69
	v_lshlrev_b32_e32 v178, 16, v70
	v_and_b32_e32 v179, 0xffff0000, v70
	v_lshlrev_b32_e32 v210, 16, v71
	v_and_b32_e32 v211, 0xffff0000, v71
	v_pk_fma_f32 v[112:113], v[112:113], v[118:119], v[112:113]
	v_pk_fma_f32 v[152:153], v[152:153], v[158:159], v[152:153]
	v_pk_fma_f32 v[166:167], v[166:167], v[172:173], v[166:167]
	v_pk_fma_f32 v[198:199], v[198:199], v[204:205], v[198:199]
	v_pk_mul_f32 v[112:113], v[112:113], v[124:125]
	v_pk_mul_f32 v[152:153], v[152:153], v[164:165]
	v_pk_mul_f32 v[166:167], v[166:167], v[178:179]
	v_pk_mul_f32 v[198:199], v[198:199], v[210:211]
	v_cvt_pk_bf16_f32 v224, v112, v113
	v_cvt_pk_bf16_f32 v225, v152, v153
	v_cvt_pk_bf16_f32 v226, v166, v167
	v_cvt_pk_bf16_f32 v227, v198, v199
	global_store_dwordx4 v[228:229], v[224:227], off nt
	v_lshl_add_u64 v[228:229], v[228:229], 0, s[98:99]
	v_lshlrev_b32_e32 v88, 16, v40
	v_and_b32_e32 v89, 0xffff0000, v40
	v_lshlrev_b32_e32 v90, 16, v41
	v_and_b32_e32 v91, 0xffff0000, v41
	v_lshlrev_b32_e32 v92, 16, v42
	v_and_b32_e32 v93, 0xffff0000, v42
	v_lshlrev_b32_e32 v94, 16, v43
	v_and_b32_e32 v95, 0xffff0000, v43
	v_pk_fma_f32 v[112:113], v[234:235], v[96:97], v[218:219]
	v_pk_fma_f32 v[152:153], v[236:237], v[98:99], v[220:221]
	v_pk_fma_f32 v[166:167], v[230:231], v[100:101], v[214:215]
	v_pk_fma_f32 v[198:199], v[232:233], v[102:103], v[216:217]
	v_pk_fma_f32 v[112:113], v[238:239], v[104:105], v[112:113]
	v_pk_fma_f32 v[152:153], v[240:241], v[106:107], v[152:153]
	v_pk_fma_f32 v[166:167], v[242:243], v[108:109], v[166:167]
	v_pk_fma_f32 v[198:199], v[244:245], v[110:111], v[198:199]
	v_pk_fma_f32 v[112:113], v[246:247], v[88:89], v[112:113]
	v_pk_fma_f32 v[152:153], v[248:249], v[90:91], v[152:153]
	v_pk_fma_f32 v[166:167], v[250:251], v[92:93], v[166:167]
	v_pk_fma_f32 v[198:199], v[252:253], v[94:95], v[198:199]
	v_add_u32_e32 v13, 4, v14
	v_and_b32_e32 v13, 0xfff, v13
	v_cmp_eq_u32_e32 vcc, 0, v13
	s_and_saveexec_b64 s[100:101], vcc
	s_cbranch_execz .Lup_b4_nolo
	v_pk_fma_f32 v[112:113], v[238:239], v[104:105], v[218:219]
	v_pk_fma_f32 v[152:153], v[240:241], v[106:107], v[220:221]
	v_pk_fma_f32 v[166:167], v[242:243], v[108:109], v[214:215]
	v_pk_fma_f32 v[198:199], v[244:245], v[110:111], v[216:217]
	v_pk_fma_f32 v[112:113], v[246:247], v[88:89], v[112:113]
	v_pk_fma_f32 v[152:153], v[248:249], v[90:91], v[152:153]
	v_pk_fma_f32 v[166:167], v[250:251], v[92:93], v[166:167]
	v_pk_fma_f32 v[198:199], v[252:253], v[94:95], v[198:199]

.Lup_b4_nohi:
	s_mov_b64 exec, s[100:101]
	v_fma_f32 v114, |v112|, v183, 1.0
	v_fma_f32 v115, |v113|, v183, 1.0
	v_fma_f32 v154, |v152|, v183, 1.0
	v_fma_f32 v155, |v153|, v183, 1.0
	v_fma_f32 v168, |v166|, v183, 1.0
	v_fma_f32 v169, |v167|, v183, 1.0
	v_fma_f32 v200, |v198|, v183, 1.0
	v_fma_f32 v201, |v199|, v183, 1.0
	v_mul_f32_e32 v116, v114, v115
	v_mul_f32_e32 v156, v154, v155
	v_mul_f32_e32 v170, v168, v169
	v_mul_f32_e32 v202, v200, v201
	v_pk_mul_f32 v[118:119], v[112:113], v[112:113]
	v_pk_mul_f32 v[158:159], v[152:153], v[152:153]
	v_pk_mul_f32 v[172:173], v[166:167], v[166:167]
	v_pk_mul_f32 v[204:205], v[198:199], v[198:199]
	v_rcp_f32_e32 v116, v116
	v_rcp_f32_e32 v156, v156
	v_rcp_f32_e32 v170, v170
	v_rcp_f32_e32 v202, v202
	v_pk_mul_f32 v[118:119], v[118:119], v[126:127]
	v_pk_mul_f32 v[158:159], v[158:159], v[126:127]
	v_pk_mul_f32 v[172:173], v[172:173], v[126:127]
	v_pk_mul_f32 v[204:205], v[204:205], v[126:127]
	v_pk_mul_f32 v[114:115], v[114:115], v[116:117] op_sel:[1,0] op_sel_hi:[0,0]
	v_pk_mul_f32 v[154:155], v[154:155], v[156:157] op_sel:[1,0] op_sel_hi:[0,0]
	v_pk_mul_f32 v[168:169], v[168:169], v[170:171] op_sel:[1,0] op_sel_hi:[0,0]
	v_pk_mul_f32 v[200:201], v[200:201], v[202:203] op_sel:[1,0] op_sel_hi:[0,0]
	v_exp_f32_e32 v118, v118
	v_exp_f32_e32 v119, v119
	v_exp_f32_e32 v158, v158
	v_exp_f32_e32 v159, v159
	v_exp_f32_e32 v172, v172
	v_exp_f32_e32 v173, v173
	v_exp_f32_e32 v204, v204
	v_exp_f32_e32 v205, v205
	v_pk_fma_f32 v[120:121], v[114:115], s[74:75], v[180:181] op_sel_hi:[1,0,0]
	v_pk_fma_f32 v[160:161], v[154:155], s[74:75], v[180:181] op_sel_hi:[1,0,0]
	v_pk_fma_f32 v[174:175], v[168:169], s[74:75], v[180:181] op_sel_hi:[1,0,0]
	v_pk_fma_f32 v[206:207], v[200:201], s[74:75], v[180:181] op_sel_hi:[1,0,0]
	v_pk_fma_f32 v[120:121], v[114:115], v[120:121], s[78:79] op_sel_hi:[1,1,0]
	v_pk_fma_f32 v[160:161], v[154:155], v[160:161], s[78:79] op_sel_hi:[1,1,0]
	v_pk_fma_f32 v[174:175], v[168:169], v[174:175], s[78:79] op_sel_hi:[1,1,0]
	v_pk_fma_f32 v[206:207], v[200:201], v[206:207], s[78:79] op_sel_hi:[1,1,0]
	v_pk_fma_f32 v[120:121], v[114:115], v[120:121], s[80:81] op_sel_hi:[1,1,0]
	v_pk_fma_f32 v[160:161], v[154:155], v[160:161], s[80:81] op_sel_hi:[1,1,0]
	v_pk_fma_f32 v[174:175], v[168:169], v[174:175], s[80:81] op_sel_hi:[1,1,0]
	v_pk_fma_f32 v[206:207], v[200:201], v[206:207], s[80:81] op_sel_hi:[1,1,0]
	v_pk_fma_f32 v[120:121], v[114:115], v[120:121], s[82:83] op_sel_hi:[1,1,0]
	v_pk_fma_f32 v[160:161], v[154:155], v[160:161], s[82:83] op_sel_hi:[1,1,0]
	v_pk_fma_f32 v[174:175], v[168:169], v[174:175], s[82:83] op_sel_hi:[1,1,0]
	v_pk_fma_f32 v[206:207], v[200:201], v[206:207], s[82:83] op_sel_hi:[1,1,0]
	v_pk_mul_f32 v[120:121], v[114:115], v[120:121]
	v_pk_mul_f32 v[160:161], v[154:155], v[160:161]
	v_pk_mul_f32 v[174:175], v[168:169], v[174:175]
	v_pk_mul_f32 v[206:207], v[200:201], v[206:207]
	v_pk_fma_f32 v[118:119], v[118:119], v[120:121], 1.0 op_sel_hi:[1,1,0] neg_lo:[1,0,0] neg_hi:[1,0,0]
	v_pk_fma_f32 v[158:159], v[158:159], v[160:161], 1.0 op_sel_hi:[1,1,0] neg_lo:[1,0,0] neg_hi:[1,0,0]
	v_pk_fma_f32 v[172:173], v[172:173], v[174:175], 1.0 op_sel_hi:[1,1,0] neg_lo:[1,0,0] neg_hi:[1,0,0]
	v_pk_fma_f32 v[204:205], v[204:205], v[206:207], 1.0 op_sel_hi:[1,1,0] neg_lo:[1,0,0] neg_hi:[1,0,0]
	v_bfi_b32 v119, s34, v119, v113
	v_bfi_b32 v118, s34, v118, v112
	v_bfi_b32 v159, s34, v159, v153
	v_bfi_b32 v158, s34, v158, v152
	v_bfi_b32 v173, s34, v173, v167
	v_bfi_b32 v172, s34, v172, v166
	v_bfi_b32 v205, s34, v205, v199
	v_bfi_b32 v204, s34, v204, v198
	v_lshlrev_b32_e32 v124, 16, v72
	v_and_b32_e32 v125, 0xffff0000, v72
	v_lshlrev_b32_e32 v164, 16, v73
	v_and_b32_e32 v165, 0xffff0000, v73
	v_lshlrev_b32_e32 v178, 16, v74
	v_and_b32_e32 v179, 0xffff0000, v74
	v_lshlrev_b32_e32 v210, 16, v75
	v_and_b32_e32 v211, 0xffff0000, v75
	v_pk_fma_f32 v[112:113], v[112:113], v[118:119], v[112:113]
	v_pk_fma_f32 v[152:153], v[152:153], v[158:159], v[152:153]
	v_pk_fma_f32 v[166:167], v[166:167], v[172:173], v[166:167]
	v_pk_fma_f32 v[198:199], v[198:199], v[204:205], v[198:199]
	v_pk_mul_f32 v[112:113], v[112:113], v[124:125]
	v_pk_mul_f32 v[152:153], v[152:153], v[164:165]
	v_pk_mul_f32 v[166:167], v[166:167], v[178:179]
	v_pk_mul_f32 v[198:199], v[198:199], v[210:211]
	v_cvt_pk_bf16_f32 v224, v112, v113
	v_cvt_pk_bf16_f32 v225, v152, v153
	v_cvt_pk_bf16_f32 v226, v166, v167
	v_cvt_pk_bf16_f32 v227, v198, v199
	global_store_dwordx4 v[228:229], v[224:227], off nt
	v_lshl_add_u64 v[228:229], v[228:229], 0, s[98:99]
	v_lshlrev_b32_e32 v96, 16, v44
	v_and_b32_e32 v97, 0xffff0000, v44
	v_lshlrev_b32_e32 v98, 16, v45
	v_and_b32_e32 v99, 0xffff0000, v45
	v_lshlrev_b32_e32 v100, 16, v46
	v_and_b32_e32 v101, 0xffff0000, v46
	v_lshlrev_b32_e32 v102, 16, v47
	v_and_b32_e32 v103, 0xffff0000, v47
	v_pk_fma_f32 v[112:113], v[234:235], v[104:105], v[218:219]
	v_pk_fma_f32 v[152:153], v[236:237], v[106:107], v[220:221]
	v_pk_fma_f32 v[166:167], v[230:231], v[108:109], v[214:215]
	v_pk_fma_f32 v[198:199], v[232:233], v[110:111], v[216:217]
	v_pk_fma_f32 v[112:113], v[238:239], v[88:89], v[112:113]
	v_pk_fma_f32 v[152:153], v[240:241], v[90:91], v[152:153]
	v_pk_fma_f32 v[166:167], v[242:243], v[92:93], v[166:167]
	v_pk_fma_f32 v[198:199], v[244:245], v[94:95], v[198:199]
	v_pk_fma_f32 v[112:113], v[246:247], v[96:97], v[112:113]
	v_pk_fma_f32 v[152:153], v[248:249], v[98:99], v[152:153]
	v_pk_fma_f32 v[166:167], v[250:251], v[100:101], v[166:167]
	v_pk_fma_f32 v[198:199], v[252:253], v[102:103], v[198:199]
	v_add_u32_e32 v13, 5, v14
	v_and_b32_e32 v13, 0xfff, v13
	v_cmp_eq_u32_e32 vcc, 0, v13
	s_and_saveexec_b64 s[100:101], vcc
	s_cbranch_execz .Lup_b5_nolo
	v_pk_fma_f32 v[112:113], v[238:239], v[88:89], v[218:219]
	v_pk_fma_f32 v[152:153], v[240:241], v[90:91], v[220:221]
	v_pk_fma_f32 v[166:167], v[242:243], v[92:93], v[214:215]
	v_pk_fma_f32 v[198:199], v[244:245], v[94:95], v[216:217]
	v_pk_fma_f32 v[112:113], v[246:247], v[96:97], v[112:113]
	v_pk_fma_f32 v[152:153], v[248:249], v[98:99], v[152:153]
	v_pk_fma_f32 v[166:167], v[250:251], v[100:101], v[166:167]
	v_pk_fma_f32 v[198:199], v[252:253], v[102:103], v[198:199]

.Lup_b5_nohi:
	s_mov_b64 exec, s[100:101]
	v_fma_f32 v114, |v112|, v183, 1.0
	v_fma_f32 v115, |v113|, v183, 1.0
	v_fma_f32 v154, |v152|, v183, 1.0
	v_fma_f32 v155, |v153|, v183, 1.0
	v_fma_f32 v168, |v166|, v183, 1.0
	v_fma_f32 v169, |v167|, v183, 1.0
	v_fma_f32 v200, |v198|, v183, 1.0
	v_fma_f32 v201, |v199|, v183, 1.0
	v_mul_f32_e32 v116, v114, v115
	v_mul_f32_e32 v156, v154, v155
	v_mul_f32_e32 v170, v168, v169
	v_mul_f32_e32 v202, v200, v201
	v_pk_mul_f32 v[118:119], v[112:113], v[112:113]
	v_pk_mul_f32 v[158:159], v[152:153], v[152:153]
	v_pk_mul_f32 v[172:173], v[166:167], v[166:167]
	v_pk_mul_f32 v[204:205], v[198:199], v[198:199]
	v_rcp_f32_e32 v116, v116
	v_rcp_f32_e32 v156, v156
	v_rcp_f32_e32 v170, v170
	v_rcp_f32_e32 v202, v202
	v_pk_mul_f32 v[118:119], v[118:119], v[126:127]
	v_pk_mul_f32 v[158:159], v[158:159], v[126:127]
	v_pk_mul_f32 v[172:173], v[172:173], v[126:127]
	v_pk_mul_f32 v[204:205], v[204:205], v[126:127]
	v_pk_mul_f32 v[114:115], v[114:115], v[116:117] op_sel:[1,0] op_sel_hi:[0,0]
	v_pk_mul_f32 v[154:155], v[154:155], v[156:157] op_sel:[1,0] op_sel_hi:[0,0]
	v_pk_mul_f32 v[168:169], v[168:169], v[170:171] op_sel:[1,0] op_sel_hi:[0,0]
	v_pk_mul_f32 v[200:201], v[200:201], v[202:203] op_sel:[1,0] op_sel_hi:[0,0]
	v_exp_f32_e32 v118, v118
	v_exp_f32_e32 v119, v119
	v_exp_f32_e32 v158, v158
	v_exp_f32_e32 v159, v159
	v_exp_f32_e32 v172, v172
	v_exp_f32_e32 v173, v173
	v_exp_f32_e32 v204, v204
	v_exp_f32_e32 v205, v205
	v_pk_fma_f32 v[120:121], v[114:115], s[74:75], v[180:181] op_sel_hi:[1,0,0]
	v_pk_fma_f32 v[160:161], v[154:155], s[74:75], v[180:181] op_sel_hi:[1,0,0]
	v_pk_fma_f32 v[174:175], v[168:169], s[74:75], v[180:181] op_sel_hi:[1,0,0]
	v_pk_fma_f32 v[206:207], v[200:201], s[74:75], v[180:181] op_sel_hi:[1,0,0]
	v_pk_fma_f32 v[120:121], v[114:115], v[120:121], s[78:79] op_sel_hi:[1,1,0]
	v_pk_fma_f32 v[160:161], v[154:155], v[160:161], s[78:79] op_sel_hi:[1,1,0]
	v_pk_fma_f32 v[174:175], v[168:169], v[174:175], s[78:79] op_sel_hi:[1,1,0]
	v_pk_fma_f32 v[206:207], v[200:201], v[206:207], s[78:79] op_sel_hi:[1,1,0]
	v_pk_fma_f32 v[120:121], v[114:115], v[120:121], s[80:81] op_sel_hi:[1,1,0]
	v_pk_fma_f32 v[160:161], v[154:155], v[160:161], s[80:81] op_sel_hi:[1,1,0]
	v_pk_fma_f32 v[174:175], v[168:169], v[174:175], s[80:81] op_sel_hi:[1,1,0]
	v_pk_fma_f32 v[206:207], v[200:201], v[206:207], s[80:81] op_sel_hi:[1,1,0]
	v_pk_fma_f32 v[120:121], v[114:115], v[120:121], s[82:83] op_sel_hi:[1,1,0]
	v_pk_fma_f32 v[160:161], v[154:155], v[160:161], s[82:83] op_sel_hi:[1,1,0]
	v_pk_fma_f32 v[174:175], v[168:169], v[174:175], s[82:83] op_sel_hi:[1,1,0]
	v_pk_fma_f32 v[206:207], v[200:201], v[206:207], s[82:83] op_sel_hi:[1,1,0]
	v_pk_mul_f32 v[120:121], v[114:115], v[120:121]
	v_pk_mul_f32 v[160:161], v[154:155], v[160:161]
	v_pk_mul_f32 v[174:175], v[168:169], v[174:175]
	v_pk_mul_f32 v[206:207], v[200:201], v[206:207]
	v_pk_fma_f32 v[118:119], v[118:119], v[120:121], 1.0 op_sel_hi:[1,1,0] neg_lo:[1,0,0] neg_hi:[1,0,0]
	v_pk_fma_f32 v[158:159], v[158:159], v[160:161], 1.0 op_sel_hi:[1,1,0] neg_lo:[1,0,0] neg_hi:[1,0,0]
	v_pk_fma_f32 v[172:173], v[172:173], v[174:175], 1.0 op_sel_hi:[1,1,0] neg_lo:[1,0,0] neg_hi:[1,0,0]
	v_pk_fma_f32 v[204:205], v[204:205], v[206:207], 1.0 op_sel_hi:[1,1,0] neg_lo:[1,0,0] neg_hi:[1,0,0]
	v_bfi_b32 v119, s34, v119, v113
	v_bfi_b32 v118, s34, v118, v112
	v_bfi_b32 v159, s34, v159, v153
	v_bfi_b32 v158, s34, v158, v152
	v_bfi_b32 v173, s34, v173, v167
	v_bfi_b32 v172, s34, v172, v166
	v_bfi_b32 v205, s34, v205, v199
	v_bfi_b32 v204, s34, v204, v198
	v_lshlrev_b32_e32 v124, 16, v76
	v_and_b32_e32 v125, 0xffff0000, v76
	v_lshlrev_b32_e32 v164, 16, v77
	v_and_b32_e32 v165, 0xffff0000, v77
	v_lshlrev_b32_e32 v178, 16, v78
	v_and_b32_e32 v179, 0xffff0000, v78
	v_lshlrev_b32_e32 v210, 16, v79
	v_and_b32_e32 v211, 0xffff0000, v79
	v_pk_fma_f32 v[112:113], v[112:113], v[118:119], v[112:113]
	v_pk_fma_f32 v[152:153], v[152:153], v[158:159], v[152:153]
	v_pk_fma_f32 v[166:167], v[166:167], v[172:173], v[166:167]
	v_pk_fma_f32 v[198:199], v[198:199], v[204:205], v[198:199]
	v_pk_mul_f32 v[112:113], v[112:113], v[124:125]
	v_pk_mul_f32 v[152:153], v[152:153], v[164:165]
	v_pk_mul_f32 v[166:167], v[166:167], v[178:179]
	v_pk_mul_f32 v[198:199], v[198:199], v[210:211]
	v_cvt_pk_bf16_f32 v224, v112, v113
	v_cvt_pk_bf16_f32 v225, v152, v153
	v_cvt_pk_bf16_f32 v226, v166, v167
	v_cvt_pk_bf16_f32 v227, v198, v199
	global_store_dwordx4 v[228:229], v[224:227], off nt
	v_lshl_add_u64 v[228:229], v[228:229], 0, s[98:99]
	v_lshlrev_b32_e32 v104, 16, v48
	v_and_b32_e32 v105, 0xffff0000, v48
	v_lshlrev_b32_e32 v106, 16, v49
	v_and_b32_e32 v107, 0xffff0000, v49
	v_lshlrev_b32_e32 v108, 16, v50
	v_and_b32_e32 v109, 0xffff0000, v50
	v_lshlrev_b32_e32 v110, 16, v51
	v_and_b32_e32 v111, 0xffff0000, v51
	v_pk_fma_f32 v[112:113], v[234:235], v[88:89], v[218:219]
	v_pk_fma_f32 v[152:153], v[236:237], v[90:91], v[220:221]
	v_pk_fma_f32 v[166:167], v[230:231], v[92:93], v[214:215]
	v_pk_fma_f32 v[198:199], v[232:233], v[94:95], v[216:217]
	v_pk_fma_f32 v[112:113], v[238:239], v[96:97], v[112:113]
	v_pk_fma_f32 v[152:153], v[240:241], v[98:99], v[152:153]
	v_pk_fma_f32 v[166:167], v[242:243], v[100:101], v[166:167]
	v_pk_fma_f32 v[198:199], v[244:245], v[102:103], v[198:199]
	v_pk_fma_f32 v[112:113], v[246:247], v[104:105], v[112:113]
	v_pk_fma_f32 v[152:153], v[248:249], v[106:107], v[152:153]
	v_pk_fma_f32 v[166:167], v[250:251], v[108:109], v[166:167]
	v_pk_fma_f32 v[198:199], v[252:253], v[110:111], v[198:199]
	v_add_u32_e32 v13, 6, v14
	v_and_b32_e32 v13, 0xfff, v13
	v_cmp_eq_u32_e32 vcc, 0, v13
	s_and_saveexec_b64 s[100:101], vcc
	s_cbranch_execz .Lup_b6_nolo
	v_pk_fma_f32 v[112:113], v[238:239], v[96:97], v[218:219]
	v_pk_fma_f32 v[152:153], v[240:241], v[98:99], v[220:221]
	v_pk_fma_f32 v[166:167], v[242:243], v[100:101], v[214:215]
	v_pk_fma_f32 v[198:199], v[244:245], v[102:103], v[216:217]
	v_pk_fma_f32 v[112:113], v[246:247], v[104:105], v[112:113]
	v_pk_fma_f32 v[152:153], v[248:249], v[106:107], v[152:153]
	v_pk_fma_f32 v[166:167], v[250:251], v[108:109], v[166:167]
	v_pk_fma_f32 v[198:199], v[252:253], v[110:111], v[198:199]

.Lup_b6_nohi:
	s_mov_b64 exec, s[100:101]
	v_fma_f32 v114, |v112|, v183, 1.0
	v_fma_f32 v115, |v113|, v183, 1.0
	v_fma_f32 v154, |v152|, v183, 1.0
	v_fma_f32 v155, |v153|, v183, 1.0
	v_fma_f32 v168, |v166|, v183, 1.0
	v_fma_f32 v169, |v167|, v183, 1.0
	v_fma_f32 v200, |v198|, v183, 1.0
	v_fma_f32 v201, |v199|, v183, 1.0
	v_mul_f32_e32 v116, v114, v115
	v_mul_f32_e32 v156, v154, v155
	v_mul_f32_e32 v170, v168, v169
	v_mul_f32_e32 v202, v200, v201
	v_pk_mul_f32 v[118:119], v[112:113], v[112:113]
	v_pk_mul_f32 v[158:159], v[152:153], v[152:153]
	v_pk_mul_f32 v[172:173], v[166:167], v[166:167]
	v_pk_mul_f32 v[204:205], v[198:199], v[198:199]
	v_rcp_f32_e32 v116, v116
	v_rcp_f32_e32 v156, v156
	v_rcp_f32_e32 v170, v170
	v_rcp_f32_e32 v202, v202
	v_pk_mul_f32 v[118:119], v[118:119], v[126:127]
	v_pk_mul_f32 v[158:159], v[158:159], v[126:127]
	v_pk_mul_f32 v[172:173], v[172:173], v[126:127]
	v_pk_mul_f32 v[204:205], v[204:205], v[126:127]
	v_pk_mul_f32 v[114:115], v[114:115], v[116:117] op_sel:[1,0] op_sel_hi:[0,0]
	v_pk_mul_f32 v[154:155], v[154:155], v[156:157] op_sel:[1,0] op_sel_hi:[0,0]
	v_pk_mul_f32 v[168:169], v[168:169], v[170:171] op_sel:[1,0] op_sel_hi:[0,0]
	v_pk_mul_f32 v[200:201], v[200:201], v[202:203] op_sel:[1,0] op_sel_hi:[0,0]
	v_exp_f32_e32 v118, v118
	v_exp_f32_e32 v119, v119
	v_exp_f32_e32 v158, v158
	v_exp_f32_e32 v159, v159
	v_exp_f32_e32 v172, v172
	v_exp_f32_e32 v173, v173
	v_exp_f32_e32 v204, v204
	v_exp_f32_e32 v205, v205
	v_pk_fma_f32 v[120:121], v[114:115], s[74:75], v[180:181] op_sel_hi:[1,0,0]
	v_pk_fma_f32 v[160:161], v[154:155], s[74:75], v[180:181] op_sel_hi:[1,0,0]
	v_pk_fma_f32 v[174:175], v[168:169], s[74:75], v[180:181] op_sel_hi:[1,0,0]
	v_pk_fma_f32 v[206:207], v[200:201], s[74:75], v[180:181] op_sel_hi:[1,0,0]
	v_pk_fma_f32 v[120:121], v[114:115], v[120:121], s[78:79] op_sel_hi:[1,1,0]
	v_pk_fma_f32 v[160:161], v[154:155], v[160:161], s[78:79] op_sel_hi:[1,1,0]
	v_pk_fma_f32 v[174:175], v[168:169], v[174:175], s[78:79] op_sel_hi:[1,1,0]
	v_pk_fma_f32 v[206:207], v[200:201], v[206:207], s[78:79] op_sel_hi:[1,1,0]
	v_pk_fma_f32 v[120:121], v[114:115], v[120:121], s[80:81] op_sel_hi:[1,1,0]
	v_pk_fma_f32 v[160:161], v[154:155], v[160:161], s[80:81] op_sel_hi:[1,1,0]
	v_pk_fma_f32 v[174:175], v[168:169], v[174:175], s[80:81] op_sel_hi:[1,1,0]
	v_pk_fma_f32 v[206:207], v[200:201], v[206:207], s[80:81] op_sel_hi:[1,1,0]
	v_pk_fma_f32 v[120:121], v[114:115], v[120:121], s[82:83] op_sel_hi:[1,1,0]
	v_pk_fma_f32 v[160:161], v[154:155], v[160:161], s[82:83] op_sel_hi:[1,1,0]
	v_pk_fma_f32 v[174:175], v[168:169], v[174:175], s[82:83] op_sel_hi:[1,1,0]
	v_pk_fma_f32 v[206:207], v[200:201], v[206:207], s[82:83] op_sel_hi:[1,1,0]
	v_pk_mul_f32 v[120:121], v[114:115], v[120:121]
	v_pk_mul_f32 v[160:161], v[154:155], v[160:161]
	v_pk_mul_f32 v[174:175], v[168:169], v[174:175]
	v_pk_mul_f32 v[206:207], v[200:201], v[206:207]
	v_pk_fma_f32 v[118:119], v[118:119], v[120:121], 1.0 op_sel_hi:[1,1,0] neg_lo:[1,0,0] neg_hi:[1,0,0]
	v_pk_fma_f32 v[158:159], v[158:159], v[160:161], 1.0 op_sel_hi:[1,1,0] neg_lo:[1,0,0] neg_hi:[1,0,0]
	v_pk_fma_f32 v[172:173], v[172:173], v[174:175], 1.0 op_sel_hi:[1,1,0] neg_lo:[1,0,0] neg_hi:[1,0,0]
	v_pk_fma_f32 v[204:205], v[204:205], v[206:207], 1.0 op_sel_hi:[1,1,0] neg_lo:[1,0,0] neg_hi:[1,0,0]
	v_bfi_b32 v119, s34, v119, v113
	v_bfi_b32 v118, s34, v118, v112
	v_bfi_b32 v159, s34, v159, v153
	v_bfi_b32 v158, s34, v158, v152
	v_bfi_b32 v173, s34, v173, v167
	v_bfi_b32 v172, s34, v172, v166
	v_bfi_b32 v205, s34, v205, v199
	v_bfi_b32 v204, s34, v204, v198
	v_lshlrev_b32_e32 v124, 16, v80
	v_and_b32_e32 v125, 0xffff0000, v80
	v_lshlrev_b32_e32 v164, 16, v81
	v_and_b32_e32 v165, 0xffff0000, v81
	v_lshlrev_b32_e32 v178, 16, v82
	v_and_b32_e32 v179, 0xffff0000, v82
	v_lshlrev_b32_e32 v210, 16, v83
	v_and_b32_e32 v211, 0xffff0000, v83
	v_pk_fma_f32 v[112:113], v[112:113], v[118:119], v[112:113]
	v_pk_fma_f32 v[152:153], v[152:153], v[158:159], v[152:153]
	v_pk_fma_f32 v[166:167], v[166:167], v[172:173], v[166:167]
	v_pk_fma_f32 v[198:199], v[198:199], v[204:205], v[198:199]
	v_pk_mul_f32 v[112:113], v[112:113], v[124:125]
	v_pk_mul_f32 v[152:153], v[152:153], v[164:165]
	v_pk_mul_f32 v[166:167], v[166:167], v[178:179]
	v_pk_mul_f32 v[198:199], v[198:199], v[210:211]
	v_cvt_pk_bf16_f32 v224, v112, v113
	v_cvt_pk_bf16_f32 v225, v152, v153
	v_cvt_pk_bf16_f32 v226, v166, v167
	v_cvt_pk_bf16_f32 v227, v198, v199
	global_store_dwordx4 v[228:229], v[224:227], off nt
	v_lshl_add_u64 v[228:229], v[228:229], 0, s[98:99]
	v_lshlrev_b32_e32 v88, 16, v52
	v_and_b32_e32 v89, 0xffff0000, v52
	v_lshlrev_b32_e32 v90, 16, v53
	v_and_b32_e32 v91, 0xffff0000, v53
	v_lshlrev_b32_e32 v92, 16, v54
	v_and_b32_e32 v93, 0xffff0000, v54
	v_lshlrev_b32_e32 v94, 16, v55
	v_and_b32_e32 v95, 0xffff0000, v55
	v_pk_fma_f32 v[112:113], v[234:235], v[96:97], v[218:219]
	v_pk_fma_f32 v[152:153], v[236:237], v[98:99], v[220:221]
	v_pk_fma_f32 v[166:167], v[230:231], v[100:101], v[214:215]
	v_pk_fma_f32 v[198:199], v[232:233], v[102:103], v[216:217]
	v_pk_fma_f32 v[112:113], v[238:239], v[104:105], v[112:113]
	v_pk_fma_f32 v[152:153], v[240:241], v[106:107], v[152:153]
	v_pk_fma_f32 v[166:167], v[242:243], v[108:109], v[166:167]
	v_pk_fma_f32 v[198:199], v[244:245], v[110:111], v[198:199]
	v_pk_fma_f32 v[112:113], v[246:247], v[88:89], v[112:113]
	v_pk_fma_f32 v[152:153], v[248:249], v[90:91], v[152:153]
	v_pk_fma_f32 v[166:167], v[250:251], v[92:93], v[166:167]
	v_pk_fma_f32 v[198:199], v[252:253], v[94:95], v[198:199]
	v_add_u32_e32 v13, 7, v14
	v_and_b32_e32 v13, 0xfff, v13
	v_cmp_eq_u32_e32 vcc, 0, v13
	s_and_saveexec_b64 s[100:101], vcc
	s_cbranch_execz .Lup_b7_nolo
	v_pk_fma_f32 v[112:113], v[238:239], v[104:105], v[218:219]
	v_pk_fma_f32 v[152:153], v[240:241], v[106:107], v[220:221]
	v_pk_fma_f32 v[166:167], v[242:243], v[108:109], v[214:215]
	v_pk_fma_f32 v[198:199], v[244:245], v[110:111], v[216:217]
	v_pk_fma_f32 v[112:113], v[246:247], v[88:89], v[112:113]
	v_pk_fma_f32 v[152:153], v[248:249], v[90:91], v[152:153]
	v_pk_fma_f32 v[166:167], v[250:251], v[92:93], v[166:167]
	v_pk_fma_f32 v[198:199], v[252:253], v[94:95], v[198:199]

.Lup_b7_nohi:
	s_mov_b64 exec, s[100:101]
	v_fma_f32 v114, |v112|, v183, 1.0
	v_fma_f32 v115, |v113|, v183, 1.0
	v_fma_f32 v154, |v152|, v183, 1.0
	v_fma_f32 v155, |v153|, v183, 1.0
	v_fma_f32 v168, |v166|, v183, 1.0
	v_fma_f32 v169, |v167|, v183, 1.0
	v_fma_f32 v200, |v198|, v183, 1.0
	v_fma_f32 v201, |v199|, v183, 1.0
	v_mul_f32_e32 v116, v114, v115
	v_mul_f32_e32 v156, v154, v155
	v_mul_f32_e32 v170, v168, v169
	v_mul_f32_e32 v202, v200, v201
	v_pk_mul_f32 v[118:119], v[112:113], v[112:113]
	v_pk_mul_f32 v[158:159], v[152:153], v[152:153]
	v_pk_mul_f32 v[172:173], v[166:167], v[166:167]
	v_pk_mul_f32 v[204:205], v[198:199], v[198:199]
	v_rcp_f32_e32 v116, v116
	v_rcp_f32_e32 v156, v156
	v_rcp_f32_e32 v170, v170
	v_rcp_f32_e32 v202, v202
	v_pk_mul_f32 v[118:119], v[118:119], v[126:127]
	v_pk_mul_f32 v[158:159], v[158:159], v[126:127]
	v_pk_mul_f32 v[172:173], v[172:173], v[126:127]
	v_pk_mul_f32 v[204:205], v[204:205], v[126:127]
	v_pk_mul_f32 v[114:115], v[114:115], v[116:117] op_sel:[1,0] op_sel_hi:[0,0]
	v_pk_mul_f32 v[154:155], v[154:155], v[156:157] op_sel:[1,0] op_sel_hi:[0,0]
	v_pk_mul_f32 v[168:169], v[168:169], v[170:171] op_sel:[1,0] op_sel_hi:[0,0]
	v_pk_mul_f32 v[200:201], v[200:201], v[202:203] op_sel:[1,0] op_sel_hi:[0,0]
	v_exp_f32_e32 v118, v118
	v_exp_f32_e32 v119, v119
	v_exp_f32_e32 v158, v158
	v_exp_f32_e32 v159, v159
	v_exp_f32_e32 v172, v172
	v_exp_f32_e32 v173, v173
	v_exp_f32_e32 v204, v204
	v_exp_f32_e32 v205, v205
	v_pk_fma_f32 v[120:121], v[114:115], s[74:75], v[180:181] op_sel_hi:[1,0,0]
	v_pk_fma_f32 v[160:161], v[154:155], s[74:75], v[180:181] op_sel_hi:[1,0,0]
	v_pk_fma_f32 v[174:175], v[168:169], s[74:75], v[180:181] op_sel_hi:[1,0,0]
	v_pk_fma_f32 v[206:207], v[200:201], s[74:75], v[180:181] op_sel_hi:[1,0,0]
	v_pk_fma_f32 v[120:121], v[114:115], v[120:121], s[78:79] op_sel_hi:[1,1,0]
	v_pk_fma_f32 v[160:161], v[154:155], v[160:161], s[78:79] op_sel_hi:[1,1,0]
	v_pk_fma_f32 v[174:175], v[168:169], v[174:175], s[78:79] op_sel_hi:[1,1,0]
	v_pk_fma_f32 v[206:207], v[200:201], v[206:207], s[78:79] op_sel_hi:[1,1,0]
	v_pk_fma_f32 v[120:121], v[114:115], v[120:121], s[80:81] op_sel_hi:[1,1,0]
	v_pk_fma_f32 v[160:161], v[154:155], v[160:161], s[80:81] op_sel_hi:[1,1,0]
	v_pk_fma_f32 v[174:175], v[168:169], v[174:175], s[80:81] op_sel_hi:[1,1,0]
	v_pk_fma_f32 v[206:207], v[200:201], v[206:207], s[80:81] op_sel_hi:[1,1,0]
	v_pk_fma_f32 v[120:121], v[114:115], v[120:121], s[82:83] op_sel_hi:[1,1,0]
	v_pk_fma_f32 v[160:161], v[154:155], v[160:161], s[82:83] op_sel_hi:[1,1,0]
	v_pk_fma_f32 v[174:175], v[168:169], v[174:175], s[82:83] op_sel_hi:[1,1,0]
	v_pk_fma_f32 v[206:207], v[200:201], v[206:207], s[82:83] op_sel_hi:[1,1,0]
	v_pk_mul_f32 v[120:121], v[114:115], v[120:121]
	v_pk_mul_f32 v[160:161], v[154:155], v[160:161]
	v_pk_mul_f32 v[174:175], v[168:169], v[174:175]
	v_pk_mul_f32 v[206:207], v[200:201], v[206:207]
	v_pk_fma_f32 v[118:119], v[118:119], v[120:121], 1.0 op_sel_hi:[1,1,0] neg_lo:[1,0,0] neg_hi:[1,0,0]
	v_pk_fma_f32 v[158:159], v[158:159], v[160:161], 1.0 op_sel_hi:[1,1,0] neg_lo:[1,0,0] neg_hi:[1,0,0]
	v_pk_fma_f32 v[172:173], v[172:173], v[174:175], 1.0 op_sel_hi:[1,1,0] neg_lo:[1,0,0] neg_hi:[1,0,0]
	v_pk_fma_f32 v[204:205], v[204:205], v[206:207], 1.0 op_sel_hi:[1,1,0] neg_lo:[1,0,0] neg_hi:[1,0,0]
	v_bfi_b32 v119, s34, v119, v113
	v_bfi_b32 v118, s34, v118, v112
	v_bfi_b32 v159, s34, v159, v153
	v_bfi_b32 v158, s34, v158, v152
	v_bfi_b32 v173, s34, v173, v167
	v_bfi_b32 v172, s34, v172, v166
	v_bfi_b32 v205, s34, v205, v199
	v_bfi_b32 v204, s34, v204, v198
	v_lshlrev_b32_e32 v124, 16, v84
	v_and_b32_e32 v125, 0xffff0000, v84
	v_lshlrev_b32_e32 v164, 16, v85
	v_and_b32_e32 v165, 0xffff0000, v85
	v_lshlrev_b32_e32 v178, 16, v86
	v_and_b32_e32 v179, 0xffff0000, v86
	v_lshlrev_b32_e32 v210, 16, v87
	v_and_b32_e32 v211, 0xffff0000, v87
	v_pk_fma_f32 v[112:113], v[112:113], v[118:119], v[112:113]
	v_pk_fma_f32 v[152:153], v[152:153], v[158:159], v[152:153]
	v_pk_fma_f32 v[166:167], v[166:167], v[172:173], v[166:167]
	v_pk_fma_f32 v[198:199], v[198:199], v[204:205], v[198:199]
	v_pk_mul_f32 v[112:113], v[112:113], v[124:125]
	v_pk_mul_f32 v[152:153], v[152:153], v[164:165]
	v_pk_mul_f32 v[166:167], v[166:167], v[178:179]
	v_pk_mul_f32 v[198:199], v[198:199], v[210:211]
	v_cvt_pk_bf16_f32 v224, v112, v113
	v_cvt_pk_bf16_f32 v225, v152, v153
	v_cvt_pk_bf16_f32 v226, v166, v167
	v_cvt_pk_bf16_f32 v227, v198, v199
	v_cmp_ne_u32_e32 vcc, 31, v212
	s_and_saveexec_b64 s[100:101], vcc
	global_store_dwordx4 v[228:229], v[224:227], off nt
	s_mov_b64 exec, s[100:101]
	s_bitcmp1_b32 s32, 2
	s_mov_b32 s32, 0
	s_cbranch_scc0 .Lup_rows_ret1
	s_branch .Lup_rows_ret2

.LBB0_2312:
	s_cmp_eq_u32 s32, 0
	s_cbranch_scc1 .Lup_exit_cont
	s_or_b32 s32, s32, 4
	s_branch .Lup_rows
